# all GEMM K-loops: LDS-DMA in saddr form (SGPR base + 32-bit VGPR offset), 106 v_lshl_add_u64 removed; hstep bases precomputed by SALU
# speedup vs baseline: 1.0008x; 1.0008x over previous
.LBB0_619:
	v_add_u32_e32 v153, s44, v151
	ds_read_b128 v[154:157], v153
	ds_read_b128 v[158:161], v153 offset:1024
	ds_read_b128 v[162:165], v153 offset:2048
	ds_read_b128 v[166:169], v153 offset:3072
	v_add_u32_e32 v153, s45, v151
	s_add_u32 s26, s18, s24
	ds_read_b128 v[170:173], v153
	ds_read_b128 v[174:177], v153 offset:1024
	ds_read_b128 v[178:181], v153 offset:2048
	ds_read_b128 v[182:185], v153 offset:3072
	s_addc_u32 s27, s19, s25
	s_add_u32 s26, s26, 0x100
	s_addc_u32 s27, s27, 0
	s_add_u32 s51, s48, s24
	s_addc_u32 s52, s49, s25
	s_cmpk_eq_i32 s24, 0x1500
	s_cselect_b32 s29, s23, s27
	s_cselect_b32 s28, s22, s26
	s_cselect_b32 s27, s9, s52
	s_cselect_b32 s26, s8, s51
	v_lshl_add_u64 v[218:219], v[146:147], 0, s[24:25]
	s_add_i32 m0, s33, 0xc000
	ds_read_b128 v[186:189], v152
	ds_read_b128 v[190:193], v152 offset:1024
	ds_read_b128 v[194:197], v152 offset:2048
	ds_read_b128 v[198:201], v152 offset:3072
	ds_read_b128 v[202:205], v152 offset:4096
	ds_read_b128 v[206:209], v152 offset:5120
	ds_read_b128 v[210:213], v152 offset:6144
	ds_read_b128 v[214:217], v152 offset:7168
	global_load_lds_dwordx4 v[218:219], off
	v_lshl_add_u64 v[218:219], v[148:149], 0, s[24:25]
	s_add_i32 m0, s33, 0xe000
	s_nop 0
	global_load_lds_dwordx4 v[218:219], off
	s_waitcnt vmcnt(8)
	s_waitcnt lgkmcnt(0)
	s_barrier
	s_setprio 1
	s_waitcnt lgkmcnt(0)
	v_mfma_f32_16x16x32_bf16 v[126:129], v[154:157], v[186:189], v[126:129]
	v_mfma_f32_16x16x32_bf16 v[122:125], v[162:165], v[186:189], v[122:125]
	v_mfma_f32_16x16x32_bf16 v[110:113], v[154:157], v[194:197], v[110:113]
	v_mfma_f32_16x16x32_bf16 v[106:109], v[162:165], v[194:197], v[106:109]
	v_mfma_f32_16x16x32_bf16 v[94:97], v[154:157], v[202:205], v[94:97]
	v_mfma_f32_16x16x32_bf16 v[90:93], v[162:165], v[202:205], v[90:93]
	v_mfma_f32_16x16x32_bf16 v[78:81], v[154:157], v[210:213], v[78:81]
	v_mfma_f32_16x16x32_bf16 v[74:77], v[162:165], v[210:213], v[74:77]
	v_mfma_f32_16x16x32_bf16 v[126:129], v[158:161], v[190:193], v[126:129]
	v_mfma_f32_16x16x32_bf16 v[122:125], v[166:169], v[190:193], v[122:125]
	v_mfma_f32_16x16x32_bf16 v[110:113], v[158:161], v[198:201], v[110:113]
	v_mfma_f32_16x16x32_bf16 v[106:109], v[166:169], v[198:201], v[106:109]
	v_mfma_f32_16x16x32_bf16 v[94:97], v[158:161], v[206:209], v[94:97]
	v_mfma_f32_16x16x32_bf16 v[90:93], v[166:169], v[206:209], v[90:93]
	v_mfma_f32_16x16x32_bf16 v[78:81], v[158:161], v[214:217], v[78:81]
	v_mfma_f32_16x16x32_bf16 v[74:77], v[166:169], v[214:217], v[74:77]
	s_setprio 0
	s_setprio 1
	v_mfma_f32_16x16x32_bf16 v[118:121], v[170:173], v[186:189], v[118:121]
	v_mfma_f32_16x16x32_bf16 v[114:117], v[178:181], v[186:189], v[114:117]
	v_mfma_f32_16x16x32_bf16 v[102:105], v[170:173], v[194:197], v[102:105]
	v_mfma_f32_16x16x32_bf16 v[98:101], v[178:181], v[194:197], v[98:101]
	v_mfma_f32_16x16x32_bf16 v[86:89], v[170:173], v[202:205], v[86:89]
	v_mfma_f32_16x16x32_bf16 v[82:85], v[178:181], v[202:205], v[82:85]
	v_mfma_f32_16x16x32_bf16 v[70:73], v[170:173], v[210:213], v[70:73]
	v_mfma_f32_16x16x32_bf16 v[66:69], v[178:181], v[210:213], v[66:69]
	v_mfma_f32_16x16x32_bf16 v[118:121], v[174:177], v[190:193], v[118:121]
	v_mfma_f32_16x16x32_bf16 v[114:117], v[182:185], v[190:193], v[114:117]
	v_mfma_f32_16x16x32_bf16 v[102:105], v[174:177], v[198:201], v[102:105]
	v_mfma_f32_16x16x32_bf16 v[98:101], v[182:185], v[198:201], v[98:101]
	v_mfma_f32_16x16x32_bf16 v[86:89], v[174:177], v[206:209], v[86:89]
	v_mfma_f32_16x16x32_bf16 v[82:85], v[182:185], v[206:209], v[82:85]
	v_mfma_f32_16x16x32_bf16 v[70:73], v[174:177], v[214:217], v[70:73]
	v_mfma_f32_16x16x32_bf16 v[66:69], v[182:185], v[214:217], v[66:69]
	s_setprio 0
	s_barrier
	s_add_i32 s51, s44, s13
	s_add_u32 s98, s26, s20
	s_addc_u32 s99, s27, s21
	s_mov_b32 m0, s51
	ds_read_b128 v[186:189], v152 offset:16384
	ds_read_b128 v[190:193], v152 offset:17408
	ds_read_b128 v[194:197], v152 offset:18432
	ds_read_b128 v[198:201], v152 offset:19456
	ds_read_b128 v[202:205], v152 offset:20480
	ds_read_b128 v[206:209], v152 offset:21504
	ds_read_b128 v[210:213], v152 offset:22528
	ds_read_b128 v[214:217], v152 offset:23552
	global_load_lds_dwordx4 v132, s[26:27]
	s_add_i32 m0, s51, 0x2000
	s_add_u32 s52, s26, 0xb0000
	s_addc_u32 s53, s27, 0
	s_add_i32 s51, s45, s13
	global_load_lds_dwordx4 v136, s[26:27]
	s_mov_b32 m0, s51
	s_nop 0
	global_load_lds_dwordx4 v132, s[52:53]
	s_add_i32 m0, s51, 0x2000
	s_nop 0
	global_load_lds_dwordx4 v136, s[52:53]
	s_add_u32 s100, s28, s20
	s_addc_u32 s101, s29, s21
	s_mov_b32 m0, s33
	s_nop 0
	global_load_lds_dwordx4 v130, s[28:29]
	s_mov_b32 m0, s14
	s_nop 0
	global_load_lds_dwordx4 v134, s[28:29]
	s_waitcnt vmcnt(8)
	s_waitcnt lgkmcnt(0)
	s_barrier
	s_setprio 1
	s_waitcnt lgkmcnt(0)
	v_mfma_f32_16x16x32_bf16 v[62:65], v[154:157], v[186:189], v[62:65]
	v_mfma_f32_16x16x32_bf16 v[58:61], v[162:165], v[186:189], v[58:61]
	v_mfma_f32_16x16x32_bf16 v[46:49], v[154:157], v[194:197], v[46:49]
	v_mfma_f32_16x16x32_bf16 v[42:45], v[162:165], v[194:197], v[42:45]
	v_mfma_f32_16x16x32_bf16 v[30:33], v[154:157], v[202:205], v[30:33]
	v_mfma_f32_16x16x32_bf16 v[26:29], v[162:165], v[202:205], v[26:29]
	v_mfma_f32_16x16x32_bf16 v[14:17], v[154:157], v[210:213], v[14:17]
	v_mfma_f32_16x16x32_bf16 v[10:13], v[162:165], v[210:213], v[10:13]
	v_mfma_f32_16x16x32_bf16 v[62:65], v[158:161], v[190:193], v[62:65]
	v_mfma_f32_16x16x32_bf16 v[58:61], v[166:169], v[190:193], v[58:61]
	v_mfma_f32_16x16x32_bf16 v[46:49], v[158:161], v[198:201], v[46:49]
	v_mfma_f32_16x16x32_bf16 v[42:45], v[166:169], v[198:201], v[42:45]
	v_mfma_f32_16x16x32_bf16 v[30:33], v[158:161], v[206:209], v[30:33]
	v_mfma_f32_16x16x32_bf16 v[26:29], v[166:169], v[206:209], v[26:29]
	v_mfma_f32_16x16x32_bf16 v[14:17], v[158:161], v[214:217], v[14:17]
	v_mfma_f32_16x16x32_bf16 v[10:13], v[166:169], v[214:217], v[10:13]
	s_setprio 0
	s_setprio 1
	v_mfma_f32_16x16x32_bf16 v[54:57], v[170:173], v[186:189], v[54:57]
	v_mfma_f32_16x16x32_bf16 v[50:53], v[178:181], v[186:189], v[50:53]
	v_mfma_f32_16x16x32_bf16 v[38:41], v[170:173], v[194:197], v[38:41]
	v_mfma_f32_16x16x32_bf16 v[34:37], v[178:181], v[194:197], v[34:37]
	v_mfma_f32_16x16x32_bf16 v[22:25], v[170:173], v[202:205], v[22:25]
	v_mfma_f32_16x16x32_bf16 v[18:21], v[178:181], v[202:205], v[18:21]
	v_mfma_f32_16x16x32_bf16 v[6:9], v[170:173], v[210:213], v[6:9]
	v_mfma_f32_16x16x32_bf16 v[2:5], v[178:181], v[210:213], v[2:5]
	v_mfma_f32_16x16x32_bf16 v[54:57], v[174:177], v[190:193], v[54:57]
	v_mfma_f32_16x16x32_bf16 v[50:53], v[182:185], v[190:193], v[50:53]
	v_mfma_f32_16x16x32_bf16 v[38:41], v[174:177], v[198:201], v[38:41]
	v_mfma_f32_16x16x32_bf16 v[34:37], v[182:185], v[198:201], v[34:37]
	v_mfma_f32_16x16x32_bf16 v[22:25], v[174:177], v[206:209], v[22:25]
	v_mfma_f32_16x16x32_bf16 v[18:21], v[182:185], v[206:209], v[18:21]
	v_mfma_f32_16x16x32_bf16 v[6:9], v[174:177], v[214:217], v[6:9]
	v_mfma_f32_16x16x32_bf16 v[2:5], v[182:185], v[214:217], v[2:5]
	s_setprio 0
	s_barrier
	s_add_i32 s51, 0, 0x18000
	v_add_u32_e32 v153, s51, v151
	s_add_i32 s52, 0, 0x1c000
	ds_read_b128 v[154:157], v153
	ds_read_b128 v[158:161], v153 offset:1024
	ds_read_b128 v[162:165], v153 offset:2048
	ds_read_b128 v[166:169], v153 offset:3072
	v_add_u32_e32 v153, s52, v151
	ds_read_b128 v[170:173], v153
	ds_read_b128 v[174:177], v153 offset:1024
	ds_read_b128 v[178:181], v153 offset:2048
	ds_read_b128 v[182:185], v153 offset:3072
	s_add_u32 s28, s28, 0xb0000
	s_addc_u32 s29, s29, 0
	s_mov_b32 m0, s15
	ds_read_b128 v[186:189], v152 offset:32768
	ds_read_b128 v[190:193], v152 offset:33792
	ds_read_b128 v[194:197], v152 offset:34816
	ds_read_b128 v[198:201], v152 offset:35840
	ds_read_b128 v[202:205], v152 offset:36864
	ds_read_b128 v[206:209], v152 offset:37888
	ds_read_b128 v[210:213], v152 offset:38912
	ds_read_b128 v[214:217], v152 offset:39936
	global_load_lds_dwordx4 v130, s[28:29]
	s_mov_b32 m0, s40
	s_nop 0
	global_load_lds_dwordx4 v134, s[28:29]
	s_waitcnt vmcnt(8)
	s_waitcnt lgkmcnt(0)
	s_barrier
	s_setprio 1
	s_waitcnt lgkmcnt(0)
	v_mfma_f32_16x16x32_bf16 v[126:129], v[154:157], v[186:189], v[126:129]
	v_mfma_f32_16x16x32_bf16 v[122:125], v[162:165], v[186:189], v[122:125]
	v_mfma_f32_16x16x32_bf16 v[110:113], v[154:157], v[194:197], v[110:113]
	v_mfma_f32_16x16x32_bf16 v[106:109], v[162:165], v[194:197], v[106:109]
	v_mfma_f32_16x16x32_bf16 v[94:97], v[154:157], v[202:205], v[94:97]
	v_mfma_f32_16x16x32_bf16 v[90:93], v[162:165], v[202:205], v[90:93]
	v_mfma_f32_16x16x32_bf16 v[78:81], v[154:157], v[210:213], v[78:81]
	v_mfma_f32_16x16x32_bf16 v[74:77], v[162:165], v[210:213], v[74:77]
	v_mfma_f32_16x16x32_bf16 v[126:129], v[158:161], v[190:193], v[126:129]
	v_mfma_f32_16x16x32_bf16 v[122:125], v[166:169], v[190:193], v[122:125]
	v_mfma_f32_16x16x32_bf16 v[110:113], v[158:161], v[198:201], v[110:113]
	v_mfma_f32_16x16x32_bf16 v[106:109], v[166:169], v[198:201], v[106:109]
	v_mfma_f32_16x16x32_bf16 v[94:97], v[158:161], v[206:209], v[94:97]
	v_mfma_f32_16x16x32_bf16 v[90:93], v[166:169], v[206:209], v[90:93]
	v_mfma_f32_16x16x32_bf16 v[78:81], v[158:161], v[214:217], v[78:81]
	v_mfma_f32_16x16x32_bf16 v[74:77], v[166:169], v[214:217], v[74:77]
	s_setprio 0
	s_setprio 1
	v_mfma_f32_16x16x32_bf16 v[118:121], v[170:173], v[186:189], v[118:121]
	v_mfma_f32_16x16x32_bf16 v[114:117], v[178:181], v[186:189], v[114:117]
	v_mfma_f32_16x16x32_bf16 v[102:105], v[170:173], v[194:197], v[102:105]
	v_mfma_f32_16x16x32_bf16 v[98:101], v[178:181], v[194:197], v[98:101]
	v_mfma_f32_16x16x32_bf16 v[86:89], v[170:173], v[202:205], v[86:89]
	v_mfma_f32_16x16x32_bf16 v[82:85], v[178:181], v[202:205], v[82:85]
	v_mfma_f32_16x16x32_bf16 v[70:73], v[170:173], v[210:213], v[70:73]
	v_mfma_f32_16x16x32_bf16 v[66:69], v[178:181], v[210:213], v[66:69]
	v_mfma_f32_16x16x32_bf16 v[118:121], v[174:177], v[190:193], v[118:121]
	v_mfma_f32_16x16x32_bf16 v[114:117], v[182:185], v[190:193], v[114:117]
	v_mfma_f32_16x16x32_bf16 v[102:105], v[174:177], v[198:201], v[102:105]
	v_mfma_f32_16x16x32_bf16 v[98:101], v[182:185], v[198:201], v[98:101]
	v_mfma_f32_16x16x32_bf16 v[86:89], v[174:177], v[206:209], v[86:89]
	v_mfma_f32_16x16x32_bf16 v[82:85], v[182:185], v[206:209], v[82:85]
	v_mfma_f32_16x16x32_bf16 v[70:73], v[174:177], v[214:217], v[70:73]
	v_mfma_f32_16x16x32_bf16 v[66:69], v[182:185], v[214:217], v[66:69]
	s_setprio 0
	s_barrier
	s_add_i32 s28, s51, s13
	s_mov_b32 m0, s28
	ds_read_b128 v[186:189], v152 offset:49152
	ds_read_b128 v[190:193], v152 offset:50176
	ds_read_b128 v[194:197], v152 offset:51200
	ds_read_b128 v[198:201], v152 offset:52224
	ds_read_b128 v[202:205], v152 offset:53248
	ds_read_b128 v[206:209], v152 offset:54272
	ds_read_b128 v[210:213], v152 offset:55296
	ds_read_b128 v[214:217], v152 offset:56320
	global_load_lds_dwordx4 v132, s[98:99]
	s_add_i32 m0, s28, 0x2000
	s_add_u32 s26, s26, 0xb0080
	s_addc_u32 s27, s27, 0
	s_add_i32 s28, s52, s13
	global_load_lds_dwordx4 v136, s[98:99]
	s_mov_b32 m0, s28
	s_nop 0
	global_load_lds_dwordx4 v132, s[26:27]
	s_add_i32 m0, s28, 0x2000
	s_nop 0
	global_load_lds_dwordx4 v136, s[26:27]
	s_mov_b32 m0, s42
	s_nop 0
	global_load_lds_dwordx4 v130, s[100:101]
	s_mov_b32 m0, s43
	s_nop 0
	global_load_lds_dwordx4 v134, s[100:101]
	s_waitcnt vmcnt(8)
	s_waitcnt lgkmcnt(0)
	s_barrier
	s_setprio 1
	s_waitcnt lgkmcnt(0)
	v_mfma_f32_16x16x32_bf16 v[62:65], v[154:157], v[186:189], v[62:65]
	v_mfma_f32_16x16x32_bf16 v[58:61], v[162:165], v[186:189], v[58:61]
	v_mfma_f32_16x16x32_bf16 v[46:49], v[154:157], v[194:197], v[46:49]
	v_mfma_f32_16x16x32_bf16 v[42:45], v[162:165], v[194:197], v[42:45]
	v_mfma_f32_16x16x32_bf16 v[30:33], v[154:157], v[202:205], v[30:33]
	v_mfma_f32_16x16x32_bf16 v[26:29], v[162:165], v[202:205], v[26:29]
	v_mfma_f32_16x16x32_bf16 v[14:17], v[154:157], v[210:213], v[14:17]
	v_mfma_f32_16x16x32_bf16 v[10:13], v[162:165], v[210:213], v[10:13]
	v_mfma_f32_16x16x32_bf16 v[62:65], v[158:161], v[190:193], v[62:65]
	v_mfma_f32_16x16x32_bf16 v[58:61], v[166:169], v[190:193], v[58:61]
	v_mfma_f32_16x16x32_bf16 v[46:49], v[158:161], v[198:201], v[46:49]
	v_mfma_f32_16x16x32_bf16 v[42:45], v[166:169], v[198:201], v[42:45]
	v_mfma_f32_16x16x32_bf16 v[30:33], v[158:161], v[206:209], v[30:33]
	v_mfma_f32_16x16x32_bf16 v[26:29], v[166:169], v[206:209], v[26:29]
	v_mfma_f32_16x16x32_bf16 v[14:17], v[158:161], v[214:217], v[14:17]
	v_mfma_f32_16x16x32_bf16 v[10:13], v[166:169], v[214:217], v[10:13]
	s_setprio 0
	s_setprio 1
	v_mfma_f32_16x16x32_bf16 v[54:57], v[170:173], v[186:189], v[54:57]
	v_mfma_f32_16x16x32_bf16 v[50:53], v[178:181], v[186:189], v[50:53]
	v_mfma_f32_16x16x32_bf16 v[38:41], v[170:173], v[194:197], v[38:41]
	v_mfma_f32_16x16x32_bf16 v[34:37], v[178:181], v[194:197], v[34:37]
	v_mfma_f32_16x16x32_bf16 v[22:25], v[170:173], v[202:205], v[22:25]
	v_mfma_f32_16x16x32_bf16 v[18:21], v[178:181], v[202:205], v[18:21]
	v_mfma_f32_16x16x32_bf16 v[6:9], v[170:173], v[210:213], v[6:9]
	v_mfma_f32_16x16x32_bf16 v[2:5], v[178:181], v[210:213], v[2:5]
	v_mfma_f32_16x16x32_bf16 v[54:57], v[174:177], v[190:193], v[54:57]
	v_mfma_f32_16x16x32_bf16 v[50:53], v[182:185], v[190:193], v[50:53]
	v_mfma_f32_16x16x32_bf16 v[38:41], v[174:177], v[198:201], v[38:41]
	v_mfma_f32_16x16x32_bf16 v[34:37], v[182:185], v[198:201], v[34:37]
	v_mfma_f32_16x16x32_bf16 v[22:25], v[174:177], v[206:209], v[22:25]
	v_mfma_f32_16x16x32_bf16 v[18:21], v[182:185], v[206:209], v[18:21]
	v_mfma_f32_16x16x32_bf16 v[6:9], v[174:177], v[214:217], v[6:9]
	v_mfma_f32_16x16x32_bf16 v[2:5], v[182:185], v[214:217], v[2:5]
	s_setprio 0
	s_barrier
	s_add_i32 s50, s50, 2
	s_add_u32 s24, s24, 0x100
	s_addc_u32 s25, s25, 0
	s_cmp_gt_u32 s50, 41
	s_cbranch_scc0 .LBB0_619
	s_add_u32 s24, s48, 0xffffff00
	s_addc_u32 s25, s49, -1
	s_and_b64 vcc, exec, s[6:7]
	s_cbranch_vccnz .LBB0_622
	v_mov_b32_e32 v2, 0
	s_mov_b32 s10, s46
	s_mov_b32 s31, s47
	s_mov_b64 s[18:19], s[22:23]
	s_mov_b32 s41, s2
	v_mov_b32_e32 v3, v2
	v_mov_b32_e32 v4, v2
	v_mov_b32_e32 v5, v2
	v_mov_b32_e32 v6, v2
	v_mov_b32_e32 v7, v2
	v_mov_b32_e32 v8, v2
	v_mov_b32_e32 v9, v2
	v_mov_b32_e32 v18, v2
	v_mov_b32_e32 v19, v2
	v_mov_b32_e32 v20, v2
	v_mov_b32_e32 v21, v2
	v_mov_b32_e32 v22, v2
	v_mov_b32_e32 v23, v2
	v_mov_b32_e32 v24, v2
	v_mov_b32_e32 v25, v2
	v_mov_b32_e32 v34, v2
	v_mov_b32_e32 v35, v2
	v_mov_b32_e32 v36, v2
	v_mov_b32_e32 v37, v2
	v_mov_b32_e32 v38, v2
	v_mov_b32_e32 v39, v2
	v_mov_b32_e32 v40, v2
	v_mov_b32_e32 v41, v2
	v_mov_b32_e32 v50, v2
	v_mov_b32_e32 v51, v2
	v_mov_b32_e32 v52, v2
	v_mov_b32_e32 v53, v2
	v_mov_b32_e32 v54, v2
	v_mov_b32_e32 v55, v2
	v_mov_b32_e32 v56, v2
	v_mov_b32_e32 v57, v2
	v_mov_b32_e32 v10, v2
	v_mov_b32_e32 v11, v2
	v_mov_b32_e32 v12, v2
	v_mov_b32_e32 v13, v2
	v_mov_b32_e32 v14, v2
	v_mov_b32_e32 v15, v2
	v_mov_b32_e32 v16, v2
	v_mov_b32_e32 v17, v2
	v_mov_b32_e32 v26, v2
	v_mov_b32_e32 v27, v2
	v_mov_b32_e32 v28, v2
	v_mov_b32_e32 v29, v2
	v_mov_b32_e32 v30, v2
	v_mov_b32_e32 v31, v2
	v_mov_b32_e32 v32, v2
	v_mov_b32_e32 v33, v2
	v_mov_b32_e32 v42, v2
	v_mov_b32_e32 v43, v2
	v_mov_b32_e32 v44, v2
	v_mov_b32_e32 v45, v2
	v_mov_b32_e32 v46, v2
	v_mov_b32_e32 v47, v2
	v_mov_b32_e32 v48, v2
	v_mov_b32_e32 v49, v2
	v_mov_b32_e32 v58, v2
	v_mov_b32_e32 v59, v2
	v_mov_b32_e32 v60, v2
	v_mov_b32_e32 v61, v2
	v_mov_b32_e32 v62, v2
	v_mov_b32_e32 v63, v2
	v_mov_b32_e32 v64, v2
	v_mov_b32_e32 v65, v2
	v_mov_b32_e32 v66, v2
	v_mov_b32_e32 v67, v2
	v_mov_b32_e32 v68, v2
	v_mov_b32_e32 v69, v2
	v_mov_b32_e32 v70, v2
	v_mov_b32_e32 v71, v2
	v_mov_b32_e32 v72, v2
	v_mov_b32_e32 v73, v2
	v_mov_b32_e32 v82, v2
	v_mov_b32_e32 v83, v2
	v_mov_b32_e32 v84, v2
	v_mov_b32_e32 v85, v2
	v_mov_b32_e32 v86, v2
	v_mov_b32_e32 v87, v2
	v_mov_b32_e32 v88, v2
	v_mov_b32_e32 v89, v2
	v_mov_b32_e32 v98, v2
	v_mov_b32_e32 v99, v2
	v_mov_b32_e32 v100, v2
	v_mov_b32_e32 v101, v2
	v_mov_b32_e32 v102, v2
	v_mov_b32_e32 v103, v2
	v_mov_b32_e32 v104, v2
	v_mov_b32_e32 v105, v2
	v_mov_b32_e32 v114, v2
	v_mov_b32_e32 v115, v2
	v_mov_b32_e32 v116, v2
	v_mov_b32_e32 v117, v2
	v_mov_b32_e32 v118, v2
	v_mov_b32_e32 v119, v2
	v_mov_b32_e32 v120, v2
	v_mov_b32_e32 v121, v2
	v_mov_b32_e32 v74, v2
	v_mov_b32_e32 v75, v2
	v_mov_b32_e32 v76, v2
	v_mov_b32_e32 v77, v2
	v_mov_b32_e32 v78, v2
	v_mov_b32_e32 v79, v2
	v_mov_b32_e32 v80, v2
	v_mov_b32_e32 v81, v2
	v_mov_b32_e32 v90, v2
	v_mov_b32_e32 v91, v2
	v_mov_b32_e32 v92, v2
	v_mov_b32_e32 v93, v2
	v_mov_b32_e32 v94, v2
	v_mov_b32_e32 v95, v2
	v_mov_b32_e32 v96, v2
	v_mov_b32_e32 v97, v2
	v_mov_b32_e32 v106, v2
	v_mov_b32_e32 v107, v2
	v_mov_b32_e32 v108, v2
	v_mov_b32_e32 v109, v2
	v_mov_b32_e32 v110, v2
	v_mov_b32_e32 v111, v2
	v_mov_b32_e32 v112, v2
	v_mov_b32_e32 v113, v2
	v_mov_b32_e32 v122, v2
	v_mov_b32_e32 v123, v2
	v_mov_b32_e32 v124, v2
	v_mov_b32_e32 v125, v2
	v_mov_b32_e32 v126, v2
	v_mov_b32_e32 v127, v2
	v_mov_b32_e32 v128, v2
	v_mov_b32_e32 v129, v2
	s_andn2_b64 vcc, exec, s[4:5]
	s_cbranch_vccnz .LBB0_623
	s_branch .LBB0_624

.LBB0_774:
	ds_read_b128 v[38:41], v231
	ds_read_b128 v[42:45], v231 offset:1024
	ds_read_b128 v[54:57], v231 offset:2048
	ds_read_b128 v[58:61], v231 offset:3072
	ds_read_b128 v[126:129], v232
	ds_read_b128 v[146:149], v232 offset:1024
	ds_read_b128 v[166:169], v232 offset:2048
	ds_read_b128 v[170:173], v232 offset:3072
	s_add_u32 s14, s10, 0xfffc0080
	s_addc_u32 s15, s11, -1
	s_cmp_eq_u32 s13, 12
	s_cselect_b32 s59, s0, s15
	s_cselect_b32 s58, s1, s14
	s_cselect_b32 s57, s2, s12
	s_cselect_b32 s56, s7, s9
	s_add_i32 m0, s67, 0xc000
	ds_read_b128 v[174:177], v233
	ds_read_b128 v[194:197], v233 offset:1024
	ds_read_b128 v[198:201], v233 offset:2048
	ds_read_b128 v[202:205], v233 offset:3072
	ds_read_b128 v[206:209], v233 offset:4096
	ds_read_b128 v[210:213], v233 offset:5120
	ds_read_b128 v[214:217], v233 offset:6144
	ds_read_b128 v[218:221], v233 offset:7168
	global_load_lds_dwordx4 v186, s[10:11]
	s_add_i32 m0, s67, 0xe000
	s_nop 0
	global_load_lds_dwordx4 v188, s[10:11]
	s_waitcnt vmcnt(8)
	s_waitcnt lgkmcnt(0)
	s_barrier
	s_setprio 1
	s_waitcnt lgkmcnt(0)
	v_mfma_f32_16x16x32_bf16 v[162:165], v[38:41], v[174:177], v[162:165]
	v_mfma_f32_16x16x32_bf16 v[158:161], v[54:57], v[174:177], v[158:161]
	v_mfma_f32_16x16x32_bf16 v[142:145], v[38:41], v[198:201], v[142:145]
	v_mfma_f32_16x16x32_bf16 v[138:141], v[54:57], v[198:201], v[138:141]
	v_mfma_f32_16x16x32_bf16 v[122:125], v[38:41], v[206:209], v[122:125]
	v_mfma_f32_16x16x32_bf16 v[118:121], v[54:57], v[206:209], v[118:121]
	v_mfma_f32_16x16x32_bf16 v[106:109], v[38:41], v[214:217], v[106:109]
	v_mfma_f32_16x16x32_bf16 v[102:105], v[54:57], v[214:217], v[102:105]
	v_mfma_f32_16x16x32_bf16 v[162:165], v[42:45], v[194:197], v[162:165]
	v_mfma_f32_16x16x32_bf16 v[158:161], v[58:61], v[194:197], v[158:161]
	v_mfma_f32_16x16x32_bf16 v[142:145], v[42:45], v[202:205], v[142:145]
	v_mfma_f32_16x16x32_bf16 v[138:141], v[58:61], v[202:205], v[138:141]
	v_mfma_f32_16x16x32_bf16 v[122:125], v[42:45], v[210:213], v[122:125]
	v_mfma_f32_16x16x32_bf16 v[118:121], v[58:61], v[210:213], v[118:121]
	v_mfma_f32_16x16x32_bf16 v[106:109], v[42:45], v[218:221], v[106:109]
	v_mfma_f32_16x16x32_bf16 v[102:105], v[58:61], v[218:221], v[102:105]
	s_setprio 0
	s_setprio 1
	v_mfma_f32_16x16x32_bf16 v[154:157], v[126:129], v[174:177], v[154:157]
	v_mfma_f32_16x16x32_bf16 v[150:153], v[166:169], v[174:177], v[150:153]
	v_mfma_f32_16x16x32_bf16 v[134:137], v[126:129], v[198:201], v[134:137]
	v_mfma_f32_16x16x32_bf16 v[130:133], v[166:169], v[198:201], v[130:133]
	v_mfma_f32_16x16x32_bf16 v[114:117], v[126:129], v[206:209], v[114:117]
	v_mfma_f32_16x16x32_bf16 v[110:113], v[166:169], v[206:209], v[110:113]
	v_mfma_f32_16x16x32_bf16 v[98:101], v[126:129], v[214:217], v[98:101]
	v_mfma_f32_16x16x32_bf16 v[94:97], v[166:169], v[214:217], v[94:97]
	v_mfma_f32_16x16x32_bf16 v[154:157], v[146:149], v[194:197], v[154:157]
	v_mfma_f32_16x16x32_bf16 v[150:153], v[170:173], v[194:197], v[150:153]
	v_mfma_f32_16x16x32_bf16 v[134:137], v[146:149], v[202:205], v[134:137]
	v_mfma_f32_16x16x32_bf16 v[130:133], v[170:173], v[202:205], v[130:133]
	v_mfma_f32_16x16x32_bf16 v[114:117], v[146:149], v[210:213], v[114:117]
	v_mfma_f32_16x16x32_bf16 v[110:113], v[170:173], v[210:213], v[110:113]
	v_mfma_f32_16x16x32_bf16 v[98:101], v[146:149], v[218:221], v[98:101]
	v_mfma_f32_16x16x32_bf16 v[94:97], v[170:173], v[218:221], v[94:97]
	s_setprio 0
	s_barrier
	s_add_i32 s14, s84, s66
	s_add_u32 s98, s56, s20
	s_addc_u32 s99, s57, s21
	s_mov_b32 m0, s14
	ds_read_b128 v[174:177], v233 offset:16384
	ds_read_b128 v[194:197], v233 offset:17408
	ds_read_b128 v[198:201], v233 offset:18432
	ds_read_b128 v[202:205], v233 offset:19456
	ds_read_b128 v[206:209], v233 offset:20480
	ds_read_b128 v[210:213], v233 offset:21504
	ds_read_b128 v[214:217], v233 offset:22528
	ds_read_b128 v[218:221], v233 offset:23552
	global_load_lds_dwordx4 v180, s[56:57]
	s_add_i32 m0, s14, 0x2000
	s_add_u32 s14, s56, 0x40000
	s_addc_u32 s15, s57, 0
	s_add_i32 s33, s85, s66
	global_load_lds_dwordx4 v184, s[56:57]
	s_mov_b32 m0, s33
	s_add_u32 s100, s58, s20
	s_addc_u32 s101, s59, s21
	global_load_lds_dwordx4 v180, s[14:15]
	s_add_i32 m0, s33, 0x2000
	s_nop 0
	global_load_lds_dwordx4 v184, s[14:15]
	s_mov_b32 m0, s67
	s_nop 0
	global_load_lds_dwordx4 v178, s[58:59]
	s_mov_b32 m0, s68
	s_nop 0
	global_load_lds_dwordx4 v182, s[58:59]
	s_waitcnt vmcnt(8)
	s_waitcnt lgkmcnt(0)
	s_barrier
	s_setprio 1
	s_waitcnt lgkmcnt(0)
	v_mfma_f32_16x16x32_bf16 v[90:93], v[38:41], v[174:177], v[90:93]
	v_mfma_f32_16x16x32_bf16 v[86:89], v[54:57], v[174:177], v[86:89]
	v_mfma_f32_16x16x32_bf16 v[74:77], v[38:41], v[198:201], v[74:77]
	v_mfma_f32_16x16x32_bf16 v[70:73], v[54:57], v[198:201], v[70:73]
	v_mfma_f32_16x16x32_bf16 v[50:53], v[38:41], v[206:209], v[50:53]
	v_mfma_f32_16x16x32_bf16 v[46:49], v[54:57], v[206:209], v[46:49]
	v_mfma_f32_16x16x32_bf16 v[26:29], v[38:41], v[214:217], v[26:29]
	v_mfma_f32_16x16x32_bf16 v[22:25], v[54:57], v[214:217], v[22:25]
	v_mfma_f32_16x16x32_bf16 v[90:93], v[42:45], v[194:197], v[90:93]
	v_mfma_f32_16x16x32_bf16 v[86:89], v[58:61], v[194:197], v[86:89]
	v_mfma_f32_16x16x32_bf16 v[74:77], v[42:45], v[202:205], v[74:77]
	v_mfma_f32_16x16x32_bf16 v[70:73], v[58:61], v[202:205], v[70:73]
	v_mfma_f32_16x16x32_bf16 v[50:53], v[42:45], v[210:213], v[50:53]
	v_mfma_f32_16x16x32_bf16 v[46:49], v[58:61], v[210:213], v[46:49]
	v_mfma_f32_16x16x32_bf16 v[26:29], v[42:45], v[218:221], v[26:29]
	v_mfma_f32_16x16x32_bf16 v[22:25], v[58:61], v[218:221], v[22:25]
	s_setprio 0
	s_setprio 1
	v_mfma_f32_16x16x32_bf16 v[34:37], v[126:129], v[206:209], v[34:37]
	v_mfma_f32_16x16x32_bf16 v[30:33], v[166:169], v[206:209], v[30:33]
	v_mfma_f32_16x16x32_bf16 v[18:21], v[126:129], v[214:217], v[18:21]
	v_mfma_f32_16x16x32_bf16 v[12:15], v[166:169], v[214:217], v[14:17]
	v_mfma_f32_16x16x32_bf16 v[38:41], v[126:129], v[174:177], v[82:85]
	v_mfma_f32_16x16x32_bf16 v[42:45], v[166:169], v[174:177], v[78:81]
	v_mfma_f32_16x16x32_bf16 v[54:57], v[126:129], v[198:201], v[66:69]
	v_mfma_f32_16x16x32_bf16 v[58:61], v[166:169], v[198:201], v[62:65]
	v_mfma_f32_16x16x32_bf16 v[34:37], v[146:149], v[210:213], v[34:37]
	v_mfma_f32_16x16x32_bf16 v[30:33], v[170:173], v[210:213], v[30:33]
	v_mfma_f32_16x16x32_bf16 v[18:21], v[146:149], v[218:221], v[18:21]
	v_mfma_f32_16x16x32_bf16 v[12:15], v[170:173], v[218:221], v[12:15]
	v_mfma_f32_16x16x32_bf16 v[38:41], v[146:149], v[194:197], v[38:41]
	v_mfma_f32_16x16x32_bf16 v[42:45], v[170:173], v[194:197], v[42:45]
	v_mfma_f32_16x16x32_bf16 v[54:57], v[146:149], v[202:205], v[54:57]
	v_mfma_f32_16x16x32_bf16 v[58:61], v[170:173], v[202:205], v[58:61]
	s_setprio 0
	s_barrier
	s_add_i32 s33, 0, 0x18000
	v_add_u32_e32 v3, s33, v230
	s_add_i32 s40, 0, 0x1c000
	ds_read_b128 v[62:65], v3
	ds_read_b128 v[66:69], v3 offset:1024
	ds_read_b128 v[78:81], v3 offset:2048
	ds_read_b128 v[82:85], v3 offset:3072
	v_add_u32_e32 v3, s40, v230
	ds_read_b128 v[126:129], v3
	ds_read_b128 v[146:149], v3 offset:1024
	ds_read_b128 v[166:169], v3 offset:2048
	ds_read_b128 v[170:173], v3 offset:3072
	s_add_u32 s14, s58, 0x40000
	s_addc_u32 s15, s59, 0
	s_mov_b32 m0, s69
	ds_read_b128 v[174:177], v233 offset:32768
	ds_read_b128 v[194:197], v233 offset:33792
	ds_read_b128 v[198:201], v233 offset:34816
	ds_read_b128 v[202:205], v233 offset:35840
	ds_read_b128 v[206:209], v233 offset:36864
	ds_read_b128 v[210:213], v233 offset:37888
	ds_read_b128 v[214:217], v233 offset:38912
	ds_read_b128 v[218:221], v233 offset:39936
	global_load_lds_dwordx4 v178, s[14:15]
	s_mov_b32 m0, s70
	s_nop 0
	global_load_lds_dwordx4 v182, s[14:15]
	s_waitcnt vmcnt(8)
	s_waitcnt lgkmcnt(0)
	s_barrier
	s_setprio 1
	s_waitcnt lgkmcnt(0)
	v_mfma_f32_16x16x32_bf16 v[162:165], v[62:65], v[174:177], v[162:165]
	v_mfma_f32_16x16x32_bf16 v[158:161], v[78:81], v[174:177], v[158:161]
	v_mfma_f32_16x16x32_bf16 v[142:145], v[62:65], v[198:201], v[142:145]
	v_mfma_f32_16x16x32_bf16 v[138:141], v[78:81], v[198:201], v[138:141]
	v_mfma_f32_16x16x32_bf16 v[122:125], v[62:65], v[206:209], v[122:125]
	v_mfma_f32_16x16x32_bf16 v[118:121], v[78:81], v[206:209], v[118:121]
	v_mfma_f32_16x16x32_bf16 v[106:109], v[62:65], v[214:217], v[106:109]
	v_mfma_f32_16x16x32_bf16 v[102:105], v[78:81], v[214:217], v[102:105]
	v_mfma_f32_16x16x32_bf16 v[162:165], v[66:69], v[194:197], v[162:165]
	v_mfma_f32_16x16x32_bf16 v[158:161], v[82:85], v[194:197], v[158:161]
	v_mfma_f32_16x16x32_bf16 v[142:145], v[66:69], v[202:205], v[142:145]
	v_mfma_f32_16x16x32_bf16 v[138:141], v[82:85], v[202:205], v[138:141]
	v_mfma_f32_16x16x32_bf16 v[122:125], v[66:69], v[210:213], v[122:125]
	v_mfma_f32_16x16x32_bf16 v[118:121], v[82:85], v[210:213], v[118:121]
	v_mfma_f32_16x16x32_bf16 v[106:109], v[66:69], v[218:221], v[106:109]
	v_mfma_f32_16x16x32_bf16 v[102:105], v[82:85], v[218:221], v[102:105]
	s_setprio 0
	s_setprio 1
	v_mfma_f32_16x16x32_bf16 v[154:157], v[126:129], v[174:177], v[154:157]
	v_mfma_f32_16x16x32_bf16 v[150:153], v[166:169], v[174:177], v[150:153]
	v_mfma_f32_16x16x32_bf16 v[134:137], v[126:129], v[198:201], v[134:137]
	v_mfma_f32_16x16x32_bf16 v[130:133], v[166:169], v[198:201], v[130:133]
	v_mfma_f32_16x16x32_bf16 v[114:117], v[126:129], v[206:209], v[114:117]
	v_mfma_f32_16x16x32_bf16 v[110:113], v[166:169], v[206:209], v[110:113]
	v_mfma_f32_16x16x32_bf16 v[98:101], v[126:129], v[214:217], v[98:101]
	v_mfma_f32_16x16x32_bf16 v[94:97], v[166:169], v[214:217], v[94:97]
	v_mfma_f32_16x16x32_bf16 v[154:157], v[146:149], v[194:197], v[154:157]
	v_mfma_f32_16x16x32_bf16 v[150:153], v[170:173], v[194:197], v[150:153]
	v_mfma_f32_16x16x32_bf16 v[134:137], v[146:149], v[202:205], v[134:137]
	v_mfma_f32_16x16x32_bf16 v[130:133], v[170:173], v[202:205], v[130:133]
	v_mfma_f32_16x16x32_bf16 v[114:117], v[146:149], v[210:213], v[114:117]
	v_mfma_f32_16x16x32_bf16 v[110:113], v[170:173], v[210:213], v[110:113]
	v_mfma_f32_16x16x32_bf16 v[98:101], v[146:149], v[218:221], v[98:101]
	v_mfma_f32_16x16x32_bf16 v[94:97], v[170:173], v[218:221], v[94:97]
	s_setprio 0
	s_barrier
	s_add_i32 s14, s33, s66
	s_mov_b32 m0, s14
	ds_read_b128 v[174:177], v233 offset:49152
	ds_read_b128 v[194:197], v233 offset:50176
	ds_read_b128 v[198:201], v233 offset:51200
	ds_read_b128 v[202:205], v233 offset:52224
	ds_read_b128 v[206:209], v233 offset:53248
	ds_read_b128 v[210:213], v233 offset:54272
	ds_read_b128 v[214:217], v233 offset:55296
	ds_read_b128 v[218:221], v233 offset:56320
	global_load_lds_dwordx4 v180, s[98:99]
	s_add_i32 m0, s14, 0x2000
	s_add_u32 s14, s56, 0x40080
	s_addc_u32 s15, s57, 0
	s_add_i32 s33, s40, s66
	global_load_lds_dwordx4 v184, s[98:99]
	s_mov_b32 m0, s33
	s_nop 0
	global_load_lds_dwordx4 v180, s[14:15]
	s_add_i32 m0, s33, 0x2000
	s_nop 0
	global_load_lds_dwordx4 v184, s[14:15]
	s_mov_b32 m0, s76
	s_nop 0
	global_load_lds_dwordx4 v178, s[100:101]
	s_mov_b32 m0, s77
	s_nop 0
	global_load_lds_dwordx4 v182, s[100:101]
	s_waitcnt vmcnt(8)
	s_waitcnt lgkmcnt(0)
	s_barrier
	s_setprio 1
	s_waitcnt lgkmcnt(0)
	v_mfma_f32_16x16x32_bf16 v[90:93], v[62:65], v[174:177], v[90:93]
	v_mfma_f32_16x16x32_bf16 v[86:89], v[78:81], v[174:177], v[86:89]
	v_mfma_f32_16x16x32_bf16 v[74:77], v[62:65], v[198:201], v[74:77]
	v_mfma_f32_16x16x32_bf16 v[70:73], v[78:81], v[198:201], v[70:73]
	v_mfma_f32_16x16x32_bf16 v[50:53], v[62:65], v[206:209], v[50:53]
	v_mfma_f32_16x16x32_bf16 v[46:49], v[78:81], v[206:209], v[46:49]
	v_mfma_f32_16x16x32_bf16 v[26:29], v[62:65], v[214:217], v[26:29]
	v_mfma_f32_16x16x32_bf16 v[22:25], v[78:81], v[214:217], v[22:25]
	v_mfma_f32_16x16x32_bf16 v[90:93], v[66:69], v[194:197], v[90:93]
	v_mfma_f32_16x16x32_bf16 v[86:89], v[82:85], v[194:197], v[86:89]
	v_mfma_f32_16x16x32_bf16 v[74:77], v[66:69], v[202:205], v[74:77]
	v_mfma_f32_16x16x32_bf16 v[70:73], v[82:85], v[202:205], v[70:73]
	v_mfma_f32_16x16x32_bf16 v[50:53], v[66:69], v[210:213], v[50:53]
	v_mfma_f32_16x16x32_bf16 v[46:49], v[82:85], v[210:213], v[46:49]
	v_mfma_f32_16x16x32_bf16 v[26:29], v[66:69], v[218:221], v[26:29]
	v_mfma_f32_16x16x32_bf16 v[22:25], v[82:85], v[218:221], v[22:25]
	s_setprio 0
	s_setprio 1
	v_mfma_f32_16x16x32_bf16 v[38:41], v[126:129], v[174:177], v[38:41]
	v_mfma_f32_16x16x32_bf16 v[82:85], v[146:149], v[194:197], v[38:41]
	v_mfma_f32_16x16x32_bf16 v[38:41], v[166:169], v[174:177], v[42:45]
	v_mfma_f32_16x16x32_bf16 v[78:81], v[170:173], v[194:197], v[38:41]
	v_mfma_f32_16x16x32_bf16 v[38:41], v[126:129], v[198:201], v[54:57]
	v_mfma_f32_16x16x32_bf16 v[66:69], v[146:149], v[202:205], v[38:41]
	v_mfma_f32_16x16x32_bf16 v[38:41], v[166:169], v[198:201], v[58:61]
	v_mfma_f32_16x16x32_bf16 v[34:37], v[126:129], v[206:209], v[34:37]
	v_mfma_f32_16x16x32_bf16 v[30:33], v[166:169], v[206:209], v[30:33]
	v_mfma_f32_16x16x32_bf16 v[16:19], v[126:129], v[214:217], v[18:21]
	v_mfma_f32_16x16x32_bf16 v[12:15], v[166:169], v[214:217], v[12:15]
	v_mfma_f32_16x16x32_bf16 v[62:65], v[170:173], v[202:205], v[38:41]
	v_mfma_f32_16x16x32_bf16 v[34:37], v[146:149], v[210:213], v[34:37]
	v_mfma_f32_16x16x32_bf16 v[30:33], v[170:173], v[210:213], v[30:33]
	v_mfma_f32_16x16x32_bf16 v[18:21], v[146:149], v[218:221], v[16:19]
	v_mfma_f32_16x16x32_bf16 v[14:17], v[170:173], v[218:221], v[12:15]
	s_setprio 0
	s_barrier
	s_add_i32 s13, s13, 2
	s_add_u32 s10, s10, 0x100
	s_addc_u32 s11, s11, 0
	s_add_u32 s9, s9, 0x100
	s_addc_u32 s12, s12, 0
	s_cmp_gt_u32 s13, 13
	s_cbranch_scc0 .LBB0_774
	s_and_b64 vcc, exec, s[22:23]
	s_cbranch_vccz .LBB0_777
	s_barrier

.LBB0_1038:
	ds_read_b128 v[26:29], v214
	ds_read_b128 v[30:33], v214 offset:1024
	ds_read_b128 v[34:37], v214 offset:2048
	ds_read_b128 v[38:41], v214 offset:3072
	ds_read_b128 v[122:125], v215
	ds_read_b128 v[142:145], v215 offset:1024
	ds_read_b128 v[162:165], v215 offset:2048
	ds_read_b128 v[166:169], v215 offset:3072
	s_add_i32 s33, s31, 2
	s_add_u32 s40, s6, 0xfffd0080
	s_addc_u32 s41, s7, -1
	s_cmp_eq_u32 s13, s31
	s_cselect_b32 s55, s47, s41
	s_cselect_b32 s54, s46, s40
	s_cselect_b32 s53, s1, s15
	s_cselect_b32 s52, s2, s14
	s_add_i32 m0, s66, 0xc000
	ds_read_b128 v[170:173], v216
	ds_read_b128 v[174:177], v216 offset:1024
	ds_read_b128 v[178:181], v216 offset:2048
	ds_read_b128 v[198:201], v216 offset:3072
	ds_read_b128 v[202:205], v216 offset:4096
	ds_read_b128 v[206:209], v216 offset:5120
	ds_read_b128 v[220:223], v216 offset:6144
	ds_read_b128 v[228:231], v216 offset:7168
	global_load_lds_dwordx4 v190, s[6:7]
	s_add_i32 m0, s66, 0xe000
	s_nop 0
	global_load_lds_dwordx4 v192, s[6:7]
	s_waitcnt vmcnt(8)
	s_waitcnt lgkmcnt(0)
	s_barrier
	s_setprio 1
	s_waitcnt lgkmcnt(0)
	v_mfma_f32_16x16x32_bf16 v[158:161], v[26:29], v[170:173], v[158:161]
	v_mfma_f32_16x16x32_bf16 v[154:157], v[34:37], v[170:173], v[154:157]
	v_mfma_f32_16x16x32_bf16 v[138:141], v[26:29], v[178:181], v[138:141]
	v_mfma_f32_16x16x32_bf16 v[134:137], v[34:37], v[178:181], v[134:137]
	v_mfma_f32_16x16x32_bf16 v[118:121], v[26:29], v[202:205], v[118:121]
	v_mfma_f32_16x16x32_bf16 v[114:117], v[34:37], v[202:205], v[114:117]
	v_mfma_f32_16x16x32_bf16 v[102:105], v[26:29], v[220:223], v[102:105]
	v_mfma_f32_16x16x32_bf16 v[98:101], v[34:37], v[220:223], v[98:101]
	v_mfma_f32_16x16x32_bf16 v[158:161], v[30:33], v[174:177], v[158:161]
	v_mfma_f32_16x16x32_bf16 v[154:157], v[38:41], v[174:177], v[154:157]
	v_mfma_f32_16x16x32_bf16 v[138:141], v[30:33], v[198:201], v[138:141]
	v_mfma_f32_16x16x32_bf16 v[134:137], v[38:41], v[198:201], v[134:137]
	v_mfma_f32_16x16x32_bf16 v[118:121], v[30:33], v[206:209], v[118:121]
	v_mfma_f32_16x16x32_bf16 v[114:117], v[38:41], v[206:209], v[114:117]
	v_mfma_f32_16x16x32_bf16 v[102:105], v[30:33], v[228:231], v[102:105]
	v_mfma_f32_16x16x32_bf16 v[98:101], v[38:41], v[228:231], v[98:101]
	s_setprio 0
	s_setprio 1
	v_mfma_f32_16x16x32_bf16 v[150:153], v[122:125], v[170:173], v[150:153]
	v_mfma_f32_16x16x32_bf16 v[146:149], v[162:165], v[170:173], v[146:149]
	v_mfma_f32_16x16x32_bf16 v[130:133], v[122:125], v[178:181], v[130:133]
	v_mfma_f32_16x16x32_bf16 v[126:129], v[162:165], v[178:181], v[126:129]
	v_mfma_f32_16x16x32_bf16 v[110:113], v[122:125], v[202:205], v[110:113]
	v_mfma_f32_16x16x32_bf16 v[106:109], v[162:165], v[202:205], v[106:109]
	v_mfma_f32_16x16x32_bf16 v[94:97], v[122:125], v[220:223], v[94:97]
	v_mfma_f32_16x16x32_bf16 v[90:93], v[162:165], v[220:223], v[90:93]
	v_mfma_f32_16x16x32_bf16 v[150:153], v[142:145], v[174:177], v[150:153]
	v_mfma_f32_16x16x32_bf16 v[146:149], v[166:169], v[174:177], v[146:149]
	v_mfma_f32_16x16x32_bf16 v[130:133], v[142:145], v[198:201], v[130:133]
	v_mfma_f32_16x16x32_bf16 v[126:129], v[166:169], v[198:201], v[126:129]
	v_mfma_f32_16x16x32_bf16 v[110:113], v[142:145], v[206:209], v[110:113]
	v_mfma_f32_16x16x32_bf16 v[106:109], v[166:169], v[206:209], v[106:109]
	v_mfma_f32_16x16x32_bf16 v[94:97], v[142:145], v[228:231], v[94:97]
	v_mfma_f32_16x16x32_bf16 v[90:93], v[166:169], v[228:231], v[90:93]
	s_setprio 0
	s_barrier
	s_add_i32 s31, s85, s64
	s_add_u32 s98, s52, s18
	s_addc_u32 s99, s53, s19
	s_mov_b32 m0, s31
	ds_read_b128 v[170:173], v216 offset:16384
	ds_read_b128 v[174:177], v216 offset:17408
	ds_read_b128 v[178:181], v216 offset:18432
	ds_read_b128 v[198:201], v216 offset:19456
	ds_read_b128 v[202:205], v216 offset:20480
	ds_read_b128 v[206:209], v216 offset:21504
	ds_read_b128 v[220:223], v216 offset:22528
	ds_read_b128 v[228:231], v216 offset:23552
	global_load_lds_dwordx4 v184, s[52:53]
	s_add_i32 m0, s31, 0x2000
	s_add_u32 s40, s52, 0x10000
	s_addc_u32 s41, s53, 0
	s_add_i32 s31, s86, s64
	global_load_lds_dwordx4 v188, s[52:53]
	s_mov_b32 m0, s31
	s_add_u32 s100, s54, s18
	s_addc_u32 s101, s55, s19
	global_load_lds_dwordx4 v184, s[40:41]
	s_add_i32 m0, s31, 0x2000
	s_nop 0
	global_load_lds_dwordx4 v188, s[40:41]
	s_mov_b32 m0, s66
	s_nop 0
	global_load_lds_dwordx4 v182, s[54:55]
	s_mov_b32 m0, s67
	s_nop 0
	global_load_lds_dwordx4 v186, s[54:55]
	s_waitcnt vmcnt(8)
	s_waitcnt lgkmcnt(0)
	s_barrier
	s_setprio 1
	s_waitcnt lgkmcnt(0)
	v_mfma_f32_16x16x32_bf16 v[86:89], v[26:29], v[170:173], v[86:89]
	v_mfma_f32_16x16x32_bf16 v[82:85], v[34:37], v[170:173], v[82:85]
	v_mfma_f32_16x16x32_bf16 v[70:73], v[26:29], v[178:181], v[70:73]
	v_mfma_f32_16x16x32_bf16 v[66:69], v[34:37], v[178:181], v[66:69]
	v_mfma_f32_16x16x32_bf16 v[54:57], v[26:29], v[202:205], v[54:57]
	v_mfma_f32_16x16x32_bf16 v[50:53], v[34:37], v[202:205], v[50:53]
	v_mfma_f32_16x16x32_bf16 v[22:25], v[26:29], v[220:223], v[22:25]
	v_mfma_f32_16x16x32_bf16 v[18:21], v[34:37], v[220:223], v[18:21]
	v_mfma_f32_16x16x32_bf16 v[86:89], v[30:33], v[174:177], v[86:89]
	v_mfma_f32_16x16x32_bf16 v[82:85], v[38:41], v[174:177], v[82:85]
	v_mfma_f32_16x16x32_bf16 v[70:73], v[30:33], v[198:201], v[70:73]
	v_mfma_f32_16x16x32_bf16 v[66:69], v[38:41], v[198:201], v[66:69]
	v_mfma_f32_16x16x32_bf16 v[54:57], v[30:33], v[206:209], v[54:57]
	v_mfma_f32_16x16x32_bf16 v[50:53], v[38:41], v[206:209], v[50:53]
	v_mfma_f32_16x16x32_bf16 v[22:25], v[30:33], v[228:231], v[22:25]
	v_mfma_f32_16x16x32_bf16 v[18:21], v[38:41], v[228:231], v[18:21]
	s_setprio 0
	s_setprio 1
	v_mfma_f32_16x16x32_bf16 v[46:49], v[122:125], v[202:205], v[46:49]
	v_mfma_f32_16x16x32_bf16 v[42:45], v[162:165], v[202:205], v[42:45]
	v_mfma_f32_16x16x32_bf16 v[14:17], v[122:125], v[220:223], v[14:17]
	v_mfma_f32_16x16x32_bf16 v[8:11], v[162:165], v[220:223], v[10:13]
	v_mfma_f32_16x16x32_bf16 v[26:29], v[122:125], v[170:173], v[78:81]
	v_mfma_f32_16x16x32_bf16 v[30:33], v[162:165], v[170:173], v[74:77]
	v_mfma_f32_16x16x32_bf16 v[34:37], v[122:125], v[178:181], v[62:65]
	v_mfma_f32_16x16x32_bf16 v[38:41], v[162:165], v[178:181], v[58:61]
	v_mfma_f32_16x16x32_bf16 v[46:49], v[142:145], v[206:209], v[46:49]
	v_mfma_f32_16x16x32_bf16 v[42:45], v[166:169], v[206:209], v[42:45]
	v_mfma_f32_16x16x32_bf16 v[14:17], v[142:145], v[228:231], v[14:17]
	v_mfma_f32_16x16x32_bf16 v[8:11], v[166:169], v[228:231], v[8:11]
	v_mfma_f32_16x16x32_bf16 v[26:29], v[142:145], v[174:177], v[26:29]
	v_mfma_f32_16x16x32_bf16 v[30:33], v[166:169], v[174:177], v[30:33]
	v_mfma_f32_16x16x32_bf16 v[34:37], v[142:145], v[198:201], v[34:37]
	v_mfma_f32_16x16x32_bf16 v[38:41], v[166:169], v[198:201], v[38:41]
	s_setprio 0
	s_barrier
	s_add_i32 s31, 0, 0x18000
	v_add_u32_e32 v3, s31, v213
	s_add_i32 s42, 0, 0x1c000
	ds_read_b128 v[58:61], v3
	ds_read_b128 v[62:65], v3 offset:1024
	ds_read_b128 v[74:77], v3 offset:2048
	ds_read_b128 v[78:81], v3 offset:3072
	v_add_u32_e32 v3, s42, v213
	ds_read_b128 v[122:125], v3
	ds_read_b128 v[142:145], v3 offset:1024
	ds_read_b128 v[162:165], v3 offset:2048
	ds_read_b128 v[166:169], v3 offset:3072
	s_add_u32 s40, s54, 0x30000
	s_addc_u32 s41, s55, 0
	s_mov_b32 m0, s68
	ds_read_b128 v[170:173], v216 offset:32768
	ds_read_b128 v[174:177], v216 offset:33792
	ds_read_b128 v[178:181], v216 offset:34816
	ds_read_b128 v[198:201], v216 offset:35840
	ds_read_b128 v[202:205], v216 offset:36864
	ds_read_b128 v[206:209], v216 offset:37888
	ds_read_b128 v[220:223], v216 offset:38912
	ds_read_b128 v[228:231], v216 offset:39936
	global_load_lds_dwordx4 v182, s[40:41]
	s_mov_b32 m0, s69
	s_nop 0
	global_load_lds_dwordx4 v186, s[40:41]
	s_waitcnt vmcnt(8)
	s_waitcnt lgkmcnt(0)
	s_barrier
	s_setprio 1
	s_waitcnt lgkmcnt(0)
	v_mfma_f32_16x16x32_bf16 v[158:161], v[58:61], v[170:173], v[158:161]
	v_mfma_f32_16x16x32_bf16 v[154:157], v[74:77], v[170:173], v[154:157]
	v_mfma_f32_16x16x32_bf16 v[138:141], v[58:61], v[178:181], v[138:141]
	v_mfma_f32_16x16x32_bf16 v[134:137], v[74:77], v[178:181], v[134:137]
	v_mfma_f32_16x16x32_bf16 v[118:121], v[58:61], v[202:205], v[118:121]
	v_mfma_f32_16x16x32_bf16 v[114:117], v[74:77], v[202:205], v[114:117]
	v_mfma_f32_16x16x32_bf16 v[102:105], v[58:61], v[220:223], v[102:105]
	v_mfma_f32_16x16x32_bf16 v[98:101], v[74:77], v[220:223], v[98:101]
	v_mfma_f32_16x16x32_bf16 v[158:161], v[62:65], v[174:177], v[158:161]
	v_mfma_f32_16x16x32_bf16 v[154:157], v[78:81], v[174:177], v[154:157]
	v_mfma_f32_16x16x32_bf16 v[138:141], v[62:65], v[198:201], v[138:141]
	v_mfma_f32_16x16x32_bf16 v[134:137], v[78:81], v[198:201], v[134:137]
	v_mfma_f32_16x16x32_bf16 v[118:121], v[62:65], v[206:209], v[118:121]
	v_mfma_f32_16x16x32_bf16 v[114:117], v[78:81], v[206:209], v[114:117]
	v_mfma_f32_16x16x32_bf16 v[102:105], v[62:65], v[228:231], v[102:105]
	v_mfma_f32_16x16x32_bf16 v[98:101], v[78:81], v[228:231], v[98:101]
	s_setprio 0
	s_setprio 1
	v_mfma_f32_16x16x32_bf16 v[150:153], v[122:125], v[170:173], v[150:153]
	v_mfma_f32_16x16x32_bf16 v[146:149], v[162:165], v[170:173], v[146:149]
	v_mfma_f32_16x16x32_bf16 v[130:133], v[122:125], v[178:181], v[130:133]
	v_mfma_f32_16x16x32_bf16 v[126:129], v[162:165], v[178:181], v[126:129]
	v_mfma_f32_16x16x32_bf16 v[110:113], v[122:125], v[202:205], v[110:113]
	v_mfma_f32_16x16x32_bf16 v[106:109], v[162:165], v[202:205], v[106:109]
	v_mfma_f32_16x16x32_bf16 v[94:97], v[122:125], v[220:223], v[94:97]
	v_mfma_f32_16x16x32_bf16 v[90:93], v[162:165], v[220:223], v[90:93]
	v_mfma_f32_16x16x32_bf16 v[150:153], v[142:145], v[174:177], v[150:153]
	v_mfma_f32_16x16x32_bf16 v[146:149], v[166:169], v[174:177], v[146:149]
	v_mfma_f32_16x16x32_bf16 v[130:133], v[142:145], v[198:201], v[130:133]
	v_mfma_f32_16x16x32_bf16 v[126:129], v[166:169], v[198:201], v[126:129]
	v_mfma_f32_16x16x32_bf16 v[110:113], v[142:145], v[206:209], v[110:113]
	v_mfma_f32_16x16x32_bf16 v[106:109], v[166:169], v[206:209], v[106:109]
	v_mfma_f32_16x16x32_bf16 v[94:97], v[142:145], v[228:231], v[94:97]
	v_mfma_f32_16x16x32_bf16 v[90:93], v[166:169], v[228:231], v[90:93]
	s_setprio 0
	s_barrier
	s_add_i32 s31, s31, s64
	s_mov_b32 m0, s31
	ds_read_b128 v[170:173], v216 offset:49152
	ds_read_b128 v[174:177], v216 offset:50176
	ds_read_b128 v[178:181], v216 offset:51200
	ds_read_b128 v[198:201], v216 offset:52224
	ds_read_b128 v[202:205], v216 offset:53248
	ds_read_b128 v[206:209], v216 offset:54272
	ds_read_b128 v[220:223], v216 offset:55296
	ds_read_b128 v[228:231], v216 offset:56320
	global_load_lds_dwordx4 v184, s[98:99]
	s_add_i32 m0, s31, 0x2000
	s_add_u32 s40, s52, 0x10080
	s_addc_u32 s41, s53, 0
	s_add_i32 s31, s42, s64
	global_load_lds_dwordx4 v188, s[98:99]
	s_mov_b32 m0, s31
	s_nop 0
	global_load_lds_dwordx4 v184, s[40:41]
	s_add_i32 m0, s31, 0x2000
	s_nop 0
	global_load_lds_dwordx4 v188, s[40:41]
	s_mov_b32 m0, s76
	s_nop 0
	global_load_lds_dwordx4 v182, s[100:101]
	s_mov_b32 m0, s77
	s_nop 0
	global_load_lds_dwordx4 v186, s[100:101]
	s_waitcnt vmcnt(8)
	s_waitcnt lgkmcnt(0)
	s_barrier
	s_setprio 1
	s_waitcnt lgkmcnt(0)
	v_mfma_f32_16x16x32_bf16 v[86:89], v[58:61], v[170:173], v[86:89]
	v_mfma_f32_16x16x32_bf16 v[82:85], v[74:77], v[170:173], v[82:85]
	v_mfma_f32_16x16x32_bf16 v[70:73], v[58:61], v[178:181], v[70:73]
	v_mfma_f32_16x16x32_bf16 v[66:69], v[74:77], v[178:181], v[66:69]
	v_mfma_f32_16x16x32_bf16 v[54:57], v[58:61], v[202:205], v[54:57]
	v_mfma_f32_16x16x32_bf16 v[50:53], v[74:77], v[202:205], v[50:53]
	v_mfma_f32_16x16x32_bf16 v[22:25], v[58:61], v[220:223], v[22:25]
	v_mfma_f32_16x16x32_bf16 v[18:21], v[74:77], v[220:223], v[18:21]
	v_mfma_f32_16x16x32_bf16 v[86:89], v[62:65], v[174:177], v[86:89]
	v_mfma_f32_16x16x32_bf16 v[82:85], v[78:81], v[174:177], v[82:85]
	v_mfma_f32_16x16x32_bf16 v[70:73], v[62:65], v[198:201], v[70:73]
	v_mfma_f32_16x16x32_bf16 v[66:69], v[78:81], v[198:201], v[66:69]
	v_mfma_f32_16x16x32_bf16 v[54:57], v[62:65], v[206:209], v[54:57]
	v_mfma_f32_16x16x32_bf16 v[50:53], v[78:81], v[206:209], v[50:53]
	v_mfma_f32_16x16x32_bf16 v[22:25], v[62:65], v[228:231], v[22:25]
	v_mfma_f32_16x16x32_bf16 v[18:21], v[78:81], v[228:231], v[18:21]
	s_setprio 0
	s_setprio 1
	v_mfma_f32_16x16x32_bf16 v[26:29], v[122:125], v[170:173], v[26:29]
	v_mfma_f32_16x16x32_bf16 v[78:81], v[142:145], v[174:177], v[26:29]
	v_mfma_f32_16x16x32_bf16 v[26:29], v[162:165], v[170:173], v[30:33]
	v_mfma_f32_16x16x32_bf16 v[74:77], v[166:169], v[174:177], v[26:29]
	v_mfma_f32_16x16x32_bf16 v[26:29], v[122:125], v[178:181], v[34:37]
	v_mfma_f32_16x16x32_bf16 v[62:65], v[142:145], v[198:201], v[26:29]
	v_mfma_f32_16x16x32_bf16 v[26:29], v[162:165], v[178:181], v[38:41]
	v_mfma_f32_16x16x32_bf16 v[58:61], v[166:169], v[198:201], v[26:29]
	v_mfma_f32_16x16x32_bf16 v[26:29], v[122:125], v[202:205], v[46:49]
	v_mfma_f32_16x16x32_bf16 v[46:49], v[142:145], v[206:209], v[26:29]
	v_mfma_f32_16x16x32_bf16 v[26:29], v[162:165], v[202:205], v[42:45]
	v_mfma_f32_16x16x32_bf16 v[12:15], v[122:125], v[220:223], v[14:17]
	v_mfma_f32_16x16x32_bf16 v[8:11], v[162:165], v[220:223], v[8:11]
	v_mfma_f32_16x16x32_bf16 v[42:45], v[166:169], v[206:209], v[26:29]
	v_mfma_f32_16x16x32_bf16 v[14:17], v[142:145], v[228:231], v[12:15]
	v_mfma_f32_16x16x32_bf16 v[10:13], v[166:169], v[228:231], v[8:11]
	s_setprio 0
	s_barrier
	s_add_u32 s6, s6, 0x100
	s_addc_u32 s7, s7, 0
	s_add_u32 s14, s14, 0x100
	s_addc_u32 s15, s15, 0
	s_cmp_ge_u32 s33, s12
	s_mov_b32 s31, s33
	s_cbranch_scc0 .LBB0_1038
	s_and_b64 vcc, exec, s[20:21]
	s_cbranch_vccz .LBB0_1041
	s_barrier

.LBB0_1631:
	v_add_u32_e32 v153, s44, v151
	ds_read_b128 v[154:157], v153
	ds_read_b128 v[158:161], v153 offset:1024
	ds_read_b128 v[162:165], v153 offset:2048
	ds_read_b128 v[166:169], v153 offset:3072
	v_add_u32_e32 v153, s45, v151
	s_add_u32 s46, s18, s30
	ds_read_b128 v[170:173], v153
	ds_read_b128 v[174:177], v153 offset:1024
	ds_read_b128 v[178:181], v153 offset:2048
	ds_read_b128 v[182:185], v153 offset:3072
	s_addc_u32 s47, s19, s31
	s_add_u32 s46, s46, 0x100
	s_addc_u32 s47, s47, 0
	s_add_u32 s55, s50, s30
	s_addc_u32 s56, s51, s31
	s_cmpk_eq_i32 s30, 0x700
	s_cselect_b32 s49, s25, s47
	s_cselect_b32 s48, s52, s46
	s_cselect_b32 s47, s23, s56
	s_cselect_b32 s46, s53, s55
	v_lshl_add_u64 v[218:219], v[146:147], 0, s[30:31]
	s_add_i32 m0, s33, 0xc000
	ds_read_b128 v[186:189], v152
	ds_read_b128 v[190:193], v152 offset:1024
	ds_read_b128 v[194:197], v152 offset:2048
	ds_read_b128 v[198:201], v152 offset:3072
	ds_read_b128 v[202:205], v152 offset:4096
	ds_read_b128 v[206:209], v152 offset:5120
	ds_read_b128 v[210:213], v152 offset:6144
	ds_read_b128 v[214:217], v152 offset:7168
	global_load_lds_dwordx4 v[218:219], off
	v_lshl_add_u64 v[218:219], v[148:149], 0, s[30:31]
	s_add_i32 m0, s33, 0xe000
	s_nop 0
	global_load_lds_dwordx4 v[218:219], off
	s_waitcnt vmcnt(8)
	s_waitcnt lgkmcnt(0)
	s_barrier
	s_setprio 1
	s_waitcnt lgkmcnt(0)
	v_mfma_f32_16x16x32_bf16 v[126:129], v[154:157], v[186:189], v[126:129]
	v_mfma_f32_16x16x32_bf16 v[122:125], v[162:165], v[186:189], v[122:125]
	v_mfma_f32_16x16x32_bf16 v[110:113], v[154:157], v[194:197], v[110:113]
	v_mfma_f32_16x16x32_bf16 v[106:109], v[162:165], v[194:197], v[106:109]
	v_mfma_f32_16x16x32_bf16 v[94:97], v[154:157], v[202:205], v[94:97]
	v_mfma_f32_16x16x32_bf16 v[90:93], v[162:165], v[202:205], v[90:93]
	v_mfma_f32_16x16x32_bf16 v[78:81], v[154:157], v[210:213], v[78:81]
	v_mfma_f32_16x16x32_bf16 v[74:77], v[162:165], v[210:213], v[74:77]
	v_mfma_f32_16x16x32_bf16 v[126:129], v[158:161], v[190:193], v[126:129]
	v_mfma_f32_16x16x32_bf16 v[122:125], v[166:169], v[190:193], v[122:125]
	v_mfma_f32_16x16x32_bf16 v[110:113], v[158:161], v[198:201], v[110:113]
	v_mfma_f32_16x16x32_bf16 v[106:109], v[166:169], v[198:201], v[106:109]
	v_mfma_f32_16x16x32_bf16 v[94:97], v[158:161], v[206:209], v[94:97]
	v_mfma_f32_16x16x32_bf16 v[90:93], v[166:169], v[206:209], v[90:93]
	v_mfma_f32_16x16x32_bf16 v[78:81], v[158:161], v[214:217], v[78:81]
	v_mfma_f32_16x16x32_bf16 v[74:77], v[166:169], v[214:217], v[74:77]
	s_setprio 0
	s_setprio 1
	v_mfma_f32_16x16x32_bf16 v[118:121], v[170:173], v[186:189], v[118:121]
	v_mfma_f32_16x16x32_bf16 v[114:117], v[178:181], v[186:189], v[114:117]
	v_mfma_f32_16x16x32_bf16 v[102:105], v[170:173], v[194:197], v[102:105]
	v_mfma_f32_16x16x32_bf16 v[98:101], v[178:181], v[194:197], v[98:101]
	v_mfma_f32_16x16x32_bf16 v[86:89], v[170:173], v[202:205], v[86:89]
	v_mfma_f32_16x16x32_bf16 v[82:85], v[178:181], v[202:205], v[82:85]
	v_mfma_f32_16x16x32_bf16 v[70:73], v[170:173], v[210:213], v[70:73]
	v_mfma_f32_16x16x32_bf16 v[66:69], v[178:181], v[210:213], v[66:69]
	v_mfma_f32_16x16x32_bf16 v[118:121], v[174:177], v[190:193], v[118:121]
	v_mfma_f32_16x16x32_bf16 v[114:117], v[182:185], v[190:193], v[114:117]
	v_mfma_f32_16x16x32_bf16 v[102:105], v[174:177], v[198:201], v[102:105]
	v_mfma_f32_16x16x32_bf16 v[98:101], v[182:185], v[198:201], v[98:101]
	v_mfma_f32_16x16x32_bf16 v[86:89], v[174:177], v[206:209], v[86:89]
	v_mfma_f32_16x16x32_bf16 v[82:85], v[182:185], v[206:209], v[82:85]
	v_mfma_f32_16x16x32_bf16 v[70:73], v[174:177], v[214:217], v[70:73]
	v_mfma_f32_16x16x32_bf16 v[66:69], v[182:185], v[214:217], v[66:69]
	s_setprio 0
	s_barrier
	s_add_i32 s55, s44, s13
	s_add_u32 s98, s46, s20
	s_addc_u32 s99, s47, s21
	s_mov_b32 m0, s55
	ds_read_b128 v[186:189], v152 offset:16384
	ds_read_b128 v[190:193], v152 offset:17408
	ds_read_b128 v[194:197], v152 offset:18432
	ds_read_b128 v[198:201], v152 offset:19456
	ds_read_b128 v[202:205], v152 offset:20480
	ds_read_b128 v[206:209], v152 offset:21504
	ds_read_b128 v[210:213], v152 offset:22528
	ds_read_b128 v[214:217], v152 offset:23552
	global_load_lds_dwordx4 v132, s[46:47]
	s_add_i32 m0, s55, 0x2000
	s_add_u32 s56, s46, 0x40000
	s_addc_u32 s57, s47, 0
	s_add_i32 s55, s45, s13
	global_load_lds_dwordx4 v136, s[46:47]
	s_mov_b32 m0, s55
	s_nop 0
	global_load_lds_dwordx4 v132, s[56:57]
	s_add_i32 m0, s55, 0x2000
	s_nop 0
	global_load_lds_dwordx4 v136, s[56:57]
	s_add_u32 s100, s48, s20
	s_addc_u32 s101, s49, s21
	s_mov_b32 m0, s33
	s_nop 0
	global_load_lds_dwordx4 v130, s[48:49]
	s_mov_b32 m0, s14
	s_nop 0
	global_load_lds_dwordx4 v134, s[48:49]
	s_waitcnt vmcnt(8)
	s_waitcnt lgkmcnt(0)
	s_barrier
	s_setprio 1
	s_waitcnt lgkmcnt(0)
	v_mfma_f32_16x16x32_bf16 v[62:65], v[154:157], v[186:189], v[62:65]
	v_mfma_f32_16x16x32_bf16 v[58:61], v[162:165], v[186:189], v[58:61]
	v_mfma_f32_16x16x32_bf16 v[46:49], v[154:157], v[194:197], v[46:49]
	v_mfma_f32_16x16x32_bf16 v[42:45], v[162:165], v[194:197], v[42:45]
	v_mfma_f32_16x16x32_bf16 v[30:33], v[154:157], v[202:205], v[30:33]
	v_mfma_f32_16x16x32_bf16 v[26:29], v[162:165], v[202:205], v[26:29]
	v_mfma_f32_16x16x32_bf16 v[14:17], v[154:157], v[210:213], v[14:17]
	v_mfma_f32_16x16x32_bf16 v[10:13], v[162:165], v[210:213], v[10:13]
	v_mfma_f32_16x16x32_bf16 v[62:65], v[158:161], v[190:193], v[62:65]
	v_mfma_f32_16x16x32_bf16 v[58:61], v[166:169], v[190:193], v[58:61]
	v_mfma_f32_16x16x32_bf16 v[46:49], v[158:161], v[198:201], v[46:49]
	v_mfma_f32_16x16x32_bf16 v[42:45], v[166:169], v[198:201], v[42:45]
	v_mfma_f32_16x16x32_bf16 v[30:33], v[158:161], v[206:209], v[30:33]
	v_mfma_f32_16x16x32_bf16 v[26:29], v[166:169], v[206:209], v[26:29]
	v_mfma_f32_16x16x32_bf16 v[14:17], v[158:161], v[214:217], v[14:17]
	v_mfma_f32_16x16x32_bf16 v[10:13], v[166:169], v[214:217], v[10:13]
	s_setprio 0
	s_setprio 1
	v_mfma_f32_16x16x32_bf16 v[54:57], v[170:173], v[186:189], v[54:57]
	v_mfma_f32_16x16x32_bf16 v[50:53], v[178:181], v[186:189], v[50:53]
	v_mfma_f32_16x16x32_bf16 v[38:41], v[170:173], v[194:197], v[38:41]
	v_mfma_f32_16x16x32_bf16 v[34:37], v[178:181], v[194:197], v[34:37]
	v_mfma_f32_16x16x32_bf16 v[22:25], v[170:173], v[202:205], v[22:25]
	v_mfma_f32_16x16x32_bf16 v[18:21], v[178:181], v[202:205], v[18:21]
	v_mfma_f32_16x16x32_bf16 v[6:9], v[170:173], v[210:213], v[6:9]
	v_mfma_f32_16x16x32_bf16 v[2:5], v[178:181], v[210:213], v[2:5]
	v_mfma_f32_16x16x32_bf16 v[54:57], v[174:177], v[190:193], v[54:57]
	v_mfma_f32_16x16x32_bf16 v[50:53], v[182:185], v[190:193], v[50:53]
	v_mfma_f32_16x16x32_bf16 v[38:41], v[174:177], v[198:201], v[38:41]
	v_mfma_f32_16x16x32_bf16 v[34:37], v[182:185], v[198:201], v[34:37]
	v_mfma_f32_16x16x32_bf16 v[22:25], v[174:177], v[206:209], v[22:25]
	v_mfma_f32_16x16x32_bf16 v[18:21], v[182:185], v[206:209], v[18:21]
	v_mfma_f32_16x16x32_bf16 v[6:9], v[174:177], v[214:217], v[6:9]
	v_mfma_f32_16x16x32_bf16 v[2:5], v[182:185], v[214:217], v[2:5]
	s_setprio 0
	s_barrier
	s_add_i32 s55, 0, 0x18000
	v_add_u32_e32 v153, s55, v151
	s_add_i32 s56, 0, 0x1c000
	ds_read_b128 v[154:157], v153
	ds_read_b128 v[158:161], v153 offset:1024
	ds_read_b128 v[162:165], v153 offset:2048
	ds_read_b128 v[166:169], v153 offset:3072
	v_add_u32_e32 v153, s56, v151
	ds_read_b128 v[170:173], v153
	ds_read_b128 v[174:177], v153 offset:1024
	ds_read_b128 v[178:181], v153 offset:2048
	ds_read_b128 v[182:185], v153 offset:3072
	s_add_u32 s48, s48, 0x40000
	s_addc_u32 s49, s49, 0
	s_mov_b32 m0, s15
	ds_read_b128 v[186:189], v152 offset:32768
	ds_read_b128 v[190:193], v152 offset:33792
	ds_read_b128 v[194:197], v152 offset:34816
	ds_read_b128 v[198:201], v152 offset:35840
	ds_read_b128 v[202:205], v152 offset:36864
	ds_read_b128 v[206:209], v152 offset:37888
	ds_read_b128 v[210:213], v152 offset:38912
	ds_read_b128 v[214:217], v152 offset:39936
	global_load_lds_dwordx4 v130, s[48:49]
	s_mov_b32 m0, s40
	s_nop 0
	global_load_lds_dwordx4 v134, s[48:49]
	s_waitcnt vmcnt(8)
	s_waitcnt lgkmcnt(0)
	s_barrier
	s_setprio 1
	s_waitcnt lgkmcnt(0)
	v_mfma_f32_16x16x32_bf16 v[126:129], v[154:157], v[186:189], v[126:129]
	v_mfma_f32_16x16x32_bf16 v[122:125], v[162:165], v[186:189], v[122:125]
	v_mfma_f32_16x16x32_bf16 v[110:113], v[154:157], v[194:197], v[110:113]
	v_mfma_f32_16x16x32_bf16 v[106:109], v[162:165], v[194:197], v[106:109]
	v_mfma_f32_16x16x32_bf16 v[94:97], v[154:157], v[202:205], v[94:97]
	v_mfma_f32_16x16x32_bf16 v[90:93], v[162:165], v[202:205], v[90:93]
	v_mfma_f32_16x16x32_bf16 v[78:81], v[154:157], v[210:213], v[78:81]
	v_mfma_f32_16x16x32_bf16 v[74:77], v[162:165], v[210:213], v[74:77]
	v_mfma_f32_16x16x32_bf16 v[126:129], v[158:161], v[190:193], v[126:129]
	v_mfma_f32_16x16x32_bf16 v[122:125], v[166:169], v[190:193], v[122:125]
	v_mfma_f32_16x16x32_bf16 v[110:113], v[158:161], v[198:201], v[110:113]
	v_mfma_f32_16x16x32_bf16 v[106:109], v[166:169], v[198:201], v[106:109]
	v_mfma_f32_16x16x32_bf16 v[94:97], v[158:161], v[206:209], v[94:97]
	v_mfma_f32_16x16x32_bf16 v[90:93], v[166:169], v[206:209], v[90:93]
	v_mfma_f32_16x16x32_bf16 v[78:81], v[158:161], v[214:217], v[78:81]
	v_mfma_f32_16x16x32_bf16 v[74:77], v[166:169], v[214:217], v[74:77]
	s_setprio 0
	s_setprio 1
	v_mfma_f32_16x16x32_bf16 v[118:121], v[170:173], v[186:189], v[118:121]
	v_mfma_f32_16x16x32_bf16 v[114:117], v[178:181], v[186:189], v[114:117]
	v_mfma_f32_16x16x32_bf16 v[102:105], v[170:173], v[194:197], v[102:105]
	v_mfma_f32_16x16x32_bf16 v[98:101], v[178:181], v[194:197], v[98:101]
	v_mfma_f32_16x16x32_bf16 v[86:89], v[170:173], v[202:205], v[86:89]
	v_mfma_f32_16x16x32_bf16 v[82:85], v[178:181], v[202:205], v[82:85]
	v_mfma_f32_16x16x32_bf16 v[70:73], v[170:173], v[210:213], v[70:73]
	v_mfma_f32_16x16x32_bf16 v[66:69], v[178:181], v[210:213], v[66:69]
	v_mfma_f32_16x16x32_bf16 v[118:121], v[174:177], v[190:193], v[118:121]
	v_mfma_f32_16x16x32_bf16 v[114:117], v[182:185], v[190:193], v[114:117]
	v_mfma_f32_16x16x32_bf16 v[102:105], v[174:177], v[198:201], v[102:105]
	v_mfma_f32_16x16x32_bf16 v[98:101], v[182:185], v[198:201], v[98:101]
	v_mfma_f32_16x16x32_bf16 v[86:89], v[174:177], v[206:209], v[86:89]
	v_mfma_f32_16x16x32_bf16 v[82:85], v[182:185], v[206:209], v[82:85]
	v_mfma_f32_16x16x32_bf16 v[70:73], v[174:177], v[214:217], v[70:73]
	v_mfma_f32_16x16x32_bf16 v[66:69], v[182:185], v[214:217], v[66:69]
	s_setprio 0
	s_barrier
	s_add_i32 s48, s55, s13
	s_mov_b32 m0, s48
	ds_read_b128 v[186:189], v152 offset:49152
	ds_read_b128 v[190:193], v152 offset:50176
	ds_read_b128 v[194:197], v152 offset:51200
	ds_read_b128 v[198:201], v152 offset:52224
	ds_read_b128 v[202:205], v152 offset:53248
	ds_read_b128 v[206:209], v152 offset:54272
	ds_read_b128 v[210:213], v152 offset:55296
	ds_read_b128 v[214:217], v152 offset:56320
	global_load_lds_dwordx4 v132, s[98:99]
	s_add_i32 m0, s48, 0x2000
	s_add_u32 s46, s46, 0x40080
	s_addc_u32 s47, s47, 0
	s_add_i32 s48, s56, s13
	global_load_lds_dwordx4 v136, s[98:99]
	s_mov_b32 m0, s48
	s_nop 0
	global_load_lds_dwordx4 v132, s[46:47]
	s_add_i32 m0, s48, 0x2000
	s_nop 0
	global_load_lds_dwordx4 v136, s[46:47]
	s_mov_b32 m0, s42
	s_nop 0
	global_load_lds_dwordx4 v130, s[100:101]
	s_mov_b32 m0, s43
	s_nop 0
	global_load_lds_dwordx4 v134, s[100:101]
	s_waitcnt vmcnt(8)
	s_waitcnt lgkmcnt(0)
	s_barrier
	s_setprio 1
	s_waitcnt lgkmcnt(0)
	v_mfma_f32_16x16x32_bf16 v[62:65], v[154:157], v[186:189], v[62:65]
	v_mfma_f32_16x16x32_bf16 v[58:61], v[162:165], v[186:189], v[58:61]
	v_mfma_f32_16x16x32_bf16 v[46:49], v[154:157], v[194:197], v[46:49]
	v_mfma_f32_16x16x32_bf16 v[42:45], v[162:165], v[194:197], v[42:45]
	v_mfma_f32_16x16x32_bf16 v[30:33], v[154:157], v[202:205], v[30:33]
	v_mfma_f32_16x16x32_bf16 v[26:29], v[162:165], v[202:205], v[26:29]
	v_mfma_f32_16x16x32_bf16 v[14:17], v[154:157], v[210:213], v[14:17]
	v_mfma_f32_16x16x32_bf16 v[10:13], v[162:165], v[210:213], v[10:13]
	v_mfma_f32_16x16x32_bf16 v[62:65], v[158:161], v[190:193], v[62:65]
	v_mfma_f32_16x16x32_bf16 v[58:61], v[166:169], v[190:193], v[58:61]
	v_mfma_f32_16x16x32_bf16 v[46:49], v[158:161], v[198:201], v[46:49]
	v_mfma_f32_16x16x32_bf16 v[42:45], v[166:169], v[198:201], v[42:45]
	v_mfma_f32_16x16x32_bf16 v[30:33], v[158:161], v[206:209], v[30:33]
	v_mfma_f32_16x16x32_bf16 v[26:29], v[166:169], v[206:209], v[26:29]
	v_mfma_f32_16x16x32_bf16 v[14:17], v[158:161], v[214:217], v[14:17]
	v_mfma_f32_16x16x32_bf16 v[10:13], v[166:169], v[214:217], v[10:13]
	s_setprio 0
	s_setprio 1
	v_mfma_f32_16x16x32_bf16 v[54:57], v[170:173], v[186:189], v[54:57]
	v_mfma_f32_16x16x32_bf16 v[50:53], v[178:181], v[186:189], v[50:53]
	v_mfma_f32_16x16x32_bf16 v[38:41], v[170:173], v[194:197], v[38:41]
	v_mfma_f32_16x16x32_bf16 v[34:37], v[178:181], v[194:197], v[34:37]
	v_mfma_f32_16x16x32_bf16 v[22:25], v[170:173], v[202:205], v[22:25]
	v_mfma_f32_16x16x32_bf16 v[18:21], v[178:181], v[202:205], v[18:21]
	v_mfma_f32_16x16x32_bf16 v[6:9], v[170:173], v[210:213], v[6:9]
	v_mfma_f32_16x16x32_bf16 v[2:5], v[178:181], v[210:213], v[2:5]
	v_mfma_f32_16x16x32_bf16 v[54:57], v[174:177], v[190:193], v[54:57]
	v_mfma_f32_16x16x32_bf16 v[50:53], v[182:185], v[190:193], v[50:53]
	v_mfma_f32_16x16x32_bf16 v[38:41], v[174:177], v[198:201], v[38:41]
	v_mfma_f32_16x16x32_bf16 v[34:37], v[182:185], v[198:201], v[34:37]
	v_mfma_f32_16x16x32_bf16 v[22:25], v[174:177], v[206:209], v[22:25]
	v_mfma_f32_16x16x32_bf16 v[18:21], v[182:185], v[206:209], v[18:21]
	v_mfma_f32_16x16x32_bf16 v[6:9], v[174:177], v[214:217], v[6:9]
	v_mfma_f32_16x16x32_bf16 v[2:5], v[182:185], v[214:217], v[2:5]
	s_setprio 0
	s_barrier
	s_add_i32 s54, s54, 2
	s_add_u32 s30, s30, 0x100
	s_addc_u32 s31, s31, 0
	s_cmp_gt_u32 s54, 13
	s_cbranch_scc0 .LBB0_1631
	s_add_u32 s30, s50, 0xffffff00
	s_addc_u32 s31, s51, -1
	s_andn2_b64 vcc, exec, s[6:7]
	s_cbranch_vccnz .LBB0_1634
	v_mov_b32_e32 v2, 0
	s_mov_b32 s10, s22
	s_mov_b32 s16, s24
	s_mov_b64 s[18:19], s[28:29]
	s_mov_b32 s41, s2
	v_mov_b32_e32 v3, v2
	v_mov_b32_e32 v4, v2
	v_mov_b32_e32 v5, v2
	v_mov_b32_e32 v6, v2
	v_mov_b32_e32 v7, v2
	v_mov_b32_e32 v8, v2
	v_mov_b32_e32 v9, v2
	v_mov_b32_e32 v18, v2
	v_mov_b32_e32 v19, v2
	v_mov_b32_e32 v20, v2
	v_mov_b32_e32 v21, v2
	v_mov_b32_e32 v22, v2
	v_mov_b32_e32 v23, v2
	v_mov_b32_e32 v24, v2
	v_mov_b32_e32 v25, v2
	v_mov_b32_e32 v34, v2
	v_mov_b32_e32 v35, v2
	v_mov_b32_e32 v36, v2
	v_mov_b32_e32 v37, v2
	v_mov_b32_e32 v38, v2
	v_mov_b32_e32 v39, v2
	v_mov_b32_e32 v40, v2
	v_mov_b32_e32 v41, v2
	v_mov_b32_e32 v50, v2
	v_mov_b32_e32 v51, v2
	v_mov_b32_e32 v52, v2
	v_mov_b32_e32 v53, v2
	v_mov_b32_e32 v54, v2
	v_mov_b32_e32 v55, v2
	v_mov_b32_e32 v56, v2
	v_mov_b32_e32 v57, v2
	v_mov_b32_e32 v10, v2
	v_mov_b32_e32 v11, v2
	v_mov_b32_e32 v12, v2
	v_mov_b32_e32 v13, v2
	v_mov_b32_e32 v14, v2
	v_mov_b32_e32 v15, v2
	v_mov_b32_e32 v16, v2
	v_mov_b32_e32 v17, v2
	v_mov_b32_e32 v26, v2
	v_mov_b32_e32 v27, v2
	v_mov_b32_e32 v28, v2
	v_mov_b32_e32 v29, v2
	v_mov_b32_e32 v30, v2
	v_mov_b32_e32 v31, v2
	v_mov_b32_e32 v32, v2
	v_mov_b32_e32 v33, v2
	v_mov_b32_e32 v42, v2
	v_mov_b32_e32 v43, v2
	v_mov_b32_e32 v44, v2
	v_mov_b32_e32 v45, v2
	v_mov_b32_e32 v46, v2
	v_mov_b32_e32 v47, v2
	v_mov_b32_e32 v48, v2
	v_mov_b32_e32 v49, v2
	v_mov_b32_e32 v58, v2
	v_mov_b32_e32 v59, v2
	v_mov_b32_e32 v60, v2
	v_mov_b32_e32 v61, v2
	v_mov_b32_e32 v62, v2
	v_mov_b32_e32 v63, v2
	v_mov_b32_e32 v64, v2
	v_mov_b32_e32 v65, v2
	v_mov_b32_e32 v66, v2
	v_mov_b32_e32 v67, v2
	v_mov_b32_e32 v68, v2
	v_mov_b32_e32 v69, v2
	v_mov_b32_e32 v70, v2
	v_mov_b32_e32 v71, v2
	v_mov_b32_e32 v72, v2
	v_mov_b32_e32 v73, v2
	v_mov_b32_e32 v82, v2
	v_mov_b32_e32 v83, v2
	v_mov_b32_e32 v84, v2
	v_mov_b32_e32 v85, v2
	v_mov_b32_e32 v86, v2
	v_mov_b32_e32 v87, v2
	v_mov_b32_e32 v88, v2
	v_mov_b32_e32 v89, v2
	v_mov_b32_e32 v98, v2
	v_mov_b32_e32 v99, v2
	v_mov_b32_e32 v100, v2
	v_mov_b32_e32 v101, v2
	v_mov_b32_e32 v102, v2
	v_mov_b32_e32 v103, v2
	v_mov_b32_e32 v104, v2
	v_mov_b32_e32 v105, v2
	v_mov_b32_e32 v114, v2
	v_mov_b32_e32 v115, v2
	v_mov_b32_e32 v116, v2
	v_mov_b32_e32 v117, v2
	v_mov_b32_e32 v118, v2
	v_mov_b32_e32 v119, v2
	v_mov_b32_e32 v120, v2
	v_mov_b32_e32 v121, v2
	v_mov_b32_e32 v74, v2
	v_mov_b32_e32 v75, v2
	v_mov_b32_e32 v76, v2
	v_mov_b32_e32 v77, v2
	v_mov_b32_e32 v78, v2
	v_mov_b32_e32 v79, v2
	v_mov_b32_e32 v80, v2
	v_mov_b32_e32 v81, v2
	v_mov_b32_e32 v90, v2
	v_mov_b32_e32 v91, v2
	v_mov_b32_e32 v92, v2
	v_mov_b32_e32 v93, v2
	v_mov_b32_e32 v94, v2
	v_mov_b32_e32 v95, v2
	v_mov_b32_e32 v96, v2
	v_mov_b32_e32 v97, v2
	v_mov_b32_e32 v106, v2
	v_mov_b32_e32 v107, v2
	v_mov_b32_e32 v108, v2
	v_mov_b32_e32 v109, v2
	v_mov_b32_e32 v110, v2
	v_mov_b32_e32 v111, v2
	v_mov_b32_e32 v112, v2
	v_mov_b32_e32 v113, v2
	v_mov_b32_e32 v122, v2
	v_mov_b32_e32 v123, v2
	v_mov_b32_e32 v124, v2
	v_mov_b32_e32 v125, v2
	v_mov_b32_e32 v126, v2
	v_mov_b32_e32 v127, v2
	v_mov_b32_e32 v128, v2
	v_mov_b32_e32 v129, v2
	s_andn2_b64 vcc, exec, s[4:5]
	s_cbranch_vccnz .LBB0_1635
	s_branch .LBB0_1636

.LBB0_1768:
	v_add_u32_e32 v146, s53, v217
	v_add_u32_e32 v162, s54, v217
	ds_read_b128 v[134:137], v146
	ds_read_b128 v[138:141], v146 offset:1024
	ds_read_b128 v[142:145], v146 offset:2048
	ds_read_b128 v[146:149], v146 offset:3072
	ds_read_b128 v[150:153], v162
	ds_read_b128 v[154:157], v162 offset:1024
	ds_read_b128 v[158:161], v162 offset:2048
	ds_read_b128 v[162:165], v162 offset:3072
	s_add_u32 s48, s28, 0xfffc0080
	s_addc_u32 s49, s29, -1
	s_and_b64 s[46:47], s[30:31], exec
	s_cselect_b32 s49, s23, s49
	s_cselect_b32 s48, s56, s48
	s_cselect_b32 s47, s57, s60
	s_cselect_b32 s46, s58, s59
	s_add_i32 m0, s40, 0xc000
	ds_read_b128 v[166:169], v220
	ds_read_b128 v[170:173], v220 offset:1024
	ds_read_b128 v[174:177], v220 offset:2048
	ds_read_b128 v[178:181], v220 offset:3072
	ds_read_b128 v[182:185], v220 offset:4096
	ds_read_b128 v[186:189], v220 offset:5120
	ds_read_b128 v[190:193], v220 offset:6144
	ds_read_b128 v[194:197], v220 offset:7168
	global_load_lds_dwordx4 v206, s[28:29]
	s_add_i32 m0, s40, 0xe000
	s_nop 0
	global_load_lds_dwordx4 v208, s[28:29]
	s_waitcnt vmcnt(8)
	s_waitcnt lgkmcnt(0)
	s_barrier
	s_setprio 1
	s_waitcnt lgkmcnt(0)
	v_mfma_f32_16x16x32_bf16 v[130:133], v[134:137], v[166:169], v[130:133]
	v_mfma_f32_16x16x32_bf16 v[122:125], v[142:145], v[166:169], v[122:125]
	v_mfma_f32_16x16x32_bf16 v[114:117], v[134:137], v[174:177], v[114:117]
	v_mfma_f32_16x16x32_bf16 v[106:109], v[142:145], v[174:177], v[106:109]
	v_mfma_f32_16x16x32_bf16 v[98:101], v[134:137], v[182:185], v[98:101]
	v_mfma_f32_16x16x32_bf16 v[90:93], v[142:145], v[182:185], v[90:93]
	v_mfma_f32_16x16x32_bf16 v[82:85], v[134:137], v[190:193], v[82:85]
	v_mfma_f32_16x16x32_bf16 v[74:77], v[142:145], v[190:193], v[74:77]
	v_mfma_f32_16x16x32_bf16 v[130:133], v[138:141], v[170:173], v[130:133]
	v_mfma_f32_16x16x32_bf16 v[122:125], v[146:149], v[170:173], v[122:125]
	v_mfma_f32_16x16x32_bf16 v[114:117], v[138:141], v[178:181], v[114:117]
	v_mfma_f32_16x16x32_bf16 v[106:109], v[146:149], v[178:181], v[106:109]
	v_mfma_f32_16x16x32_bf16 v[98:101], v[138:141], v[186:189], v[98:101]
	v_mfma_f32_16x16x32_bf16 v[90:93], v[146:149], v[186:189], v[90:93]
	v_mfma_f32_16x16x32_bf16 v[82:85], v[138:141], v[194:197], v[82:85]
	v_mfma_f32_16x16x32_bf16 v[74:77], v[146:149], v[194:197], v[74:77]
	s_setprio 0
	s_setprio 1
	v_mfma_f32_16x16x32_bf16 v[126:129], v[150:153], v[166:169], v[126:129]
	v_mfma_f32_16x16x32_bf16 v[118:121], v[158:161], v[166:169], v[118:121]
	v_mfma_f32_16x16x32_bf16 v[110:113], v[150:153], v[174:177], v[110:113]
	v_mfma_f32_16x16x32_bf16 v[102:105], v[158:161], v[174:177], v[102:105]
	v_mfma_f32_16x16x32_bf16 v[94:97], v[150:153], v[182:185], v[94:97]
	v_mfma_f32_16x16x32_bf16 v[86:89], v[158:161], v[182:185], v[86:89]
	v_mfma_f32_16x16x32_bf16 v[78:81], v[150:153], v[190:193], v[78:81]
	v_mfma_f32_16x16x32_bf16 v[70:73], v[158:161], v[190:193], v[70:73]
	v_mfma_f32_16x16x32_bf16 v[126:129], v[154:157], v[170:173], v[126:129]
	v_mfma_f32_16x16x32_bf16 v[118:121], v[162:165], v[170:173], v[118:121]
	v_mfma_f32_16x16x32_bf16 v[110:113], v[154:157], v[178:181], v[110:113]
	v_mfma_f32_16x16x32_bf16 v[102:105], v[162:165], v[178:181], v[102:105]
	v_mfma_f32_16x16x32_bf16 v[94:97], v[154:157], v[186:189], v[94:97]
	v_mfma_f32_16x16x32_bf16 v[86:89], v[162:165], v[186:189], v[86:89]
	v_mfma_f32_16x16x32_bf16 v[78:81], v[154:157], v[194:197], v[78:81]
	v_mfma_f32_16x16x32_bf16 v[70:73], v[162:165], v[194:197], v[70:73]
	s_setprio 0
	s_barrier
	s_add_i32 s62, s53, s12
	s_add_u32 s98, s46, s16
	s_addc_u32 s99, s47, s17
	s_mov_b32 m0, s62
	ds_read_b128 v[166:169], v220 offset:16384
	ds_read_b128 v[170:173], v220 offset:17408
	ds_read_b128 v[174:177], v220 offset:18432
	ds_read_b128 v[178:181], v220 offset:19456
	ds_read_b128 v[182:185], v220 offset:20480
	ds_read_b128 v[186:189], v220 offset:21504
	ds_read_b128 v[190:193], v220 offset:22528
	ds_read_b128 v[194:197], v220 offset:23552
	global_load_lds_dwordx4 v202, s[46:47]
	s_add_i32 m0, s62, 0x2000
	s_add_u32 s62, s46, 0x40000
	s_addc_u32 s63, s47, 0
	s_add_i32 s64, s54, s12
	global_load_lds_dwordx4 v198, s[46:47]
	s_mov_b32 m0, s64
	s_nop 0
	global_load_lds_dwordx4 v202, s[62:63]
	s_add_i32 m0, s64, 0x2000
	s_nop 0
	global_load_lds_dwordx4 v198, s[62:63]
	s_add_u32 s100, s48, s16
	s_addc_u32 s101, s49, s17
	s_mov_b32 m0, s40
	s_nop 0
	global_load_lds_dwordx4 v204, s[48:49]
	s_mov_b32 m0, s41
	s_nop 0
	global_load_lds_dwordx4 v200, s[48:49]
	s_waitcnt vmcnt(8)
	s_waitcnt lgkmcnt(0)
	s_barrier
	s_setprio 1
	s_waitcnt lgkmcnt(0)
	v_mfma_f32_16x16x32_bf16 v[66:69], v[134:137], v[166:169], v[66:69]
	v_mfma_f32_16x16x32_bf16 v[58:61], v[142:145], v[166:169], v[58:61]
	v_mfma_f32_16x16x32_bf16 v[50:53], v[134:137], v[174:177], v[50:53]
	v_mfma_f32_16x16x32_bf16 v[42:45], v[142:145], v[174:177], v[42:45]
	v_mfma_f32_16x16x32_bf16 v[34:37], v[134:137], v[182:185], v[34:37]
	v_mfma_f32_16x16x32_bf16 v[26:29], v[142:145], v[182:185], v[26:29]
	v_mfma_f32_16x16x32_bf16 v[18:21], v[134:137], v[190:193], v[18:21]
	v_mfma_f32_16x16x32_bf16 v[10:13], v[142:145], v[190:193], v[10:13]
	v_mfma_f32_16x16x32_bf16 v[66:69], v[138:141], v[170:173], v[66:69]
	v_mfma_f32_16x16x32_bf16 v[58:61], v[146:149], v[170:173], v[58:61]
	v_mfma_f32_16x16x32_bf16 v[50:53], v[138:141], v[178:181], v[50:53]
	v_mfma_f32_16x16x32_bf16 v[42:45], v[146:149], v[178:181], v[42:45]
	v_mfma_f32_16x16x32_bf16 v[34:37], v[138:141], v[186:189], v[34:37]
	v_mfma_f32_16x16x32_bf16 v[26:29], v[146:149], v[186:189], v[26:29]
	v_mfma_f32_16x16x32_bf16 v[18:21], v[138:141], v[194:197], v[18:21]
	v_mfma_f32_16x16x32_bf16 v[10:13], v[146:149], v[194:197], v[10:13]
	s_setprio 0
	s_setprio 1
	v_mfma_f32_16x16x32_bf16 v[62:65], v[150:153], v[166:169], v[62:65]
	v_mfma_f32_16x16x32_bf16 v[54:57], v[158:161], v[166:169], v[54:57]
	v_mfma_f32_16x16x32_bf16 v[46:49], v[150:153], v[174:177], v[46:49]
	v_mfma_f32_16x16x32_bf16 v[38:41], v[158:161], v[174:177], v[38:41]
	v_mfma_f32_16x16x32_bf16 v[30:33], v[150:153], v[182:185], v[30:33]
	v_mfma_f32_16x16x32_bf16 v[22:25], v[158:161], v[182:185], v[22:25]
	v_mfma_f32_16x16x32_bf16 v[14:17], v[150:153], v[190:193], v[14:17]
	v_mfma_f32_16x16x32_bf16 v[6:9], v[158:161], v[190:193], v[6:9]
	v_mfma_f32_16x16x32_bf16 v[62:65], v[154:157], v[170:173], v[62:65]
	v_mfma_f32_16x16x32_bf16 v[54:57], v[162:165], v[170:173], v[54:57]
	v_mfma_f32_16x16x32_bf16 v[46:49], v[154:157], v[178:181], v[46:49]
	v_mfma_f32_16x16x32_bf16 v[38:41], v[162:165], v[178:181], v[38:41]
	v_mfma_f32_16x16x32_bf16 v[30:33], v[154:157], v[186:189], v[30:33]
	v_mfma_f32_16x16x32_bf16 v[22:25], v[162:165], v[186:189], v[22:25]
	v_mfma_f32_16x16x32_bf16 v[14:17], v[154:157], v[194:197], v[14:17]
	v_mfma_f32_16x16x32_bf16 v[6:9], v[162:165], v[194:197], v[6:9]
	s_setprio 0
	s_barrier
	s_add_i32 s62, 0, 0x18000
	s_add_i32 s63, 0, 0x1c000
	v_add_u32_e32 v134, s62, v217
	v_add_u32_e32 v146, s63, v217
	ds_read_b128 v[150:153], v134
	ds_read_b128 v[154:157], v134 offset:1024
	ds_read_b128 v[158:161], v134 offset:2048
	ds_read_b128 v[162:165], v134 offset:3072
	ds_read_b128 v[134:137], v146
	ds_read_b128 v[138:141], v146 offset:1024
	ds_read_b128 v[142:145], v146 offset:2048
	ds_read_b128 v[146:149], v146 offset:3072
	s_add_u32 s48, s48, 0x40000
	s_addc_u32 s49, s49, 0
	s_mov_b32 m0, s42
	ds_read_b128 v[166:169], v220 offset:32768
	ds_read_b128 v[170:173], v220 offset:33792
	ds_read_b128 v[174:177], v220 offset:34816
	ds_read_b128 v[178:181], v220 offset:35840
	ds_read_b128 v[182:185], v220 offset:36864
	ds_read_b128 v[186:189], v220 offset:37888
	ds_read_b128 v[190:193], v220 offset:38912
	ds_read_b128 v[194:197], v220 offset:39936
	global_load_lds_dwordx4 v204, s[48:49]
	s_mov_b32 m0, s43
	s_nop 0
	global_load_lds_dwordx4 v200, s[48:49]
	s_waitcnt vmcnt(8)
	s_waitcnt lgkmcnt(0)
	s_barrier
	s_setprio 1
	s_waitcnt lgkmcnt(0)
	v_mfma_f32_16x16x32_bf16 v[130:133], v[150:153], v[166:169], v[130:133]
	v_mfma_f32_16x16x32_bf16 v[122:125], v[158:161], v[166:169], v[122:125]
	v_mfma_f32_16x16x32_bf16 v[114:117], v[150:153], v[174:177], v[114:117]
	v_mfma_f32_16x16x32_bf16 v[106:109], v[158:161], v[174:177], v[106:109]
	v_mfma_f32_16x16x32_bf16 v[98:101], v[150:153], v[182:185], v[98:101]
	v_mfma_f32_16x16x32_bf16 v[90:93], v[158:161], v[182:185], v[90:93]
	v_mfma_f32_16x16x32_bf16 v[82:85], v[150:153], v[190:193], v[82:85]
	v_mfma_f32_16x16x32_bf16 v[74:77], v[158:161], v[190:193], v[74:77]
	v_mfma_f32_16x16x32_bf16 v[130:133], v[154:157], v[170:173], v[130:133]
	v_mfma_f32_16x16x32_bf16 v[122:125], v[162:165], v[170:173], v[122:125]
	v_mfma_f32_16x16x32_bf16 v[114:117], v[154:157], v[178:181], v[114:117]
	v_mfma_f32_16x16x32_bf16 v[106:109], v[162:165], v[178:181], v[106:109]
	v_mfma_f32_16x16x32_bf16 v[98:101], v[154:157], v[186:189], v[98:101]
	v_mfma_f32_16x16x32_bf16 v[90:93], v[162:165], v[186:189], v[90:93]
	v_mfma_f32_16x16x32_bf16 v[82:85], v[154:157], v[194:197], v[82:85]
	v_mfma_f32_16x16x32_bf16 v[74:77], v[162:165], v[194:197], v[74:77]
	s_setprio 0
	s_setprio 1
	v_mfma_f32_16x16x32_bf16 v[126:129], v[134:137], v[166:169], v[126:129]
	v_mfma_f32_16x16x32_bf16 v[118:121], v[142:145], v[166:169], v[118:121]
	v_mfma_f32_16x16x32_bf16 v[110:113], v[134:137], v[174:177], v[110:113]
	v_mfma_f32_16x16x32_bf16 v[102:105], v[142:145], v[174:177], v[102:105]
	v_mfma_f32_16x16x32_bf16 v[94:97], v[134:137], v[182:185], v[94:97]
	v_mfma_f32_16x16x32_bf16 v[86:89], v[142:145], v[182:185], v[86:89]
	v_mfma_f32_16x16x32_bf16 v[78:81], v[134:137], v[190:193], v[78:81]
	v_mfma_f32_16x16x32_bf16 v[70:73], v[142:145], v[190:193], v[70:73]
	v_mfma_f32_16x16x32_bf16 v[126:129], v[138:141], v[170:173], v[126:129]
	v_mfma_f32_16x16x32_bf16 v[118:121], v[146:149], v[170:173], v[118:121]
	v_mfma_f32_16x16x32_bf16 v[110:113], v[138:141], v[178:181], v[110:113]
	v_mfma_f32_16x16x32_bf16 v[102:105], v[146:149], v[178:181], v[102:105]
	v_mfma_f32_16x16x32_bf16 v[94:97], v[138:141], v[186:189], v[94:97]
	v_mfma_f32_16x16x32_bf16 v[86:89], v[146:149], v[186:189], v[86:89]
	v_mfma_f32_16x16x32_bf16 v[78:81], v[138:141], v[194:197], v[78:81]
	v_mfma_f32_16x16x32_bf16 v[70:73], v[146:149], v[194:197], v[70:73]
	s_setprio 0
	s_barrier
	s_add_i32 s48, s62, s12
	s_mov_b32 m0, s48
	ds_read_b128 v[190:193], v220 offset:49152
	ds_read_b128 v[194:197], v220 offset:50176
	ds_read_b128 v[182:185], v220 offset:51200
	ds_read_b128 v[186:189], v220 offset:52224
	ds_read_b128 v[174:177], v220 offset:53248
	ds_read_b128 v[178:181], v220 offset:54272
	ds_read_b128 v[166:169], v220 offset:55296
	ds_read_b128 v[170:173], v220 offset:56320
	global_load_lds_dwordx4 v202, s[98:99]
	s_add_i32 m0, s48, 0x2000
	s_add_u32 s46, s46, 0x40080
	s_addc_u32 s47, s47, 0
	s_add_i32 s48, s63, s12
	global_load_lds_dwordx4 v198, s[98:99]
	s_mov_b32 m0, s48
	s_andn2_b64 vcc, exec, s[30:31]
	global_load_lds_dwordx4 v202, s[46:47]
	s_add_i32 m0, s48, 0x2000
	s_nop 0
	global_load_lds_dwordx4 v198, s[46:47]
	s_mov_b32 m0, s51
	s_nop 0
	global_load_lds_dwordx4 v204, s[100:101]
	s_mov_b32 m0, s52
	s_nop 0
	global_load_lds_dwordx4 v200, s[100:101]
	s_waitcnt vmcnt(8)
	s_cbranch_vccnz .LBB0_1765
	s_and_saveexec_b64 s[30:31], s[4:5]
	s_cbranch_execz .LBB0_1764
	v_mov_b32_e32 v222, v3
	v_mov_b32_e32 v223, v4
	v_mov_b32_e32 v224, v2
	v_mov_b32_e32 v225, v5
	v_pk_add_f32 v[222:223], v[222:223], v[224:225]
	s_nop 0
	v_add_f32_e32 v222, v222, v223
	v_fmamk_f32 v222, v222, 0x3a800000, v221
	ds_write_b32 v219, v222
	s_branch .LBB0_1764

.LBB0_1894:
	v_add_u32_e32 v153, s44, v151
	ds_read_b128 v[154:157], v153
	ds_read_b128 v[158:161], v153 offset:1024
	ds_read_b128 v[162:165], v153 offset:2048
	ds_read_b128 v[166:169], v153 offset:3072
	v_add_u32_e32 v153, s45, v151
	s_add_u32 s26, s18, s24
	ds_read_b128 v[170:173], v153
	ds_read_b128 v[174:177], v153 offset:1024
	ds_read_b128 v[178:181], v153 offset:2048
	ds_read_b128 v[182:185], v153 offset:3072
	s_addc_u32 s27, s19, s25
	s_add_u32 s26, s26, 0x100
	s_addc_u32 s27, s27, 0
	s_add_u32 s51, s48, s24
	s_addc_u32 s52, s49, s25
	s_cmpk_eq_i32 s24, 0x1500
	s_cselect_b32 s29, s23, s27
	s_cselect_b32 s28, s22, s26
	s_cselect_b32 s27, s9, s52
	s_cselect_b32 s26, s8, s51
	v_lshl_add_u64 v[218:219], v[146:147], 0, s[24:25]
	s_add_i32 m0, s33, 0xc000
	ds_read_b128 v[186:189], v152
	ds_read_b128 v[190:193], v152 offset:1024
	ds_read_b128 v[194:197], v152 offset:2048
	ds_read_b128 v[198:201], v152 offset:3072
	ds_read_b128 v[202:205], v152 offset:4096
	ds_read_b128 v[206:209], v152 offset:5120
	ds_read_b128 v[210:213], v152 offset:6144
	ds_read_b128 v[214:217], v152 offset:7168
	global_load_lds_dwordx4 v[218:219], off
	v_lshl_add_u64 v[218:219], v[148:149], 0, s[24:25]
	s_add_i32 m0, s33, 0xe000
	s_nop 0
	global_load_lds_dwordx4 v[218:219], off
	s_waitcnt vmcnt(8)
	s_waitcnt lgkmcnt(0)
	s_barrier
	s_setprio 1
	s_waitcnt lgkmcnt(0)
	v_mfma_f32_16x16x32_bf16 v[126:129], v[154:157], v[186:189], v[126:129]
	v_mfma_f32_16x16x32_bf16 v[122:125], v[162:165], v[186:189], v[122:125]
	v_mfma_f32_16x16x32_bf16 v[110:113], v[154:157], v[194:197], v[110:113]
	v_mfma_f32_16x16x32_bf16 v[106:109], v[162:165], v[194:197], v[106:109]
	v_mfma_f32_16x16x32_bf16 v[94:97], v[154:157], v[202:205], v[94:97]
	v_mfma_f32_16x16x32_bf16 v[90:93], v[162:165], v[202:205], v[90:93]
	v_mfma_f32_16x16x32_bf16 v[78:81], v[154:157], v[210:213], v[78:81]
	v_mfma_f32_16x16x32_bf16 v[74:77], v[162:165], v[210:213], v[74:77]
	v_mfma_f32_16x16x32_bf16 v[126:129], v[158:161], v[190:193], v[126:129]
	v_mfma_f32_16x16x32_bf16 v[122:125], v[166:169], v[190:193], v[122:125]
	v_mfma_f32_16x16x32_bf16 v[110:113], v[158:161], v[198:201], v[110:113]
	v_mfma_f32_16x16x32_bf16 v[106:109], v[166:169], v[198:201], v[106:109]
	v_mfma_f32_16x16x32_bf16 v[94:97], v[158:161], v[206:209], v[94:97]
	v_mfma_f32_16x16x32_bf16 v[90:93], v[166:169], v[206:209], v[90:93]
	v_mfma_f32_16x16x32_bf16 v[78:81], v[158:161], v[214:217], v[78:81]
	v_mfma_f32_16x16x32_bf16 v[74:77], v[166:169], v[214:217], v[74:77]
	s_setprio 0
	s_setprio 1
	v_mfma_f32_16x16x32_bf16 v[118:121], v[170:173], v[186:189], v[118:121]
	v_mfma_f32_16x16x32_bf16 v[114:117], v[178:181], v[186:189], v[114:117]
	v_mfma_f32_16x16x32_bf16 v[102:105], v[170:173], v[194:197], v[102:105]
	v_mfma_f32_16x16x32_bf16 v[98:101], v[178:181], v[194:197], v[98:101]
	v_mfma_f32_16x16x32_bf16 v[86:89], v[170:173], v[202:205], v[86:89]
	v_mfma_f32_16x16x32_bf16 v[82:85], v[178:181], v[202:205], v[82:85]
	v_mfma_f32_16x16x32_bf16 v[70:73], v[170:173], v[210:213], v[70:73]
	v_mfma_f32_16x16x32_bf16 v[66:69], v[178:181], v[210:213], v[66:69]
	v_mfma_f32_16x16x32_bf16 v[118:121], v[174:177], v[190:193], v[118:121]
	v_mfma_f32_16x16x32_bf16 v[114:117], v[182:185], v[190:193], v[114:117]
	v_mfma_f32_16x16x32_bf16 v[102:105], v[174:177], v[198:201], v[102:105]
	v_mfma_f32_16x16x32_bf16 v[98:101], v[182:185], v[198:201], v[98:101]
	v_mfma_f32_16x16x32_bf16 v[86:89], v[174:177], v[206:209], v[86:89]
	v_mfma_f32_16x16x32_bf16 v[82:85], v[182:185], v[206:209], v[82:85]
	v_mfma_f32_16x16x32_bf16 v[70:73], v[174:177], v[214:217], v[70:73]
	v_mfma_f32_16x16x32_bf16 v[66:69], v[182:185], v[214:217], v[66:69]
	s_setprio 0
	s_barrier
	s_add_i32 s51, s44, s13
	s_add_u32 s98, s26, s20
	s_addc_u32 s99, s27, s21
	s_mov_b32 m0, s51
	ds_read_b128 v[186:189], v152 offset:16384
	ds_read_b128 v[190:193], v152 offset:17408
	ds_read_b128 v[194:197], v152 offset:18432
	ds_read_b128 v[198:201], v152 offset:19456
	ds_read_b128 v[202:205], v152 offset:20480
	ds_read_b128 v[206:209], v152 offset:21504
	ds_read_b128 v[210:213], v152 offset:22528
	ds_read_b128 v[214:217], v152 offset:23552
	global_load_lds_dwordx4 v132, s[26:27]
	s_add_i32 m0, s51, 0x2000
	s_add_u32 s52, s26, 0xb0000
	s_addc_u32 s53, s27, 0
	s_add_i32 s51, s45, s13
	global_load_lds_dwordx4 v136, s[26:27]
	s_mov_b32 m0, s51
	s_nop 0
	global_load_lds_dwordx4 v132, s[52:53]
	s_add_i32 m0, s51, 0x2000
	s_nop 0
	global_load_lds_dwordx4 v136, s[52:53]
	s_add_u32 s100, s28, s20
	s_addc_u32 s101, s29, s21
	s_mov_b32 m0, s33
	s_nop 0
	global_load_lds_dwordx4 v130, s[28:29]
	s_mov_b32 m0, s14
	s_nop 0
	global_load_lds_dwordx4 v134, s[28:29]
	s_waitcnt vmcnt(8)
	s_waitcnt lgkmcnt(0)
	s_barrier
	s_setprio 1
	s_waitcnt lgkmcnt(0)
	v_mfma_f32_16x16x32_bf16 v[62:65], v[154:157], v[186:189], v[62:65]
	v_mfma_f32_16x16x32_bf16 v[58:61], v[162:165], v[186:189], v[58:61]
	v_mfma_f32_16x16x32_bf16 v[46:49], v[154:157], v[194:197], v[46:49]
	v_mfma_f32_16x16x32_bf16 v[42:45], v[162:165], v[194:197], v[42:45]
	v_mfma_f32_16x16x32_bf16 v[30:33], v[154:157], v[202:205], v[30:33]
	v_mfma_f32_16x16x32_bf16 v[26:29], v[162:165], v[202:205], v[26:29]
	v_mfma_f32_16x16x32_bf16 v[14:17], v[154:157], v[210:213], v[14:17]
	v_mfma_f32_16x16x32_bf16 v[10:13], v[162:165], v[210:213], v[10:13]
	v_mfma_f32_16x16x32_bf16 v[62:65], v[158:161], v[190:193], v[62:65]
	v_mfma_f32_16x16x32_bf16 v[58:61], v[166:169], v[190:193], v[58:61]
	v_mfma_f32_16x16x32_bf16 v[46:49], v[158:161], v[198:201], v[46:49]
	v_mfma_f32_16x16x32_bf16 v[42:45], v[166:169], v[198:201], v[42:45]
	v_mfma_f32_16x16x32_bf16 v[30:33], v[158:161], v[206:209], v[30:33]
	v_mfma_f32_16x16x32_bf16 v[26:29], v[166:169], v[206:209], v[26:29]
	v_mfma_f32_16x16x32_bf16 v[14:17], v[158:161], v[214:217], v[14:17]
	v_mfma_f32_16x16x32_bf16 v[10:13], v[166:169], v[214:217], v[10:13]
	s_setprio 0
	s_setprio 1
	v_mfma_f32_16x16x32_bf16 v[54:57], v[170:173], v[186:189], v[54:57]
	v_mfma_f32_16x16x32_bf16 v[50:53], v[178:181], v[186:189], v[50:53]
	v_mfma_f32_16x16x32_bf16 v[38:41], v[170:173], v[194:197], v[38:41]
	v_mfma_f32_16x16x32_bf16 v[34:37], v[178:181], v[194:197], v[34:37]
	v_mfma_f32_16x16x32_bf16 v[22:25], v[170:173], v[202:205], v[22:25]
	v_mfma_f32_16x16x32_bf16 v[18:21], v[178:181], v[202:205], v[18:21]
	v_mfma_f32_16x16x32_bf16 v[6:9], v[170:173], v[210:213], v[6:9]
	v_mfma_f32_16x16x32_bf16 v[2:5], v[178:181], v[210:213], v[2:5]
	v_mfma_f32_16x16x32_bf16 v[54:57], v[174:177], v[190:193], v[54:57]
	v_mfma_f32_16x16x32_bf16 v[50:53], v[182:185], v[190:193], v[50:53]
	v_mfma_f32_16x16x32_bf16 v[38:41], v[174:177], v[198:201], v[38:41]
	v_mfma_f32_16x16x32_bf16 v[34:37], v[182:185], v[198:201], v[34:37]
	v_mfma_f32_16x16x32_bf16 v[22:25], v[174:177], v[206:209], v[22:25]
	v_mfma_f32_16x16x32_bf16 v[18:21], v[182:185], v[206:209], v[18:21]
	v_mfma_f32_16x16x32_bf16 v[6:9], v[174:177], v[214:217], v[6:9]
	v_mfma_f32_16x16x32_bf16 v[2:5], v[182:185], v[214:217], v[2:5]
	s_setprio 0
	s_barrier
	s_add_i32 s51, 0, 0x18000
	v_add_u32_e32 v153, s51, v151
	s_add_i32 s52, 0, 0x1c000
	ds_read_b128 v[154:157], v153
	ds_read_b128 v[158:161], v153 offset:1024
	ds_read_b128 v[162:165], v153 offset:2048
	ds_read_b128 v[166:169], v153 offset:3072
	v_add_u32_e32 v153, s52, v151
	ds_read_b128 v[170:173], v153
	ds_read_b128 v[174:177], v153 offset:1024
	ds_read_b128 v[178:181], v153 offset:2048
	ds_read_b128 v[182:185], v153 offset:3072
	s_add_u32 s28, s28, 0xb0000
	s_addc_u32 s29, s29, 0
	s_mov_b32 m0, s15
	ds_read_b128 v[186:189], v152 offset:32768
	ds_read_b128 v[190:193], v152 offset:33792
	ds_read_b128 v[194:197], v152 offset:34816
	ds_read_b128 v[198:201], v152 offset:35840
	ds_read_b128 v[202:205], v152 offset:36864
	ds_read_b128 v[206:209], v152 offset:37888
	ds_read_b128 v[210:213], v152 offset:38912
	ds_read_b128 v[214:217], v152 offset:39936
	global_load_lds_dwordx4 v130, s[28:29]
	s_mov_b32 m0, s40
	s_nop 0
	global_load_lds_dwordx4 v134, s[28:29]
	s_waitcnt vmcnt(8)
	s_waitcnt lgkmcnt(0)
	s_barrier
	s_setprio 1
	s_waitcnt lgkmcnt(0)
	v_mfma_f32_16x16x32_bf16 v[126:129], v[154:157], v[186:189], v[126:129]
	v_mfma_f32_16x16x32_bf16 v[122:125], v[162:165], v[186:189], v[122:125]
	v_mfma_f32_16x16x32_bf16 v[110:113], v[154:157], v[194:197], v[110:113]
	v_mfma_f32_16x16x32_bf16 v[106:109], v[162:165], v[194:197], v[106:109]
	v_mfma_f32_16x16x32_bf16 v[94:97], v[154:157], v[202:205], v[94:97]
	v_mfma_f32_16x16x32_bf16 v[90:93], v[162:165], v[202:205], v[90:93]
	v_mfma_f32_16x16x32_bf16 v[78:81], v[154:157], v[210:213], v[78:81]
	v_mfma_f32_16x16x32_bf16 v[74:77], v[162:165], v[210:213], v[74:77]
	v_mfma_f32_16x16x32_bf16 v[126:129], v[158:161], v[190:193], v[126:129]
	v_mfma_f32_16x16x32_bf16 v[122:125], v[166:169], v[190:193], v[122:125]
	v_mfma_f32_16x16x32_bf16 v[110:113], v[158:161], v[198:201], v[110:113]
	v_mfma_f32_16x16x32_bf16 v[106:109], v[166:169], v[198:201], v[106:109]
	v_mfma_f32_16x16x32_bf16 v[94:97], v[158:161], v[206:209], v[94:97]
	v_mfma_f32_16x16x32_bf16 v[90:93], v[166:169], v[206:209], v[90:93]
	v_mfma_f32_16x16x32_bf16 v[78:81], v[158:161], v[214:217], v[78:81]
	v_mfma_f32_16x16x32_bf16 v[74:77], v[166:169], v[214:217], v[74:77]
	s_setprio 0
	s_setprio 1
	v_mfma_f32_16x16x32_bf16 v[118:121], v[170:173], v[186:189], v[118:121]
	v_mfma_f32_16x16x32_bf16 v[114:117], v[178:181], v[186:189], v[114:117]
	v_mfma_f32_16x16x32_bf16 v[102:105], v[170:173], v[194:197], v[102:105]
	v_mfma_f32_16x16x32_bf16 v[98:101], v[178:181], v[194:197], v[98:101]
	v_mfma_f32_16x16x32_bf16 v[86:89], v[170:173], v[202:205], v[86:89]
	v_mfma_f32_16x16x32_bf16 v[82:85], v[178:181], v[202:205], v[82:85]
	v_mfma_f32_16x16x32_bf16 v[70:73], v[170:173], v[210:213], v[70:73]
	v_mfma_f32_16x16x32_bf16 v[66:69], v[178:181], v[210:213], v[66:69]
	v_mfma_f32_16x16x32_bf16 v[118:121], v[174:177], v[190:193], v[118:121]
	v_mfma_f32_16x16x32_bf16 v[114:117], v[182:185], v[190:193], v[114:117]
	v_mfma_f32_16x16x32_bf16 v[102:105], v[174:177], v[198:201], v[102:105]
	v_mfma_f32_16x16x32_bf16 v[98:101], v[182:185], v[198:201], v[98:101]
	v_mfma_f32_16x16x32_bf16 v[86:89], v[174:177], v[206:209], v[86:89]
	v_mfma_f32_16x16x32_bf16 v[82:85], v[182:185], v[206:209], v[82:85]
	v_mfma_f32_16x16x32_bf16 v[70:73], v[174:177], v[214:217], v[70:73]
	v_mfma_f32_16x16x32_bf16 v[66:69], v[182:185], v[214:217], v[66:69]
	s_setprio 0
	s_barrier
	s_add_i32 s28, s51, s13
	s_mov_b32 m0, s28
	ds_read_b128 v[186:189], v152 offset:49152
	ds_read_b128 v[190:193], v152 offset:50176
	ds_read_b128 v[194:197], v152 offset:51200
	ds_read_b128 v[198:201], v152 offset:52224
	ds_read_b128 v[202:205], v152 offset:53248
	ds_read_b128 v[206:209], v152 offset:54272
	ds_read_b128 v[210:213], v152 offset:55296
	ds_read_b128 v[214:217], v152 offset:56320
	global_load_lds_dwordx4 v132, s[98:99]
	s_add_i32 m0, s28, 0x2000
	s_add_u32 s26, s26, 0xb0080
	s_addc_u32 s27, s27, 0
	s_add_i32 s28, s52, s13
	global_load_lds_dwordx4 v136, s[98:99]
	s_mov_b32 m0, s28
	s_nop 0
	global_load_lds_dwordx4 v132, s[26:27]
	s_add_i32 m0, s28, 0x2000
	s_nop 0
	global_load_lds_dwordx4 v136, s[26:27]
	s_mov_b32 m0, s42
	s_nop 0
	global_load_lds_dwordx4 v130, s[100:101]
	s_mov_b32 m0, s43
	s_nop 0
	global_load_lds_dwordx4 v134, s[100:101]
	s_waitcnt vmcnt(8)
	s_waitcnt lgkmcnt(0)
	s_barrier
	s_setprio 1
	s_waitcnt lgkmcnt(0)
	v_mfma_f32_16x16x32_bf16 v[62:65], v[154:157], v[186:189], v[62:65]
	v_mfma_f32_16x16x32_bf16 v[58:61], v[162:165], v[186:189], v[58:61]
	v_mfma_f32_16x16x32_bf16 v[46:49], v[154:157], v[194:197], v[46:49]
	v_mfma_f32_16x16x32_bf16 v[42:45], v[162:165], v[194:197], v[42:45]
	v_mfma_f32_16x16x32_bf16 v[30:33], v[154:157], v[202:205], v[30:33]
	v_mfma_f32_16x16x32_bf16 v[26:29], v[162:165], v[202:205], v[26:29]
	v_mfma_f32_16x16x32_bf16 v[14:17], v[154:157], v[210:213], v[14:17]
	v_mfma_f32_16x16x32_bf16 v[10:13], v[162:165], v[210:213], v[10:13]
	v_mfma_f32_16x16x32_bf16 v[62:65], v[158:161], v[190:193], v[62:65]
	v_mfma_f32_16x16x32_bf16 v[58:61], v[166:169], v[190:193], v[58:61]
	v_mfma_f32_16x16x32_bf16 v[46:49], v[158:161], v[198:201], v[46:49]
	v_mfma_f32_16x16x32_bf16 v[42:45], v[166:169], v[198:201], v[42:45]
	v_mfma_f32_16x16x32_bf16 v[30:33], v[158:161], v[206:209], v[30:33]
	v_mfma_f32_16x16x32_bf16 v[26:29], v[166:169], v[206:209], v[26:29]
	v_mfma_f32_16x16x32_bf16 v[14:17], v[158:161], v[214:217], v[14:17]
	v_mfma_f32_16x16x32_bf16 v[10:13], v[166:169], v[214:217], v[10:13]
	s_setprio 0
	s_setprio 1
	v_mfma_f32_16x16x32_bf16 v[54:57], v[170:173], v[186:189], v[54:57]
	v_mfma_f32_16x16x32_bf16 v[50:53], v[178:181], v[186:189], v[50:53]
	v_mfma_f32_16x16x32_bf16 v[38:41], v[170:173], v[194:197], v[38:41]
	v_mfma_f32_16x16x32_bf16 v[34:37], v[178:181], v[194:197], v[34:37]
	v_mfma_f32_16x16x32_bf16 v[22:25], v[170:173], v[202:205], v[22:25]
	v_mfma_f32_16x16x32_bf16 v[18:21], v[178:181], v[202:205], v[18:21]
	v_mfma_f32_16x16x32_bf16 v[6:9], v[170:173], v[210:213], v[6:9]
	v_mfma_f32_16x16x32_bf16 v[2:5], v[178:181], v[210:213], v[2:5]
	v_mfma_f32_16x16x32_bf16 v[54:57], v[174:177], v[190:193], v[54:57]
	v_mfma_f32_16x16x32_bf16 v[50:53], v[182:185], v[190:193], v[50:53]
	v_mfma_f32_16x16x32_bf16 v[38:41], v[174:177], v[198:201], v[38:41]
	v_mfma_f32_16x16x32_bf16 v[34:37], v[182:185], v[198:201], v[34:37]
	v_mfma_f32_16x16x32_bf16 v[22:25], v[174:177], v[206:209], v[22:25]
	v_mfma_f32_16x16x32_bf16 v[18:21], v[182:185], v[206:209], v[18:21]
	v_mfma_f32_16x16x32_bf16 v[6:9], v[174:177], v[214:217], v[6:9]
	v_mfma_f32_16x16x32_bf16 v[2:5], v[182:185], v[214:217], v[2:5]
	s_setprio 0
	s_barrier
	s_add_i32 s50, s50, 2
	s_add_u32 s24, s24, 0x100
	s_addc_u32 s25, s25, 0
	s_cmp_gt_u32 s50, 41
	s_cbranch_scc0 .LBB0_1894
	s_add_u32 s24, s48, 0xffffff00
	s_addc_u32 s25, s49, -1
	s_and_b64 vcc, exec, s[6:7]
	s_cbranch_vccnz .LBB0_1897
	v_mov_b32_e32 v2, 0
	s_mov_b32 s16, s46
	s_mov_b32 s31, s47
	s_mov_b64 s[18:19], s[22:23]
	s_mov_b32 s41, s2
	v_mov_b32_e32 v3, v2
	v_mov_b32_e32 v4, v2
	v_mov_b32_e32 v5, v2
	v_mov_b32_e32 v6, v2
	v_mov_b32_e32 v7, v2
	v_mov_b32_e32 v8, v2
	v_mov_b32_e32 v9, v2
	v_mov_b32_e32 v18, v2
	v_mov_b32_e32 v19, v2
	v_mov_b32_e32 v20, v2
	v_mov_b32_e32 v21, v2
	v_mov_b32_e32 v22, v2
	v_mov_b32_e32 v23, v2
	v_mov_b32_e32 v24, v2
	v_mov_b32_e32 v25, v2
	v_mov_b32_e32 v34, v2
	v_mov_b32_e32 v35, v2
	v_mov_b32_e32 v36, v2
	v_mov_b32_e32 v37, v2
	v_mov_b32_e32 v38, v2
	v_mov_b32_e32 v39, v2
	v_mov_b32_e32 v40, v2
	v_mov_b32_e32 v41, v2
	v_mov_b32_e32 v50, v2
	v_mov_b32_e32 v51, v2
	v_mov_b32_e32 v52, v2
	v_mov_b32_e32 v53, v2
	v_mov_b32_e32 v54, v2
	v_mov_b32_e32 v55, v2
	v_mov_b32_e32 v56, v2
	v_mov_b32_e32 v57, v2
	v_mov_b32_e32 v10, v2
	v_mov_b32_e32 v11, v2
	v_mov_b32_e32 v12, v2
	v_mov_b32_e32 v13, v2
	v_mov_b32_e32 v14, v2
	v_mov_b32_e32 v15, v2
	v_mov_b32_e32 v16, v2
	v_mov_b32_e32 v17, v2
	v_mov_b32_e32 v26, v2
	v_mov_b32_e32 v27, v2
	v_mov_b32_e32 v28, v2
	v_mov_b32_e32 v29, v2
	v_mov_b32_e32 v30, v2
	v_mov_b32_e32 v31, v2
	v_mov_b32_e32 v32, v2
	v_mov_b32_e32 v33, v2
	v_mov_b32_e32 v42, v2
	v_mov_b32_e32 v43, v2
	v_mov_b32_e32 v44, v2
	v_mov_b32_e32 v45, v2
	v_mov_b32_e32 v46, v2
	v_mov_b32_e32 v47, v2
	v_mov_b32_e32 v48, v2
	v_mov_b32_e32 v49, v2
	v_mov_b32_e32 v58, v2
	v_mov_b32_e32 v59, v2
	v_mov_b32_e32 v60, v2
	v_mov_b32_e32 v61, v2
	v_mov_b32_e32 v62, v2
	v_mov_b32_e32 v63, v2
	v_mov_b32_e32 v64, v2
	v_mov_b32_e32 v65, v2
	v_mov_b32_e32 v66, v2
	v_mov_b32_e32 v67, v2
	v_mov_b32_e32 v68, v2
	v_mov_b32_e32 v69, v2
	v_mov_b32_e32 v70, v2
	v_mov_b32_e32 v71, v2
	v_mov_b32_e32 v72, v2
	v_mov_b32_e32 v73, v2
	v_mov_b32_e32 v82, v2
	v_mov_b32_e32 v83, v2
	v_mov_b32_e32 v84, v2
	v_mov_b32_e32 v85, v2
	v_mov_b32_e32 v86, v2
	v_mov_b32_e32 v87, v2
	v_mov_b32_e32 v88, v2
	v_mov_b32_e32 v89, v2
	v_mov_b32_e32 v98, v2
	v_mov_b32_e32 v99, v2
	v_mov_b32_e32 v100, v2
	v_mov_b32_e32 v101, v2
	v_mov_b32_e32 v102, v2
	v_mov_b32_e32 v103, v2
	v_mov_b32_e32 v104, v2
	v_mov_b32_e32 v105, v2
	v_mov_b32_e32 v114, v2
	v_mov_b32_e32 v115, v2
	v_mov_b32_e32 v116, v2
	v_mov_b32_e32 v117, v2
	v_mov_b32_e32 v118, v2
	v_mov_b32_e32 v119, v2
	v_mov_b32_e32 v120, v2
	v_mov_b32_e32 v121, v2
	v_mov_b32_e32 v74, v2
	v_mov_b32_e32 v75, v2
	v_mov_b32_e32 v76, v2
	v_mov_b32_e32 v77, v2
	v_mov_b32_e32 v78, v2
	v_mov_b32_e32 v79, v2
	v_mov_b32_e32 v80, v2
	v_mov_b32_e32 v81, v2
	v_mov_b32_e32 v90, v2
	v_mov_b32_e32 v91, v2
	v_mov_b32_e32 v92, v2
	v_mov_b32_e32 v93, v2
	v_mov_b32_e32 v94, v2
	v_mov_b32_e32 v95, v2
	v_mov_b32_e32 v96, v2
	v_mov_b32_e32 v97, v2
	v_mov_b32_e32 v106, v2
	v_mov_b32_e32 v107, v2
	v_mov_b32_e32 v108, v2
	v_mov_b32_e32 v109, v2
	v_mov_b32_e32 v110, v2
	v_mov_b32_e32 v111, v2
	v_mov_b32_e32 v112, v2
	v_mov_b32_e32 v113, v2
	v_mov_b32_e32 v122, v2
	v_mov_b32_e32 v123, v2
	v_mov_b32_e32 v124, v2
	v_mov_b32_e32 v125, v2
	v_mov_b32_e32 v126, v2
	v_mov_b32_e32 v127, v2
	v_mov_b32_e32 v128, v2
	v_mov_b32_e32 v129, v2
	s_andn2_b64 vcc, exec, s[4:5]
	s_cbranch_vccnz .LBB0_1898
	s_branch .LBB0_1899

.LBB0_2031:
	ds_read_b128 v[36:39], v203
	ds_read_b128 v[44:47], v203 offset:1024
	ds_read_b128 v[48:51], v203 offset:2048
	ds_read_b128 v[56:59], v203 offset:3072
	ds_read_b128 v[144:147], v207
	ds_read_b128 v[148:151], v207 offset:1024
	ds_read_b128 v[152:155], v207 offset:2048
	ds_read_b128 v[156:159], v207 offset:3072
	s_add_u32 s34, s30, 0xfffc0080
	s_addc_u32 s35, s31, -1
	s_cmp_eq_u32 s63, 12
	s_cselect_b32 s39, s14, s35
	s_cselect_b32 s38, s15, s34
	s_cselect_b32 s35, s21, s62
	s_cselect_b32 s34, s23, s61
	s_add_i32 m0, s29, 0xc000
	ds_read_b128 v[172:175], v209
	ds_read_b128 v[176:179], v209 offset:1024
	ds_read_b128 v[180:183], v209 offset:2048
	ds_read_b128 v[184:187], v209 offset:3072
	ds_read_b128 v[188:191], v209 offset:4096
	ds_read_b128 v[192:195], v209 offset:5120
	ds_read_b128 v[196:199], v209 offset:6144
	ds_read_b128 v[214:217], v209 offset:7168
	global_load_lds_dwordx4 v168, s[30:31]
	s_add_i32 m0, s29, 0xe000
	s_nop 0
	global_load_lds_dwordx4 v170, s[30:31]
	s_waitcnt vmcnt(8)
	s_waitcnt lgkmcnt(0)
	s_barrier
	s_setprio 1
	s_waitcnt lgkmcnt(0)
	v_mfma_f32_16x16x32_bf16 v[140:143], v[36:39], v[172:175], v[140:143]
	v_mfma_f32_16x16x32_bf16 v[136:139], v[48:51], v[172:175], v[136:139]
	v_mfma_f32_16x16x32_bf16 v[124:127], v[36:39], v[180:183], v[124:127]
	v_mfma_f32_16x16x32_bf16 v[120:123], v[48:51], v[180:183], v[120:123]
	v_mfma_f32_16x16x32_bf16 v[108:111], v[36:39], v[188:191], v[108:111]
	v_mfma_f32_16x16x32_bf16 v[104:107], v[48:51], v[188:191], v[104:107]
	v_mfma_f32_16x16x32_bf16 v[92:95], v[36:39], v[196:199], v[92:95]
	v_mfma_f32_16x16x32_bf16 v[88:91], v[48:51], v[196:199], v[88:91]
	v_mfma_f32_16x16x32_bf16 v[140:143], v[44:47], v[176:179], v[140:143]
	v_mfma_f32_16x16x32_bf16 v[136:139], v[56:59], v[176:179], v[136:139]
	v_mfma_f32_16x16x32_bf16 v[124:127], v[44:47], v[184:187], v[124:127]
	v_mfma_f32_16x16x32_bf16 v[120:123], v[56:59], v[184:187], v[120:123]
	v_mfma_f32_16x16x32_bf16 v[108:111], v[44:47], v[192:195], v[108:111]
	v_mfma_f32_16x16x32_bf16 v[104:107], v[56:59], v[192:195], v[104:107]
	v_mfma_f32_16x16x32_bf16 v[92:95], v[44:47], v[214:217], v[92:95]
	v_mfma_f32_16x16x32_bf16 v[88:91], v[56:59], v[214:217], v[88:91]
	s_setprio 0
	s_setprio 1
	v_mfma_f32_16x16x32_bf16 v[132:135], v[144:147], v[172:175], v[132:135]
	v_mfma_f32_16x16x32_bf16 v[128:131], v[152:155], v[172:175], v[128:131]
	v_mfma_f32_16x16x32_bf16 v[116:119], v[144:147], v[180:183], v[116:119]
	v_mfma_f32_16x16x32_bf16 v[112:115], v[152:155], v[180:183], v[112:115]
	v_mfma_f32_16x16x32_bf16 v[100:103], v[144:147], v[188:191], v[100:103]
	v_mfma_f32_16x16x32_bf16 v[96:99], v[152:155], v[188:191], v[96:99]
	v_mfma_f32_16x16x32_bf16 v[84:87], v[144:147], v[196:199], v[84:87]
	v_mfma_f32_16x16x32_bf16 v[80:83], v[152:155], v[196:199], v[80:83]
	v_mfma_f32_16x16x32_bf16 v[132:135], v[148:151], v[176:179], v[132:135]
	v_mfma_f32_16x16x32_bf16 v[128:131], v[156:159], v[176:179], v[128:131]
	v_mfma_f32_16x16x32_bf16 v[116:119], v[148:151], v[184:187], v[116:119]
	v_mfma_f32_16x16x32_bf16 v[112:115], v[156:159], v[184:187], v[112:115]
	v_mfma_f32_16x16x32_bf16 v[100:103], v[148:151], v[192:195], v[100:103]
	v_mfma_f32_16x16x32_bf16 v[96:99], v[156:159], v[192:195], v[96:99]
	v_mfma_f32_16x16x32_bf16 v[84:87], v[148:151], v[214:217], v[84:87]
	v_mfma_f32_16x16x32_bf16 v[80:83], v[156:159], v[214:217], v[80:83]
	s_setprio 0
	s_barrier
	s_add_i32 s64, s55, s42
	s_add_u32 s98, s34, s16
	s_addc_u32 s99, s35, s17
	s_mov_b32 m0, s64
	ds_read_b128 v[172:175], v209 offset:16384
	ds_read_b128 v[176:179], v209 offset:17408
	ds_read_b128 v[180:183], v209 offset:18432
	ds_read_b128 v[184:187], v209 offset:19456
	ds_read_b128 v[188:191], v209 offset:20480
	ds_read_b128 v[192:195], v209 offset:21504
	ds_read_b128 v[196:199], v209 offset:22528
	ds_read_b128 v[214:217], v209 offset:23552
	global_load_lds_dwordx4 v162, s[34:35]
	s_add_i32 m0, s64, 0x2000
	s_add_u32 s64, s34, 0x40000
	s_addc_u32 s65, s35, 0
	s_add_i32 s66, s56, s42
	global_load_lds_dwordx4 v166, s[34:35]
	s_mov_b32 m0, s66
	s_nop 0
	global_load_lds_dwordx4 v162, s[64:65]
	s_add_i32 m0, s66, 0x2000
	s_nop 0
	global_load_lds_dwordx4 v166, s[64:65]
	s_add_u32 s100, s38, s16
	s_addc_u32 s101, s39, s17
	s_mov_b32 m0, s29
	s_nop 0
	global_load_lds_dwordx4 v160, s[38:39]
	s_mov_b32 m0, s43
	s_nop 0
	global_load_lds_dwordx4 v164, s[38:39]
	s_waitcnt vmcnt(8)
	s_waitcnt lgkmcnt(0)
	s_barrier
	s_setprio 1
	s_waitcnt lgkmcnt(0)
	v_mfma_f32_16x16x32_bf16 v[76:79], v[36:39], v[172:175], v[76:79]
	v_mfma_f32_16x16x32_bf16 v[72:75], v[48:51], v[172:175], v[72:75]
	v_mfma_f32_16x16x32_bf16 v[60:63], v[36:39], v[180:183], v[60:63]
	v_mfma_f32_16x16x32_bf16 v[52:55], v[48:51], v[180:183], v[52:55]
	v_mfma_f32_16x16x32_bf16 v[28:31], v[36:39], v[188:191], v[28:31]
	v_mfma_f32_16x16x32_bf16 v[24:27], v[48:51], v[188:191], v[24:27]
	v_mfma_f32_16x16x32_bf16 v[12:15], v[36:39], v[196:199], v[12:15]
	v_mfma_f32_16x16x32_bf16 v[8:11], v[48:51], v[196:199], v[8:11]
	v_mfma_f32_16x16x32_bf16 v[76:79], v[44:47], v[176:179], v[76:79]
	v_mfma_f32_16x16x32_bf16 v[72:75], v[56:59], v[176:179], v[72:75]
	v_mfma_f32_16x16x32_bf16 v[60:63], v[44:47], v[184:187], v[60:63]
	v_mfma_f32_16x16x32_bf16 v[52:55], v[56:59], v[184:187], v[52:55]
	v_mfma_f32_16x16x32_bf16 v[28:31], v[44:47], v[192:195], v[28:31]
	v_mfma_f32_16x16x32_bf16 v[24:27], v[56:59], v[192:195], v[24:27]
	v_mfma_f32_16x16x32_bf16 v[12:15], v[44:47], v[214:217], v[12:15]
	v_mfma_f32_16x16x32_bf16 v[8:11], v[56:59], v[214:217], v[8:11]
	s_setprio 0
	s_setprio 1
	v_mfma_f32_16x16x32_bf16 v[40:43], v[144:147], v[180:183], v[40:43]
	v_mfma_f32_16x16x32_bf16 v[32:35], v[152:155], v[180:183], v[32:35]
	v_mfma_f32_16x16x32_bf16 v[20:23], v[144:147], v[188:191], v[20:23]
	v_mfma_f32_16x16x32_bf16 v[16:19], v[152:155], v[188:191], v[16:19]
	v_mfma_f32_16x16x32_bf16 v[4:7], v[144:147], v[196:199], v[4:7]
	v_mfma_f32_16x16x32_bf16 v[0:3], v[152:155], v[196:199], v[0:3]
	v_mfma_f32_16x16x32_bf16 v[36:39], v[144:147], v[172:175], v[68:71]
	v_mfma_f32_16x16x32_bf16 v[44:47], v[152:155], v[172:175], v[64:67]
	v_mfma_f32_16x16x32_bf16 v[40:43], v[148:151], v[184:187], v[40:43]
	v_mfma_f32_16x16x32_bf16 v[32:35], v[156:159], v[184:187], v[32:35]
	v_mfma_f32_16x16x32_bf16 v[20:23], v[148:151], v[192:195], v[20:23]
	v_mfma_f32_16x16x32_bf16 v[16:19], v[156:159], v[192:195], v[16:19]
	v_mfma_f32_16x16x32_bf16 v[4:7], v[148:151], v[214:217], v[4:7]
	v_mfma_f32_16x16x32_bf16 v[0:3], v[156:159], v[214:217], v[0:3]
	v_mfma_f32_16x16x32_bf16 v[36:39], v[148:151], v[176:179], v[36:39]
	v_mfma_f32_16x16x32_bf16 v[44:47], v[156:159], v[176:179], v[44:47]
	s_setprio 0
	s_barrier
	s_add_i32 s64, 0, 0x18000
	s_add_i32 s65, 0, 0x1c000
	v_add_u32_e32 v68, s64, v201
	v_add_u32_e32 v156, s65, v201
	ds_read_b128 v[48:51], v68
	ds_read_b128 v[56:59], v68 offset:1024
	ds_read_b128 v[64:67], v68 offset:2048
	ds_read_b128 v[68:71], v68 offset:3072
	ds_read_b128 v[144:147], v156
	ds_read_b128 v[148:151], v156 offset:1024
	ds_read_b128 v[152:155], v156 offset:2048
	ds_read_b128 v[156:159], v156 offset:3072
	s_add_u32 s38, s38, 0x40000
	s_addc_u32 s39, s39, 0
	s_mov_b32 m0, s44
	ds_read_b128 v[172:175], v209 offset:32768
	ds_read_b128 v[176:179], v209 offset:33792
	ds_read_b128 v[180:183], v209 offset:34816
	ds_read_b128 v[184:187], v209 offset:35840
	ds_read_b128 v[188:191], v209 offset:36864
	ds_read_b128 v[192:195], v209 offset:37888
	ds_read_b128 v[196:199], v209 offset:38912
	ds_read_b128 v[214:217], v209 offset:39936
	global_load_lds_dwordx4 v160, s[38:39]
	s_mov_b32 m0, s45
	s_nop 0
	global_load_lds_dwordx4 v164, s[38:39]
	s_waitcnt vmcnt(8)
	s_waitcnt lgkmcnt(0)
	s_barrier
	s_setprio 1
	s_waitcnt lgkmcnt(0)
	v_mfma_f32_16x16x32_bf16 v[140:143], v[48:51], v[172:175], v[140:143]
	v_mfma_f32_16x16x32_bf16 v[136:139], v[64:67], v[172:175], v[136:139]
	v_mfma_f32_16x16x32_bf16 v[124:127], v[48:51], v[180:183], v[124:127]
	v_mfma_f32_16x16x32_bf16 v[120:123], v[64:67], v[180:183], v[120:123]
	v_mfma_f32_16x16x32_bf16 v[108:111], v[48:51], v[188:191], v[108:111]
	v_mfma_f32_16x16x32_bf16 v[104:107], v[64:67], v[188:191], v[104:107]
	v_mfma_f32_16x16x32_bf16 v[92:95], v[48:51], v[196:199], v[92:95]
	v_mfma_f32_16x16x32_bf16 v[88:91], v[64:67], v[196:199], v[88:91]
	v_mfma_f32_16x16x32_bf16 v[140:143], v[56:59], v[176:179], v[140:143]
	v_mfma_f32_16x16x32_bf16 v[136:139], v[68:71], v[176:179], v[136:139]
	v_mfma_f32_16x16x32_bf16 v[124:127], v[56:59], v[184:187], v[124:127]
	v_mfma_f32_16x16x32_bf16 v[120:123], v[68:71], v[184:187], v[120:123]
	v_mfma_f32_16x16x32_bf16 v[108:111], v[56:59], v[192:195], v[108:111]
	v_mfma_f32_16x16x32_bf16 v[104:107], v[68:71], v[192:195], v[104:107]
	v_mfma_f32_16x16x32_bf16 v[92:95], v[56:59], v[214:217], v[92:95]
	v_mfma_f32_16x16x32_bf16 v[88:91], v[68:71], v[214:217], v[88:91]
	s_setprio 0
	s_setprio 1
	v_mfma_f32_16x16x32_bf16 v[132:135], v[144:147], v[172:175], v[132:135]
	v_mfma_f32_16x16x32_bf16 v[128:131], v[152:155], v[172:175], v[128:131]
	v_mfma_f32_16x16x32_bf16 v[116:119], v[144:147], v[180:183], v[116:119]
	v_mfma_f32_16x16x32_bf16 v[112:115], v[152:155], v[180:183], v[112:115]
	v_mfma_f32_16x16x32_bf16 v[100:103], v[144:147], v[188:191], v[100:103]
	v_mfma_f32_16x16x32_bf16 v[96:99], v[152:155], v[188:191], v[96:99]
	v_mfma_f32_16x16x32_bf16 v[84:87], v[144:147], v[196:199], v[84:87]
	v_mfma_f32_16x16x32_bf16 v[80:83], v[152:155], v[196:199], v[80:83]
	v_mfma_f32_16x16x32_bf16 v[132:135], v[148:151], v[176:179], v[132:135]
	v_mfma_f32_16x16x32_bf16 v[128:131], v[156:159], v[176:179], v[128:131]
	v_mfma_f32_16x16x32_bf16 v[116:119], v[148:151], v[184:187], v[116:119]
	v_mfma_f32_16x16x32_bf16 v[112:115], v[156:159], v[184:187], v[112:115]
	v_mfma_f32_16x16x32_bf16 v[100:103], v[148:151], v[192:195], v[100:103]
	v_mfma_f32_16x16x32_bf16 v[96:99], v[156:159], v[192:195], v[96:99]
	v_mfma_f32_16x16x32_bf16 v[84:87], v[148:151], v[214:217], v[84:87]
	v_mfma_f32_16x16x32_bf16 v[80:83], v[156:159], v[214:217], v[80:83]
	s_setprio 0
	s_barrier
	s_add_i32 s38, s64, s42
	s_mov_b32 m0, s38
	ds_read_b128 v[172:175], v209 offset:49152
	ds_read_b128 v[176:179], v209 offset:50176
	ds_read_b128 v[180:183], v209 offset:51200
	ds_read_b128 v[184:187], v209 offset:52224
	ds_read_b128 v[188:191], v209 offset:53248
	ds_read_b128 v[192:195], v209 offset:54272
	ds_read_b128 v[196:199], v209 offset:55296
	ds_read_b128 v[214:217], v209 offset:56320
	global_load_lds_dwordx4 v162, s[98:99]
	s_add_i32 m0, s38, 0x2000
	s_add_u32 s34, s34, 0x40080
	s_addc_u32 s35, s35, 0
	s_add_i32 s38, s65, s42
	global_load_lds_dwordx4 v166, s[98:99]
	s_mov_b32 m0, s38
	s_nop 0
	global_load_lds_dwordx4 v162, s[34:35]
	s_add_i32 m0, s38, 0x2000
	s_nop 0
	global_load_lds_dwordx4 v166, s[34:35]
	s_mov_b32 m0, s50
	s_nop 0
	global_load_lds_dwordx4 v160, s[100:101]
	s_mov_b32 m0, s51
	s_nop 0
	global_load_lds_dwordx4 v164, s[100:101]
	s_waitcnt vmcnt(8)
	s_waitcnt lgkmcnt(0)
	s_barrier
	s_setprio 1
	s_waitcnt lgkmcnt(0)
	v_mfma_f32_16x16x32_bf16 v[76:79], v[48:51], v[172:175], v[76:79]
	v_mfma_f32_16x16x32_bf16 v[72:75], v[64:67], v[172:175], v[72:75]
	v_mfma_f32_16x16x32_bf16 v[60:63], v[48:51], v[180:183], v[60:63]
	v_mfma_f32_16x16x32_bf16 v[52:55], v[64:67], v[180:183], v[52:55]
	v_mfma_f32_16x16x32_bf16 v[28:31], v[48:51], v[188:191], v[28:31]
	v_mfma_f32_16x16x32_bf16 v[24:27], v[64:67], v[188:191], v[24:27]
	v_mfma_f32_16x16x32_bf16 v[12:15], v[48:51], v[196:199], v[12:15]
	v_mfma_f32_16x16x32_bf16 v[8:11], v[64:67], v[196:199], v[8:11]
	v_mfma_f32_16x16x32_bf16 v[76:79], v[56:59], v[176:179], v[76:79]
	v_mfma_f32_16x16x32_bf16 v[72:75], v[68:71], v[176:179], v[72:75]
	v_mfma_f32_16x16x32_bf16 v[60:63], v[56:59], v[184:187], v[60:63]
	v_mfma_f32_16x16x32_bf16 v[52:55], v[68:71], v[184:187], v[52:55]
	v_mfma_f32_16x16x32_bf16 v[28:31], v[56:59], v[192:195], v[28:31]
	v_mfma_f32_16x16x32_bf16 v[24:27], v[68:71], v[192:195], v[24:27]
	v_mfma_f32_16x16x32_bf16 v[12:15], v[56:59], v[214:217], v[12:15]
	v_mfma_f32_16x16x32_bf16 v[8:11], v[68:71], v[214:217], v[8:11]
	s_setprio 0
	s_setprio 1
	v_mfma_f32_16x16x32_bf16 v[36:39], v[144:147], v[172:175], v[36:39]
	v_mfma_f32_16x16x32_bf16 v[68:71], v[148:151], v[176:179], v[36:39]
	v_mfma_f32_16x16x32_bf16 v[36:39], v[152:155], v[172:175], v[44:47]
	v_mfma_f32_16x16x32_bf16 v[64:67], v[156:159], v[176:179], v[36:39]
	v_mfma_f32_16x16x32_bf16 v[36:39], v[144:147], v[180:183], v[40:43]
	v_mfma_f32_16x16x32_bf16 v[32:35], v[152:155], v[180:183], v[32:35]
	v_mfma_f32_16x16x32_bf16 v[20:23], v[144:147], v[188:191], v[20:23]
	v_mfma_f32_16x16x32_bf16 v[16:19], v[152:155], v[188:191], v[16:19]
	v_mfma_f32_16x16x32_bf16 v[4:7], v[144:147], v[196:199], v[4:7]
	v_mfma_f32_16x16x32_bf16 v[0:3], v[152:155], v[196:199], v[0:3]
	v_mfma_f32_16x16x32_bf16 v[40:43], v[148:151], v[184:187], v[36:39]
	v_mfma_f32_16x16x32_bf16 v[32:35], v[156:159], v[184:187], v[32:35]
	v_mfma_f32_16x16x32_bf16 v[20:23], v[148:151], v[192:195], v[20:23]
	v_mfma_f32_16x16x32_bf16 v[16:19], v[156:159], v[192:195], v[16:19]
	v_mfma_f32_16x16x32_bf16 v[4:7], v[148:151], v[214:217], v[4:7]
	v_mfma_f32_16x16x32_bf16 v[0:3], v[156:159], v[214:217], v[0:3]
	s_setprio 0
	s_barrier
	s_add_i32 s63, s63, 2
	s_add_u32 s30, s30, 0x100
	s_addc_u32 s31, s31, 0
	s_add_u32 s61, s61, 0x100
	s_addc_u32 s62, s62, 0
	s_cmp_gt_u32 s63, 13
	s_cbranch_scc0 .LBB0_2031
	s_lshl_b32 s2, s2, 8
	v_mov_b32_e32 v154, v229
	v_mov_b32_e32 v155, v231
	s_or_b32 s2, s2, s49
	s_mov_b64 s[34:35], s[26:27]
	v_lshl_add_u32 v144, v155, 3, s2
	v_ashrrev_i32_e32 v145, 31, v144
	v_lshlrev_b64 v[188:189], 2, v[144:145]
	v_lshl_add_u64 v[150:151], s[4:5], 0, v[188:189]
	global_load_dwordx4 v[36:39], v[150:151], off offset:16
	global_load_dwordx4 v[44:47], v[150:151], off
	v_lshl_add_u64 v[152:153], s[6:7], 0, v[188:189]
	global_load_dwordx4 v[48:51], v[152:153], off offset:16
	global_load_dwordx4 v[56:59], v[152:153], off
	s_lshl_b32 s2, s28, 8
	s_add_i32 s2, s2, s48
	s_mov_b32 s28, s22
	s_mov_b64 s[30:31], s[24:25]
	s_waitcnt vmcnt(0)
	v_pk_mul_f32 v[184:185], v[38:39], s[18:19] op_sel_hi:[1,0]
	v_pk_mul_f32 v[186:187], v[36:37], s[18:19] op_sel_hi:[1,0]
	global_load_dwordx4 v[146:149], v[150:151], off offset:528
	global_load_dwordx4 v[36:39], v[150:151], off offset:512
	v_pk_mul_f32 v[190:191], v[46:47], s[18:19] op_sel_hi:[1,0]
	v_pk_mul_f32 v[192:193], v[44:45], s[18:19] op_sel_hi:[1,0]
	s_waitcnt vmcnt(1)
	v_pk_mul_f32 v[176:177], v[148:149], s[18:19] op_sel_hi:[1,0]
	v_pk_mul_f32 v[178:179], v[146:147], s[18:19] op_sel_hi:[1,0]
	v_add_u32_e32 v146, s2, v154
	v_lshlrev_b32_e32 v148, 2, v155
	v_ashrrev_i32_e32 v149, 31, v148
	v_ashrrev_i32_e32 v147, 31, v146
	v_lshl_add_u64 v[194:195], v[148:149], 2, s[12:13]
	v_lshl_add_u64 v[148:149], v[146:147], 4, s[10:11]
	s_waitcnt vmcnt(0)
	v_pk_mul_f32 v[180:181], v[38:39], s[18:19] op_sel_hi:[1,0]
	v_pk_mul_f32 v[182:183], v[36:37], s[18:19] op_sel_hi:[1,0]
	global_load_dwordx4 v[36:39], v[152:153], off offset:528
	global_load_dwordx4 v[44:47], v[152:153], off offset:512
	v_lshlrev_b64 v[152:153], 6, v[146:147]
	global_load_dwordx4 v[148:151], v[148:149], off
	v_lshl_add_u64 v[152:153], v[194:195], 0, v[152:153]
	global_load_dwordx4 v[152:155], v[152:153], off
	v_add_u32_e32 v238, 16, v146
	v_ashrrev_i32_e32 v239, 31, v238
	v_lshl_add_u64 v[156:157], v[238:239], 4, s[10:11]
	global_load_dwordx4 v[156:159], v[156:157], off
	v_lshlrev_b64 v[172:173], 6, v[238:239]
	v_lshl_add_u64 v[172:173], v[194:195], 0, v[172:173]
	global_load_dwordx4 v[214:217], v[172:173], off
	v_add_u32_e32 v232, 32, v146
	v_ashrrev_i32_e32 v233, 31, v232
	v_lshl_add_u64 v[172:173], v[232:233], 4, s[10:11]
	global_load_dwordx4 v[218:221], v[172:173], off
	v_lshlrev_b64 v[172:173], 6, v[232:233]
	v_lshl_add_u64 v[172:173], v[194:195], 0, v[172:173]
	global_load_dwordx4 v[222:225], v[172:173], off
	v_add_u32_e32 v226, 48, v146
	v_ashrrev_i32_e32 v227, 31, v226
	v_lshl_add_u64 v[172:173], v[226:227], 4, s[10:11]
	global_load_dwordx4 v[244:247], v[172:173], off
	v_lshlrev_b64 v[172:173], 6, v[226:227]
	v_lshl_add_u64 v[172:173], v[194:195], 0, v[172:173]
	global_load_dwordx4 v[248:251], v[172:173], off
	v_add_u32_e32 v210, 0x90, v146
	v_ashrrev_i32_e32 v211, 31, v210
	v_add_u32_e32 v204, 0xa0, v146
	v_ashrrev_i32_e32 v205, 31, v204
	v_add_u32_e32 v198, 0xb0, v146
	v_ashrrev_i32_e32 v199, 31, v198
	v_lshlrev_b64 v[196:197], 6, v[198:199]
	s_mov_b32 s2, s20
	s_waitcnt vmcnt(7)
	v_mov_b32_e32 v172, v149
	v_mov_b32_e32 v173, v150
	v_mov_b32_e32 v149, v151
	v_pk_add_f32 v[148:149], v[172:173], v[148:149]
	v_lshlrev_b64 v[172:173], 6, v[210:211]
	v_add_f32_e32 v148, v148, v149
	v_fmamk_f32 v148, v148, 0x3a800000, v213
	v_rsq_f32_e32 v148, v148
	s_waitcnt vmcnt(6)
	v_add_f32_e32 v149, v154, v155
	v_lshl_add_u64 v[172:173], v[194:195], 0, v[172:173]
	v_mul_f32_e32 v242, 0xbfb8aa3b, v148
	v_add_f32_e32 v148, v152, v153
	v_add_f32_e32 v148, v148, v149
	v_mov_b32_e32 v149, v148
	s_nop 1
	v_permlane16_swap_b32_e32 v148, v149
	v_add_f32_e32 v148, v148, v149
	v_mov_b32_e32 v149, v148
	s_nop 1
	v_permlane32_swap_b32_e32 v148, v149
	v_add_f32_e32 v148, v148, v149
	v_fmamk_f32 v148, v148, 0x3a800000, v213
	v_rsq_f32_e32 v240, v148
	s_waitcnt vmcnt(5)
	v_mov_b32_e32 v148, v157
	v_mov_b32_e32 v149, v158
	v_mov_b32_e32 v157, v159
	v_pk_add_f32 v[148:149], v[148:149], v[156:157]
	v_lshl_add_u64 v[156:157], v[210:211], 4, s[10:11]
	v_add_f32_e32 v148, v148, v149
	v_fmamk_f32 v148, v148, 0x3a800000, v213
	v_rsq_f32_e32 v148, v148
	s_waitcnt vmcnt(4)
	v_add_f32_e32 v149, v216, v217
	global_load_dwordx4 v[156:159], v[156:157], off
	v_pk_fma_f32 v[142:143], v[142:143], v[242:243], v[190:191] op_sel_hi:[1,0,1]
	v_mul_f32_e32 v236, 0xbfb8aa3b, v148
	v_add_f32_e32 v148, v214, v215
	v_add_f32_e32 v148, v148, v149
	v_mov_b32_e32 v149, v148
	s_nop 1
	v_permlane16_swap_b32_e32 v148, v149
	v_add_f32_e32 v148, v148, v149
	v_mov_b32_e32 v149, v148
	s_nop 1
	v_permlane32_swap_b32_e32 v148, v149
	v_add_f32_e32 v148, v148, v149
	v_fmamk_f32 v148, v148, 0x3a800000, v213
	v_rsq_f32_e32 v234, v148
	s_waitcnt vmcnt(4)
	v_mov_b32_e32 v148, v219
	v_mov_b32_e32 v149, v220
	v_mov_b32_e32 v219, v221
	v_pk_add_f32 v[148:149], v[148:149], v[218:219]
	v_add_u32_e32 v220, 0x80, v146
	v_add_f32_e32 v148, v148, v149
	v_fmamk_f32 v148, v148, 0x3a800000, v213
	v_rsq_f32_e32 v148, v148
	s_waitcnt vmcnt(3)
	v_add_f32_e32 v149, v224, v225
	v_ashrrev_i32_e32 v221, 31, v220
	v_lshlrev_b64 v[152:153], 6, v[220:221]
	v_mul_f32_e32 v230, 0xbfb8aa3b, v148
	v_add_f32_e32 v148, v222, v223
	v_add_f32_e32 v148, v148, v149
	v_mov_b32_e32 v149, v148
	s_nop 1
	v_permlane16_swap_b32_e32 v148, v149
	v_add_f32_e32 v148, v148, v149
	v_mov_b32_e32 v149, v148
	s_nop 1
	v_permlane32_swap_b32_e32 v148, v149
	v_add_f32_e32 v148, v148, v149
	v_fmamk_f32 v148, v148, 0x3a800000, v213
	v_rsq_f32_e32 v228, v148
	s_waitcnt vmcnt(2)
	v_mov_b32_e32 v148, v245
	v_mov_b32_e32 v149, v246
	v_mov_b32_e32 v245, v247
	v_pk_add_f32 v[148:149], v[148:149], v[244:245]
	v_lshl_add_u64 v[152:153], v[194:195], 0, v[152:153]
	v_add_f32_e32 v148, v148, v149
	v_fmamk_f32 v148, v148, 0x3a800000, v213
	v_rsq_f32_e32 v148, v148
	s_waitcnt vmcnt(1)
	v_add_f32_e32 v149, v250, v251
	global_load_dwordx4 v[152:155], v[152:153], off
	v_pk_fma_f32 v[140:141], v[140:141], v[242:243], v[192:193] op_sel_hi:[1,0,1]
	v_mul_f32_e32 v224, 0xbfb8aa3b, v148
	v_add_f32_e32 v148, v248, v249
	v_add_f32_e32 v148, v148, v149
	v_mov_b32_e32 v149, v148
	s_nop 1
	v_permlane16_swap_b32_e32 v148, v149
	v_add_f32_e32 v148, v148, v149
	v_mov_b32_e32 v149, v148
	s_nop 1
	v_permlane32_swap_b32_e32 v148, v149
	v_add_f32_e32 v148, v148, v149
	v_fmamk_f32 v148, v148, 0x3a800000, v213
	v_rsq_f32_e32 v222, v148
	v_lshl_add_u64 v[148:149], v[220:221], 4, s[10:11]
	global_load_dwordx4 v[148:151], v[148:149], off
	v_exp_f32_e32 v142, v142
	global_load_dwordx4 v[216:219], v[172:173], off
	v_lshl_add_u64 v[172:173], v[204:205], 4, s[10:11]
	global_load_dwordx4 v[244:247], v[172:173], off
	v_lshlrev_b64 v[172:173], 6, v[204:205]
	v_lshl_add_u64 v[172:173], v[194:195], 0, v[172:173]
	global_load_dwordx4 v[248:251], v[172:173], off
	v_lshl_add_u64 v[194:195], v[194:195], 0, v[196:197]
	global_load_dwordx4 v[194:197], v[194:195], off
	v_lshl_add_u64 v[172:173], v[198:199], 4, s[10:11]
	global_load_dwordx4 v[172:175], v[172:173], off
	v_exp_f32_e32 v143, v143
	v_exp_f32_e32 v140, v140
	v_exp_f32_e32 v141, v141
	v_pk_fma_f32 v[138:139], v[138:139], v[242:243], v[184:185] op_sel_hi:[1,0,1]
	v_pk_add_f32 v[142:143], v[142:143], 1.0 op_sel_hi:[1,0]
	v_exp_f32_e32 v138, v138
	v_exp_f32_e32 v139, v139
	v_pk_fma_f32 v[136:137], v[136:137], v[242:243], v[186:187] op_sel_hi:[1,0,1]
	v_pk_add_f32 v[140:141], v[140:141], 1.0 op_sel_hi:[1,0]
	v_rcp_f32_e32 v142, v142
	v_rcp_f32_e32 v143, v143
	v_exp_f32_e32 v136, v136
	v_exp_f32_e32 v137, v137
	v_rcp_f32_e32 v140, v140
	v_rcp_f32_e32 v141, v141
	v_pk_add_f32 v[138:139], v[138:139], 1.0 op_sel_hi:[1,0]
	v_pk_add_f32 v[136:137], v[136:137], 1.0 op_sel_hi:[1,0]
	v_rcp_f32_e32 v138, v138
	v_rcp_f32_e32 v139, v139
	v_rcp_f32_e32 v136, v136
	v_rcp_f32_e32 v137, v137
	v_pk_fma_f32 v[132:133], v[132:133], v[242:243], v[182:183] op_sel_hi:[1,0,1]
	v_pk_fma_f32 v[134:135], v[134:135], v[242:243], v[180:181] op_sel_hi:[1,0,1]
	v_exp_f32_e32 v132, v132
	v_exp_f32_e32 v133, v133
	v_exp_f32_e32 v134, v134
	v_exp_f32_e32 v135, v135
	v_pk_fma_f32 v[128:129], v[128:129], v[242:243], v[178:179] op_sel_hi:[1,0,1]
	v_pk_fma_f32 v[130:131], v[130:131], v[242:243], v[176:177] op_sel_hi:[1,0,1]
	v_pk_add_f32 v[132:133], v[132:133], 1.0 op_sel_hi:[1,0]
	v_pk_add_f32 v[134:135], v[134:135], 1.0 op_sel_hi:[1,0]
	v_exp_f32_e32 v128, v128
	v_exp_f32_e32 v129, v129
	v_exp_f32_e32 v130, v130
	v_exp_f32_e32 v131, v131
	v_rcp_f32_e32 v132, v132
	v_rcp_f32_e32 v133, v133
	v_rcp_f32_e32 v134, v134
	v_rcp_f32_e32 v135, v135
	v_pk_add_f32 v[128:129], v[128:129], 1.0 op_sel_hi:[1,0]
	v_pk_add_f32 v[130:131], v[130:131], 1.0 op_sel_hi:[1,0]
	v_rcp_f32_e32 v128, v128
	v_rcp_f32_e32 v129, v129
	v_rcp_f32_e32 v130, v130
	v_rcp_f32_e32 v131, v131
	v_pk_fma_f32 v[126:127], v[126:127], v[236:237], v[190:191] op_sel_hi:[1,0,1]
	v_pk_fma_f32 v[124:125], v[124:125], v[236:237], v[192:193] op_sel_hi:[1,0,1]
	v_exp_f32_e32 v126, v126
	v_exp_f32_e32 v127, v127
	v_exp_f32_e32 v124, v124
	v_exp_f32_e32 v125, v125
	v_pk_fma_f32 v[122:123], v[122:123], v[236:237], v[184:185] op_sel_hi:[1,0,1]
	v_pk_add_f32 v[126:127], v[126:127], 1.0 op_sel_hi:[1,0]
	v_exp_f32_e32 v122, v122
	v_exp_f32_e32 v123, v123
	v_pk_fma_f32 v[120:121], v[120:121], v[236:237], v[186:187] op_sel_hi:[1,0,1]
	v_pk_add_f32 v[124:125], v[124:125], 1.0 op_sel_hi:[1,0]
	v_rcp_f32_e32 v126, v126
	v_rcp_f32_e32 v127, v127
	v_exp_f32_e32 v120, v120
	v_exp_f32_e32 v121, v121
	v_rcp_f32_e32 v124, v124
	v_rcp_f32_e32 v125, v125
	v_pk_add_f32 v[122:123], v[122:123], 1.0 op_sel_hi:[1,0]
	v_pk_add_f32 v[120:121], v[120:121], 1.0 op_sel_hi:[1,0]
	v_rcp_f32_e32 v122, v122
	v_rcp_f32_e32 v123, v123
	v_rcp_f32_e32 v120, v120
	s_waitcnt vmcnt(5)
	v_mov_b32_e32 v214, v149
	v_mov_b32_e32 v215, v150
	v_mov_b32_e32 v149, v151
	v_pk_add_f32 v[148:149], v[214:215], v[148:149]
	v_rcp_f32_e32 v121, v121
	v_add_f32_e32 v148, v148, v149
	v_fmamk_f32 v148, v148, 0x3a800000, v213
	v_rsq_f32_e32 v148, v148
	v_add_f32_e32 v149, v154, v155
	v_pk_fma_f32 v[116:117], v[116:117], v[236:237], v[182:183] op_sel_hi:[1,0,1]
	v_pk_fma_f32 v[118:119], v[118:119], v[236:237], v[180:181] op_sel_hi:[1,0,1]
	v_mul_f32_e32 v214, 0xbfb8aa3b, v148
	v_add_f32_e32 v148, v152, v153
	v_add_f32_e32 v148, v148, v149
	v_mov_b32_e32 v149, v148
	s_nop 1
	v_permlane16_swap_b32_e32 v148, v149
	v_add_f32_e32 v148, v148, v149
	v_mov_b32_e32 v149, v148
	s_nop 1
	v_permlane32_swap_b32_e32 v148, v149
	v_add_f32_e32 v148, v148, v149
	v_fmamk_f32 v148, v148, 0x3a800000, v213
	v_rsq_f32_e32 v212, v148
	v_mov_b32_e32 v148, v157
	v_mov_b32_e32 v149, v158
	v_mov_b32_e32 v157, v159
	v_pk_add_f32 v[148:149], v[148:149], v[156:157]
	v_exp_f32_e32 v116, v116
	v_add_f32_e32 v148, v148, v149
	v_fmamk_f32 v148, v148, 0x3a800000, v213
	v_rsq_f32_e32 v148, v148
	s_waitcnt vmcnt(4)
	v_add_f32_e32 v149, v218, v219
	v_exp_f32_e32 v117, v117
	v_exp_f32_e32 v118, v118
	v_mul_f32_e32 v208, 0xbfb8aa3b, v148
	v_add_f32_e32 v148, v216, v217
	v_add_f32_e32 v148, v148, v149
	v_mov_b32_e32 v149, v148
	s_nop 1
	v_permlane16_swap_b32_e32 v148, v149
	v_add_f32_e32 v148, v148, v149
	v_mov_b32_e32 v149, v148
	s_nop 1
	v_permlane32_swap_b32_e32 v148, v149
	v_add_f32_e32 v148, v148, v149
	v_fmamk_f32 v148, v148, 0x3a800000, v213
	v_rsq_f32_e32 v206, v148
	s_waitcnt vmcnt(3)
	v_mov_b32_e32 v148, v245
	v_mov_b32_e32 v149, v246
	v_mov_b32_e32 v245, v247
	v_pk_add_f32 v[148:149], v[148:149], v[244:245]
	v_lshlrev_b64 v[244:245], 12, v[146:147]
	v_add_f32_e32 v148, v148, v149
	v_fmamk_f32 v148, v148, 0x3a800000, v213
	v_rsq_f32_e32 v148, v148
	s_waitcnt vmcnt(2)
	v_add_f32_e32 v149, v250, v251
	v_exp_f32_e32 v119, v119
	v_pk_fma_f32 v[112:113], v[112:113], v[236:237], v[178:179] op_sel_hi:[1,0,1]
	v_mul_f32_e32 v202, 0xbfb8aa3b, v148
	v_add_f32_e32 v148, v248, v249
	v_add_f32_e32 v148, v148, v149
	v_mov_b32_e32 v149, v148
	s_nop 1
	v_permlane16_swap_b32_e32 v148, v149
	v_add_f32_e32 v148, v148, v149
	v_mov_b32_e32 v149, v148
	s_nop 1
	v_permlane32_swap_b32_e32 v148, v149
	v_add_f32_e32 v148, v148, v149
	v_fmamk_f32 v148, v148, 0x3a800000, v213
	v_rsq_f32_e32 v200, v148
	s_waitcnt vmcnt(0)
	v_mov_b32_e32 v148, v173
	v_mov_b32_e32 v149, v174
	v_mov_b32_e32 v173, v175
	v_pk_add_f32 v[148:149], v[148:149], v[172:173]
	v_pk_fma_f32 v[114:115], v[114:115], v[236:237], v[176:177] op_sel_hi:[1,0,1]
	v_add_f32_e32 v148, v148, v149
	v_fmamk_f32 v148, v148, 0x3a800000, v213
	v_rsq_f32_e32 v148, v148
	v_add_f32_e32 v149, v196, v197
	v_pk_add_f32 v[116:117], v[116:117], 1.0 op_sel_hi:[1,0]
	v_pk_add_f32 v[118:119], v[118:119], 1.0 op_sel_hi:[1,0]
	v_mul_f32_e32 v172, 0xbfb8aa3b, v148
	v_add_f32_e32 v148, v194, v195
	v_add_f32_e32 v148, v148, v149
	v_mov_b32_e32 v149, v148
	s_nop 1
	v_permlane16_swap_b32_e32 v148, v149
	v_add_f32_e32 v148, v148, v149
	v_mov_b32_e32 v149, v148
	s_nop 1
	v_permlane32_swap_b32_e32 v148, v149
	v_add_f32_e32 v148, v148, v149
	v_fmamk_f32 v148, v148, 0x3a800000, v213
	v_rsq_f32_e32 v194, v148
	v_lshlrev_b64 v[148:149], 10, v[146:147]
	v_lshl_add_u64 v[144:145], v[148:149], 0, v[144:145]
	v_lshlrev_b64 v[144:145], 1, v[144:145]
	v_lshl_add_u64 v[216:217], s[68:69], 0, v[144:145]
	v_lshl_add_u64 v[218:219], s[8:9], 0, v[144:145]
	global_load_dwordx4 v[152:155], v[216:217], off
	global_load_dwordx4 v[156:159], v[218:219], off
	global_load_dwordx4 v[148:151], v[216:217], off offset:256
	global_load_dwordx4 v[144:147], v[218:219], off offset:256
	v_exp_f32_e32 v112, v112
	v_exp_f32_e32 v113, v113
	v_exp_f32_e32 v114, v114
	v_exp_f32_e32 v115, v115
	v_rcp_f32_e32 v116, v116
	v_rcp_f32_e32 v117, v117
	v_rcp_f32_e32 v118, v118
	v_rcp_f32_e32 v119, v119
	v_pk_add_f32 v[112:113], v[112:113], 1.0 op_sel_hi:[1,0]
	v_pk_add_f32 v[114:115], v[114:115], 1.0 op_sel_hi:[1,0]
	v_rcp_f32_e32 v112, v112
	v_rcp_f32_e32 v113, v113
	v_rcp_f32_e32 v114, v114
	v_rcp_f32_e32 v115, v115
	v_pk_fma_f32 v[110:111], v[110:111], v[230:231], v[190:191] op_sel_hi:[1,0,1]
	v_pk_fma_f32 v[108:109], v[108:109], v[230:231], v[192:193] op_sel_hi:[1,0,1]
	v_exp_f32_e32 v110, v110
	v_exp_f32_e32 v111, v111
	v_exp_f32_e32 v108, v108
	v_exp_f32_e32 v109, v109
	v_pk_fma_f32 v[106:107], v[106:107], v[230:231], v[184:185] op_sel_hi:[1,0,1]
	v_pk_add_f32 v[110:111], v[110:111], 1.0 op_sel_hi:[1,0]
	v_exp_f32_e32 v106, v106
	v_exp_f32_e32 v107, v107
	v_pk_fma_f32 v[104:105], v[104:105], v[230:231], v[186:187] op_sel_hi:[1,0,1]
	v_pk_add_f32 v[108:109], v[108:109], 1.0 op_sel_hi:[1,0]
	v_rcp_f32_e32 v110, v110
	v_rcp_f32_e32 v111, v111
	v_exp_f32_e32 v104, v104
	v_exp_f32_e32 v105, v105
	v_rcp_f32_e32 v108, v108
	v_rcp_f32_e32 v109, v109
	v_pk_add_f32 v[106:107], v[106:107], 1.0 op_sel_hi:[1,0]
	v_pk_add_f32 v[104:105], v[104:105], 1.0 op_sel_hi:[1,0]
	v_rcp_f32_e32 v106, v106
	v_rcp_f32_e32 v107, v107
	v_rcp_f32_e32 v104, v104
	v_rcp_f32_e32 v105, v105
	v_pk_fma_f32 v[100:101], v[100:101], v[230:231], v[182:183] op_sel_hi:[1,0,1]
	v_pk_fma_f32 v[102:103], v[102:103], v[230:231], v[180:181] op_sel_hi:[1,0,1]
	v_exp_f32_e32 v100, v100
	v_exp_f32_e32 v101, v101
	v_exp_f32_e32 v102, v102
	v_exp_f32_e32 v103, v103
	v_pk_fma_f32 v[96:97], v[96:97], v[230:231], v[178:179] op_sel_hi:[1,0,1]
	v_pk_fma_f32 v[98:99], v[98:99], v[230:231], v[176:177] op_sel_hi:[1,0,1]
	v_pk_add_f32 v[100:101], v[100:101], 1.0 op_sel_hi:[1,0]
	v_pk_add_f32 v[102:103], v[102:103], 1.0 op_sel_hi:[1,0]
	v_exp_f32_e32 v96, v96
	v_exp_f32_e32 v97, v97
	v_exp_f32_e32 v98, v98
	v_exp_f32_e32 v99, v99
	v_rcp_f32_e32 v100, v100
	v_rcp_f32_e32 v101, v101
	v_rcp_f32_e32 v102, v102
	v_rcp_f32_e32 v103, v103
	v_pk_add_f32 v[96:97], v[96:97], 1.0 op_sel_hi:[1,0]
	v_pk_add_f32 v[98:99], v[98:99], 1.0 op_sel_hi:[1,0]
	v_rcp_f32_e32 v96, v96
	v_rcp_f32_e32 v97, v97
	v_rcp_f32_e32 v98, v98
	v_rcp_f32_e32 v99, v99
	v_pk_fma_f32 v[94:95], v[94:95], v[224:225], v[190:191] op_sel_hi:[1,0,1]
	v_pk_fma_f32 v[92:93], v[92:93], v[224:225], v[192:193] op_sel_hi:[1,0,1]
	v_exp_f32_e32 v94, v94
	v_exp_f32_e32 v95, v95
	v_exp_f32_e32 v92, v92
	v_exp_f32_e32 v93, v93
	v_pk_fma_f32 v[90:91], v[90:91], v[224:225], v[184:185] op_sel_hi:[1,0,1]
	v_pk_add_f32 v[94:95], v[94:95], 1.0 op_sel_hi:[1,0]
	v_exp_f32_e32 v90, v90
	v_exp_f32_e32 v91, v91
	v_pk_fma_f32 v[88:89], v[88:89], v[224:225], v[186:187] op_sel_hi:[1,0,1]
	v_pk_add_f32 v[92:93], v[92:93], 1.0 op_sel_hi:[1,0]
	v_rcp_f32_e32 v94, v94
	v_rcp_f32_e32 v95, v95
	s_waitcnt vmcnt(3)
	v_lshlrev_b32_e32 v246, 16, v152
	s_waitcnt vmcnt(2)
	v_lshlrev_b32_e32 v174, 16, v156
	v_and_b32_e32 v175, 0xffff0000, v156
	v_lshlrev_b32_e32 v156, 16, v157
	v_and_b32_e32 v157, 0xffff0000, v157
	v_pk_mul_f32 v[156:157], v[240:241], v[156:157] op_sel_hi:[0,1]
	v_and_b32_e32 v247, 0xffff0000, v152
	v_lshlrev_b32_e32 v152, 16, v153
	v_and_b32_e32 v153, 0xffff0000, v153
	v_pk_mul_f32 v[174:175], v[240:241], v[174:175] op_sel_hi:[0,1]
	v_pk_mul_f32 v[156:157], v[58:59], v[156:157]
	v_pk_mul_f32 v[174:175], v[56:57], v[174:175]
	v_pk_fma_f32 v[142:143], v[142:143], v[156:157], v[152:153]
	v_lshl_add_u64 v[152:153], s[36:37], 0, v[244:245]
	v_lshlrev_b32_e32 v156, 16, v159
	v_and_b32_e32 v157, 0xffff0000, v159
	v_pk_fma_f32 v[140:141], v[140:141], v[174:175], v[246:247]
	v_lshl_add_u64 v[152:153], v[152:153], 0, v[188:189]
	v_pk_mul_f32 v[156:157], v[240:241], v[156:157] op_sel_hi:[0,1]
	global_store_dwordx4 v[152:153], v[140:143], off nt
	v_pk_mul_f32 v[156:157], v[50:51], v[156:157]
	s_waitcnt vmcnt(1)
	v_lshlrev_b32_e32 v174, 16, v144
	v_lshlrev_b32_e32 v140, 16, v154
	v_and_b32_e32 v141, 0xffff0000, v154
	v_lshlrev_b32_e32 v142, 16, v158
	v_and_b32_e32 v143, 0xffff0000, v158
	v_lshlrev_b32_e32 v154, 16, v155
	v_and_b32_e32 v155, 0xffff0000, v155
	v_pk_mul_f32 v[142:143], v[240:241], v[142:143] op_sel_hi:[0,1]
	v_pk_fma_f32 v[138:139], v[138:139], v[156:157], v[154:155]
	v_add_co_u32_e32 v154, vcc, s53, v216
	v_pk_mul_f32 v[142:143], v[48:49], v[142:143]
	s_nop 0
	v_addc_co_u32_e32 v155, vcc, 0, v217, vcc
	v_pk_fma_f32 v[136:137], v[136:137], v[142:143], v[140:141]
	v_add_co_u32_e32 v156, vcc, s53, v218
	global_store_dwordx4 v[152:153], v[136:139], off offset:16 nt
	s_nop 0
	v_addc_co_u32_e32 v157, vcc, 0, v219, vcc
	global_load_dwordx4 v[136:139], v[154:155], off
	global_load_dwordx4 v[140:143], v[156:157], off
	v_and_b32_e32 v175, 0xffff0000, v144
	v_lshlrev_b32_e32 v144, 16, v145
	v_and_b32_e32 v145, 0xffff0000, v145
	v_pk_mul_f32 v[144:145], v[240:241], v[144:145] op_sel_hi:[0,1]
	v_pk_mul_f32 v[174:175], v[240:241], v[174:175] op_sel_hi:[0,1]
	v_lshlrev_b32_e32 v158, 16, v148
	v_and_b32_e32 v159, 0xffff0000, v148
	v_lshlrev_b32_e32 v148, 16, v149
	v_and_b32_e32 v149, 0xffff0000, v149
	v_pk_mul_f32 v[174:175], v[44:45], v[174:175]
	v_pk_mul_f32 v[144:145], v[46:47], v[144:145]
	v_pk_fma_f32 v[132:133], v[132:133], v[174:175], v[158:159]
	v_pk_fma_f32 v[134:135], v[134:135], v[144:145], v[148:149]
	global_store_dwordx4 v[152:153], v[132:135], off offset:512 nt
	v_lshlrev_b32_e32 v144, 16, v151
	v_and_b32_e32 v145, 0xffff0000, v151
	v_lshlrev_b32_e32 v134, 16, v146
	v_and_b32_e32 v135, 0xffff0000, v146
	v_lshlrev_b32_e32 v146, 16, v147
	v_and_b32_e32 v147, 0xffff0000, v147
	v_pk_mul_f32 v[146:147], v[240:241], v[146:147] op_sel_hi:[0,1]
	v_pk_mul_f32 v[134:135], v[240:241], v[134:135] op_sel_hi:[0,1]
	v_lshlrev_b32_e32 v132, 16, v150
	v_and_b32_e32 v133, 0xffff0000, v150
	v_pk_mul_f32 v[134:135], v[36:37], v[134:135]
	v_pk_mul_f32 v[146:147], v[38:39], v[146:147]
	v_pk_fma_f32 v[128:129], v[128:129], v[134:135], v[132:133]
	v_pk_fma_f32 v[130:131], v[130:131], v[146:147], v[144:145]
	global_store_dwordx4 v[152:153], v[128:131], off offset:528 nt
	global_load_dwordx4 v[132:135], v[154:155], off offset:256
	s_nop 0
	global_load_dwordx4 v[128:131], v[156:157], off offset:256
	v_lshlrev_b64 v[144:145], 12, v[238:239]
	v_exp_f32_e32 v88, v88
	v_exp_f32_e32 v89, v89
	v_rcp_f32_e32 v92, v92
	v_rcp_f32_e32 v93, v93
	v_pk_add_f32 v[90:91], v[90:91], 1.0 op_sel_hi:[1,0]
	v_pk_add_f32 v[88:89], v[88:89], 1.0 op_sel_hi:[1,0]
	v_rcp_f32_e32 v90, v90
	v_rcp_f32_e32 v91, v91
	v_rcp_f32_e32 v88, v88
	v_rcp_f32_e32 v89, v89
	v_pk_fma_f32 v[84:85], v[84:85], v[224:225], v[182:183] op_sel_hi:[1,0,1]
	v_pk_fma_f32 v[86:87], v[86:87], v[224:225], v[180:181] op_sel_hi:[1,0,1]
	v_exp_f32_e32 v84, v84
	v_exp_f32_e32 v85, v85
	v_exp_f32_e32 v86, v86
	v_exp_f32_e32 v87, v87
	v_pk_fma_f32 v[80:81], v[80:81], v[224:225], v[178:179] op_sel_hi:[1,0,1]
	v_pk_fma_f32 v[82:83], v[82:83], v[224:225], v[176:177] op_sel_hi:[1,0,1]
	v_pk_add_f32 v[84:85], v[84:85], 1.0 op_sel_hi:[1,0]
	v_pk_add_f32 v[86:87], v[86:87], 1.0 op_sel_hi:[1,0]
	v_exp_f32_e32 v80, v80
	v_exp_f32_e32 v81, v81
	v_exp_f32_e32 v82, v82
	v_exp_f32_e32 v83, v83
	v_rcp_f32_e32 v84, v84
	v_rcp_f32_e32 v85, v85
	v_rcp_f32_e32 v86, v86
	v_rcp_f32_e32 v87, v87
	v_pk_add_f32 v[80:81], v[80:81], 1.0 op_sel_hi:[1,0]
	v_pk_add_f32 v[82:83], v[82:83], 1.0 op_sel_hi:[1,0]
	v_rcp_f32_e32 v80, v80
	v_rcp_f32_e32 v81, v81
	v_rcp_f32_e32 v82, v82
	v_rcp_f32_e32 v83, v83
	v_pk_fma_f32 v[78:79], v[78:79], v[214:215], v[190:191] op_sel_hi:[1,0,1]
	v_pk_fma_f32 v[76:77], v[76:77], v[214:215], v[192:193] op_sel_hi:[1,0,1]
	v_exp_f32_e32 v78, v78
	v_exp_f32_e32 v79, v79
	v_exp_f32_e32 v76, v76
	v_exp_f32_e32 v77, v77
	v_pk_fma_f32 v[74:75], v[74:75], v[214:215], v[184:185] op_sel_hi:[1,0,1]
	v_pk_add_f32 v[78:79], v[78:79], 1.0 op_sel_hi:[1,0]
	v_exp_f32_e32 v74, v74
	v_exp_f32_e32 v75, v75
	v_pk_fma_f32 v[72:73], v[72:73], v[214:215], v[186:187] op_sel_hi:[1,0,1]
	s_waitcnt vmcnt(5)
	v_lshlrev_b32_e32 v146, 16, v136
	s_waitcnt vmcnt(4)
	v_lshlrev_b32_e32 v148, 16, v140
	v_and_b32_e32 v149, 0xffff0000, v140
	v_lshlrev_b32_e32 v140, 16, v141
	v_and_b32_e32 v141, 0xffff0000, v141
	v_pk_mul_f32 v[140:141], v[234:235], v[140:141] op_sel_hi:[0,1]
	v_and_b32_e32 v147, 0xffff0000, v136
	v_lshlrev_b32_e32 v136, 16, v137
	v_and_b32_e32 v137, 0xffff0000, v137
	v_pk_mul_f32 v[148:149], v[234:235], v[148:149] op_sel_hi:[0,1]
	v_pk_mul_f32 v[140:141], v[58:59], v[140:141]
	v_pk_mul_f32 v[148:149], v[56:57], v[148:149]
	v_pk_fma_f32 v[126:127], v[126:127], v[140:141], v[136:137]
	v_lshl_add_u64 v[136:137], s[36:37], 0, v[144:145]
	v_lshlrev_b32_e32 v140, 16, v143
	v_and_b32_e32 v141, 0xffff0000, v143
	v_pk_fma_f32 v[124:125], v[124:125], v[148:149], v[146:147]
	v_lshl_add_u64 v[136:137], v[136:137], 0, v[188:189]
	v_pk_mul_f32 v[140:141], v[234:235], v[140:141] op_sel_hi:[0,1]
	global_store_dwordx4 v[136:137], v[124:127], off nt
	v_pk_mul_f32 v[140:141], v[50:51], v[140:141]
	v_pk_add_f32 v[76:77], v[76:77], 1.0 op_sel_hi:[1,0]
	v_lshlrev_b32_e32 v124, 16, v138
	v_and_b32_e32 v125, 0xffff0000, v138
	v_lshlrev_b32_e32 v126, 16, v142
	v_and_b32_e32 v127, 0xffff0000, v142
	v_lshlrev_b32_e32 v138, 16, v139
	v_and_b32_e32 v139, 0xffff0000, v139
	v_pk_mul_f32 v[126:127], v[234:235], v[126:127] op_sel_hi:[0,1]
	v_pk_fma_f32 v[122:123], v[122:123], v[140:141], v[138:139]
	v_add_co_u32_e32 v138, vcc, s47, v216
	v_pk_mul_f32 v[126:127], v[48:49], v[126:127]
	s_nop 0
	v_addc_co_u32_e32 v139, vcc, 0, v217, vcc
	v_pk_fma_f32 v[120:121], v[120:121], v[126:127], v[124:125]
	v_add_co_u32_e32 v140, vcc, s47, v218
	global_store_dwordx4 v[136:137], v[120:123], off offset:16 nt
	s_nop 0
	v_addc_co_u32_e32 v141, vcc, 0, v219, vcc
	global_load_dwordx4 v[120:123], v[138:139], off
	global_load_dwordx4 v[124:127], v[140:141], off
	s_waitcnt vmcnt(4)
	v_lshlrev_b32_e32 v144, 16, v128
	v_and_b32_e32 v145, 0xffff0000, v128
	v_lshlrev_b32_e32 v128, 16, v129
	v_and_b32_e32 v129, 0xffff0000, v129
	v_pk_mul_f32 v[128:129], v[234:235], v[128:129] op_sel_hi:[0,1]
	v_pk_mul_f32 v[144:145], v[234:235], v[144:145] op_sel_hi:[0,1]
	v_lshlrev_b32_e32 v142, 16, v132
	v_and_b32_e32 v143, 0xffff0000, v132
	v_lshlrev_b32_e32 v132, 16, v133
	v_and_b32_e32 v133, 0xffff0000, v133
	v_pk_mul_f32 v[144:145], v[44:45], v[144:145]
	v_pk_mul_f32 v[128:129], v[46:47], v[128:129]
	v_pk_fma_f32 v[116:117], v[116:117], v[144:145], v[142:143]
	v_pk_fma_f32 v[118:119], v[118:119], v[128:129], v[132:133]
	global_store_dwordx4 v[136:137], v[116:119], off offset:512 nt
	v_lshlrev_b32_e32 v128, 16, v135
	v_and_b32_e32 v129, 0xffff0000, v135
	v_lshlrev_b32_e32 v118, 16, v130
	v_and_b32_e32 v119, 0xffff0000, v130
	v_lshlrev_b32_e32 v130, 16, v131
	v_and_b32_e32 v131, 0xffff0000, v131
	v_pk_mul_f32 v[130:131], v[234:235], v[130:131] op_sel_hi:[0,1]
	v_pk_mul_f32 v[118:119], v[234:235], v[118:119] op_sel_hi:[0,1]
	v_lshlrev_b32_e32 v116, 16, v134
	v_and_b32_e32 v117, 0xffff0000, v134
	v_pk_mul_f32 v[118:119], v[36:37], v[118:119]
	v_pk_mul_f32 v[130:131], v[38:39], v[130:131]
	v_pk_fma_f32 v[112:113], v[112:113], v[118:119], v[116:117]
	v_pk_fma_f32 v[114:115], v[114:115], v[130:131], v[128:129]
	global_store_dwordx4 v[136:137], v[112:115], off offset:528 nt
	global_load_dwordx4 v[116:119], v[138:139], off offset:256
	s_nop 0
	global_load_dwordx4 v[112:115], v[140:141], off offset:256
	v_lshlrev_b64 v[128:129], 12, v[232:233]
	v_rcp_f32_e32 v78, v78
	v_rcp_f32_e32 v79, v79
	v_exp_f32_e32 v72, v72
	v_exp_f32_e32 v73, v73
	v_rcp_f32_e32 v76, v76
	v_rcp_f32_e32 v77, v77
	v_pk_add_f32 v[74:75], v[74:75], 1.0 op_sel_hi:[1,0]
	v_pk_add_f32 v[72:73], v[72:73], 1.0 op_sel_hi:[1,0]
	v_rcp_f32_e32 v74, v74
	v_rcp_f32_e32 v75, v75
	v_pk_fma_f32 v[68:69], v[68:69], v[214:215], v[182:183] op_sel_hi:[1,0,1]
	v_pk_fma_f32 v[70:71], v[70:71], v[214:215], v[180:181] op_sel_hi:[1,0,1]
	v_rcp_f32_e32 v72, v72
	v_rcp_f32_e32 v73, v73
	v_exp_f32_e32 v68, v68
	v_exp_f32_e32 v69, v69
	v_exp_f32_e32 v70, v70
	v_exp_f32_e32 v71, v71
	v_pk_fma_f32 v[64:65], v[64:65], v[214:215], v[178:179] op_sel_hi:[1,0,1]
	v_pk_fma_f32 v[66:67], v[66:67], v[214:215], v[176:177] op_sel_hi:[1,0,1]
	v_pk_add_f32 v[68:69], v[68:69], 1.0 op_sel_hi:[1,0]
	v_pk_add_f32 v[70:71], v[70:71], 1.0 op_sel_hi:[1,0]
	v_exp_f32_e32 v64, v64
	v_exp_f32_e32 v65, v65
	v_exp_f32_e32 v66, v66
	v_exp_f32_e32 v67, v67
	v_rcp_f32_e32 v68, v68
	v_rcp_f32_e32 v69, v69
	v_rcp_f32_e32 v70, v70
	v_rcp_f32_e32 v71, v71
	v_pk_add_f32 v[64:65], v[64:65], 1.0 op_sel_hi:[1,0]
	v_pk_add_f32 v[66:67], v[66:67], 1.0 op_sel_hi:[1,0]
	v_rcp_f32_e32 v64, v64
	v_rcp_f32_e32 v65, v65
	v_rcp_f32_e32 v66, v66
	v_rcp_f32_e32 v67, v67
	v_pk_fma_f32 v[62:63], v[62:63], v[208:209], v[190:191] op_sel_hi:[1,0,1]
	v_pk_fma_f32 v[60:61], v[60:61], v[208:209], v[192:193] op_sel_hi:[1,0,1]
	v_exp_f32_e32 v62, v62
	v_exp_f32_e32 v63, v63
	v_exp_f32_e32 v60, v60
	v_exp_f32_e32 v61, v61
	v_pk_fma_f32 v[54:55], v[54:55], v[208:209], v[184:185] op_sel_hi:[1,0,1]
	v_pk_add_f32 v[62:63], v[62:63], 1.0 op_sel_hi:[1,0]
	s_waitcnt vmcnt(5)
	v_lshlrev_b32_e32 v130, 16, v120
	s_waitcnt vmcnt(4)
	v_lshlrev_b32_e32 v132, 16, v124
	v_and_b32_e32 v133, 0xffff0000, v124
	v_lshlrev_b32_e32 v124, 16, v125
	v_and_b32_e32 v125, 0xffff0000, v125
	v_pk_mul_f32 v[124:125], v[228:229], v[124:125] op_sel_hi:[0,1]
	v_and_b32_e32 v131, 0xffff0000, v120
	v_lshlrev_b32_e32 v120, 16, v121
	v_and_b32_e32 v121, 0xffff0000, v121
	v_pk_mul_f32 v[132:133], v[228:229], v[132:133] op_sel_hi:[0,1]
	v_pk_mul_f32 v[124:125], v[58:59], v[124:125]
	v_pk_mul_f32 v[132:133], v[56:57], v[132:133]
	v_pk_fma_f32 v[110:111], v[110:111], v[124:125], v[120:121]
	v_lshl_add_u64 v[120:121], s[36:37], 0, v[128:129]
	v_lshlrev_b32_e32 v124, 16, v127
	v_and_b32_e32 v125, 0xffff0000, v127
	v_pk_fma_f32 v[108:109], v[108:109], v[132:133], v[130:131]
	v_lshl_add_u64 v[120:121], v[120:121], 0, v[188:189]
	v_pk_mul_f32 v[124:125], v[228:229], v[124:125] op_sel_hi:[0,1]
	global_store_dwordx4 v[120:121], v[108:111], off nt
	v_pk_mul_f32 v[124:125], v[50:51], v[124:125]
	v_exp_f32_e32 v54, v54
	v_lshlrev_b32_e32 v108, 16, v122
	v_and_b32_e32 v109, 0xffff0000, v122
	v_lshlrev_b32_e32 v110, 16, v126
	v_and_b32_e32 v111, 0xffff0000, v126
	v_lshlrev_b32_e32 v122, 16, v123
	v_and_b32_e32 v123, 0xffff0000, v123
	v_pk_mul_f32 v[110:111], v[228:229], v[110:111] op_sel_hi:[0,1]
	v_pk_fma_f32 v[106:107], v[106:107], v[124:125], v[122:123]
	v_add_co_u32_e32 v122, vcc, s52, v216
	v_pk_mul_f32 v[110:111], v[48:49], v[110:111]
	s_nop 0
	v_addc_co_u32_e32 v123, vcc, 0, v217, vcc
	v_pk_fma_f32 v[104:105], v[104:105], v[110:111], v[108:109]
	v_add_co_u32_e32 v124, vcc, s52, v218
	global_store_dwordx4 v[120:121], v[104:107], off offset:16 nt
	s_nop 0
	v_addc_co_u32_e32 v125, vcc, 0, v219, vcc
	global_load_dwordx4 v[104:107], v[122:123], off
	global_load_dwordx4 v[108:111], v[124:125], off
	s_waitcnt vmcnt(4)
	v_lshlrev_b32_e32 v128, 16, v112
	v_and_b32_e32 v129, 0xffff0000, v112
	v_lshlrev_b32_e32 v112, 16, v113
	v_and_b32_e32 v113, 0xffff0000, v113
	v_pk_mul_f32 v[112:113], v[228:229], v[112:113] op_sel_hi:[0,1]
	v_pk_mul_f32 v[128:129], v[228:229], v[128:129] op_sel_hi:[0,1]
	v_lshlrev_b32_e32 v126, 16, v116
	v_and_b32_e32 v127, 0xffff0000, v116
	v_lshlrev_b32_e32 v116, 16, v117
	v_and_b32_e32 v117, 0xffff0000, v117
	v_pk_mul_f32 v[128:129], v[44:45], v[128:129]
	v_pk_mul_f32 v[112:113], v[46:47], v[112:113]
	v_pk_fma_f32 v[100:101], v[100:101], v[128:129], v[126:127]
	v_pk_fma_f32 v[102:103], v[102:103], v[112:113], v[116:117]
	global_store_dwordx4 v[120:121], v[100:103], off offset:512 nt
	v_lshlrev_b32_e32 v112, 16, v119
	v_and_b32_e32 v113, 0xffff0000, v119
	v_lshlrev_b32_e32 v102, 16, v114
	v_and_b32_e32 v103, 0xffff0000, v114
	v_lshlrev_b32_e32 v114, 16, v115
	v_and_b32_e32 v115, 0xffff0000, v115
	v_pk_mul_f32 v[114:115], v[228:229], v[114:115] op_sel_hi:[0,1]
	v_pk_mul_f32 v[102:103], v[228:229], v[102:103] op_sel_hi:[0,1]
	v_lshlrev_b32_e32 v100, 16, v118
	v_and_b32_e32 v101, 0xffff0000, v118
	v_pk_mul_f32 v[102:103], v[36:37], v[102:103]
	v_pk_mul_f32 v[114:115], v[38:39], v[114:115]
	v_pk_fma_f32 v[96:97], v[96:97], v[102:103], v[100:101]
	v_pk_fma_f32 v[98:99], v[98:99], v[114:115], v[112:113]
	global_store_dwordx4 v[120:121], v[96:99], off offset:528 nt
	global_load_dwordx4 v[100:103], v[122:123], off offset:256
	s_nop 0
	global_load_dwordx4 v[96:99], v[124:125], off offset:256
	v_lshlrev_b64 v[112:113], 12, v[226:227]
	v_exp_f32_e32 v55, v55
	v_pk_fma_f32 v[52:53], v[52:53], v[208:209], v[186:187] op_sel_hi:[1,0,1]
	v_pk_add_f32 v[60:61], v[60:61], 1.0 op_sel_hi:[1,0]
	v_rcp_f32_e32 v62, v62
	v_rcp_f32_e32 v63, v63
	v_exp_f32_e32 v52, v52
	v_exp_f32_e32 v53, v53
	v_rcp_f32_e32 v60, v60
	v_rcp_f32_e32 v61, v61
	v_pk_add_f32 v[54:55], v[54:55], 1.0 op_sel_hi:[1,0]
	v_pk_fma_f32 v[40:41], v[40:41], v[208:209], v[182:183] op_sel_hi:[1,0,1]
	v_rcp_f32_e32 v54, v54
	v_rcp_f32_e32 v55, v55
	v_pk_fma_f32 v[42:43], v[42:43], v[208:209], v[180:181] op_sel_hi:[1,0,1]
	v_pk_add_f32 v[52:53], v[52:53], 1.0 op_sel_hi:[1,0]
	v_exp_f32_e32 v40, v40
	v_exp_f32_e32 v41, v41
	v_exp_f32_e32 v42, v42
	v_exp_f32_e32 v43, v43
	v_rcp_f32_e32 v52, v52
	v_rcp_f32_e32 v53, v53
	v_pk_fma_f32 v[32:33], v[32:33], v[208:209], v[178:179] op_sel_hi:[1,0,1]
	v_pk_fma_f32 v[34:35], v[34:35], v[208:209], v[176:177] op_sel_hi:[1,0,1]
	v_pk_add_f32 v[40:41], v[40:41], 1.0 op_sel_hi:[1,0]
	v_pk_add_f32 v[42:43], v[42:43], 1.0 op_sel_hi:[1,0]
	v_exp_f32_e32 v32, v32
	v_exp_f32_e32 v33, v33
	v_exp_f32_e32 v34, v34
	v_exp_f32_e32 v35, v35
	v_rcp_f32_e32 v40, v40
	v_rcp_f32_e32 v41, v41
	v_rcp_f32_e32 v42, v42
	v_rcp_f32_e32 v43, v43
	v_pk_add_f32 v[32:33], v[32:33], 1.0 op_sel_hi:[1,0]
	v_pk_add_f32 v[34:35], v[34:35], 1.0 op_sel_hi:[1,0]
	v_rcp_f32_e32 v32, v32
	v_rcp_f32_e32 v33, v33
	v_rcp_f32_e32 v34, v34
	v_rcp_f32_e32 v35, v35
	v_pk_fma_f32 v[30:31], v[30:31], v[202:203], v[190:191] op_sel_hi:[1,0,1]
	v_pk_fma_f32 v[28:29], v[28:29], v[202:203], v[192:193] op_sel_hi:[1,0,1]
	v_exp_f32_e32 v30, v30
	v_exp_f32_e32 v31, v31
	v_exp_f32_e32 v28, v28
	s_waitcnt vmcnt(5)
	v_lshlrev_b32_e32 v114, 16, v104
	s_waitcnt vmcnt(4)
	v_lshlrev_b32_e32 v116, 16, v108
	v_and_b32_e32 v117, 0xffff0000, v108
	v_lshlrev_b32_e32 v108, 16, v109
	v_and_b32_e32 v109, 0xffff0000, v109
	v_pk_mul_f32 v[108:109], v[222:223], v[108:109] op_sel_hi:[0,1]
	v_and_b32_e32 v115, 0xffff0000, v104
	v_lshlrev_b32_e32 v104, 16, v105
	v_and_b32_e32 v105, 0xffff0000, v105
	v_pk_mul_f32 v[116:117], v[222:223], v[116:117] op_sel_hi:[0,1]
	v_pk_mul_f32 v[108:109], v[58:59], v[108:109]
	v_pk_mul_f32 v[116:117], v[56:57], v[116:117]
	v_pk_fma_f32 v[94:95], v[94:95], v[108:109], v[104:105]
	v_lshl_add_u64 v[104:105], s[36:37], 0, v[112:113]
	v_lshlrev_b32_e32 v108, 16, v111
	v_and_b32_e32 v109, 0xffff0000, v111
	v_pk_fma_f32 v[92:93], v[92:93], v[116:117], v[114:115]
	v_lshl_add_u64 v[104:105], v[104:105], 0, v[188:189]
	v_pk_mul_f32 v[108:109], v[222:223], v[108:109] op_sel_hi:[0,1]
	global_store_dwordx4 v[104:105], v[92:95], off nt
	v_pk_mul_f32 v[108:109], v[50:51], v[108:109]
	v_exp_f32_e32 v29, v29
	v_lshlrev_b32_e32 v92, 16, v106
	v_and_b32_e32 v93, 0xffff0000, v106
	v_lshlrev_b32_e32 v94, 16, v110
	v_and_b32_e32 v95, 0xffff0000, v110
	v_lshlrev_b32_e32 v106, 16, v107
	v_and_b32_e32 v107, 0xffff0000, v107
	v_pk_mul_f32 v[94:95], v[222:223], v[94:95] op_sel_hi:[0,1]
	v_pk_fma_f32 v[90:91], v[90:91], v[108:109], v[106:107]
	v_add_co_u32_e32 v106, vcc, s57, v216
	v_pk_mul_f32 v[94:95], v[48:49], v[94:95]
	s_nop 0
	v_addc_co_u32_e32 v107, vcc, 0, v217, vcc
	v_pk_fma_f32 v[88:89], v[88:89], v[94:95], v[92:93]
	v_add_co_u32_e32 v108, vcc, s57, v218
	global_store_dwordx4 v[104:105], v[88:91], off offset:16 nt
	s_nop 0
	v_addc_co_u32_e32 v109, vcc, 0, v219, vcc
	global_load_dwordx4 v[88:91], v[106:107], off
	global_load_dwordx4 v[92:95], v[108:109], off
	s_waitcnt vmcnt(4)
	v_lshlrev_b32_e32 v112, 16, v96
	v_and_b32_e32 v113, 0xffff0000, v96
	v_lshlrev_b32_e32 v96, 16, v97
	v_and_b32_e32 v97, 0xffff0000, v97
	v_pk_mul_f32 v[96:97], v[222:223], v[96:97] op_sel_hi:[0,1]
	v_pk_mul_f32 v[112:113], v[222:223], v[112:113] op_sel_hi:[0,1]
	v_lshlrev_b32_e32 v110, 16, v100
	v_and_b32_e32 v111, 0xffff0000, v100
	v_lshlrev_b32_e32 v100, 16, v101
	v_and_b32_e32 v101, 0xffff0000, v101
	v_pk_mul_f32 v[112:113], v[44:45], v[112:113]
	v_pk_mul_f32 v[96:97], v[46:47], v[96:97]
	v_pk_fma_f32 v[84:85], v[84:85], v[112:113], v[110:111]
	v_pk_fma_f32 v[86:87], v[86:87], v[96:97], v[100:101]
	global_store_dwordx4 v[104:105], v[84:87], off offset:512 nt
	v_lshlrev_b32_e32 v96, 16, v103
	v_and_b32_e32 v97, 0xffff0000, v103
	v_lshlrev_b32_e32 v86, 16, v98
	v_and_b32_e32 v87, 0xffff0000, v98
	v_lshlrev_b32_e32 v98, 16, v99
	v_and_b32_e32 v99, 0xffff0000, v99
	v_pk_mul_f32 v[98:99], v[222:223], v[98:99] op_sel_hi:[0,1]
	v_pk_mul_f32 v[86:87], v[222:223], v[86:87] op_sel_hi:[0,1]
	v_lshlrev_b32_e32 v84, 16, v102
	v_and_b32_e32 v85, 0xffff0000, v102
	v_pk_mul_f32 v[86:87], v[36:37], v[86:87]
	v_pk_mul_f32 v[98:99], v[38:39], v[98:99]
	v_pk_fma_f32 v[80:81], v[80:81], v[86:87], v[84:85]
	v_pk_fma_f32 v[82:83], v[82:83], v[98:99], v[96:97]
	global_store_dwordx4 v[104:105], v[80:83], off offset:528 nt
	global_load_dwordx4 v[84:87], v[106:107], off offset:256
	s_nop 0
	global_load_dwordx4 v[80:83], v[108:109], off offset:256
	v_lshlrev_b64 v[96:97], 12, v[220:221]
	v_pk_fma_f32 v[26:27], v[26:27], v[202:203], v[184:185] op_sel_hi:[1,0,1]
	v_pk_add_f32 v[30:31], v[30:31], 1.0 op_sel_hi:[1,0]
	v_exp_f32_e32 v26, v26
	v_exp_f32_e32 v27, v27
	v_pk_fma_f32 v[24:25], v[24:25], v[202:203], v[186:187] op_sel_hi:[1,0,1]
	v_pk_add_f32 v[28:29], v[28:29], 1.0 op_sel_hi:[1,0]
	v_rcp_f32_e32 v30, v30
	v_rcp_f32_e32 v31, v31
	v_exp_f32_e32 v24, v24
	v_exp_f32_e32 v25, v25
	v_rcp_f32_e32 v28, v28
	v_rcp_f32_e32 v29, v29
	v_pk_add_f32 v[26:27], v[26:27], 1.0 op_sel_hi:[1,0]
	v_pk_fma_f32 v[20:21], v[20:21], v[202:203], v[182:183] op_sel_hi:[1,0,1]
	v_pk_fma_f32 v[22:23], v[22:23], v[202:203], v[180:181] op_sel_hi:[1,0,1]
	v_rcp_f32_e32 v26, v26
	v_rcp_f32_e32 v27, v27
	v_exp_f32_e32 v20, v20
	v_exp_f32_e32 v21, v21
	v_exp_f32_e32 v22, v22
	v_exp_f32_e32 v23, v23
	v_pk_add_f32 v[24:25], v[24:25], 1.0 op_sel_hi:[1,0]
	v_pk_fma_f32 v[16:17], v[16:17], v[202:203], v[178:179] op_sel_hi:[1,0,1]
	v_rcp_f32_e32 v24, v24
	v_rcp_f32_e32 v25, v25
	v_pk_fma_f32 v[18:19], v[18:19], v[202:203], v[176:177] op_sel_hi:[1,0,1]
	v_pk_add_f32 v[20:21], v[20:21], 1.0 op_sel_hi:[1,0]
	v_pk_add_f32 v[22:23], v[22:23], 1.0 op_sel_hi:[1,0]
	v_exp_f32_e32 v16, v16
	v_exp_f32_e32 v17, v17
	v_exp_f32_e32 v18, v18
	v_exp_f32_e32 v19, v19
	v_rcp_f32_e32 v20, v20
	v_rcp_f32_e32 v21, v21
	v_rcp_f32_e32 v22, v22
	v_rcp_f32_e32 v23, v23
	v_pk_add_f32 v[16:17], v[16:17], 1.0 op_sel_hi:[1,0]
	v_pk_add_f32 v[18:19], v[18:19], 1.0 op_sel_hi:[1,0]
	v_rcp_f32_e32 v16, v16
	v_rcp_f32_e32 v17, v17
	v_rcp_f32_e32 v18, v18
	v_rcp_f32_e32 v19, v19
	v_pk_fma_f32 v[14:15], v[14:15], v[172:173], v[190:191] op_sel_hi:[1,0,1]
	v_pk_fma_f32 v[12:13], v[12:13], v[172:173], v[192:193] op_sel_hi:[1,0,1]
	s_waitcnt vmcnt(5)
	v_lshlrev_b32_e32 v98, 16, v88
	s_waitcnt vmcnt(4)
	v_lshlrev_b32_e32 v100, 16, v92
	v_and_b32_e32 v101, 0xffff0000, v92
	v_lshlrev_b32_e32 v92, 16, v93
	v_and_b32_e32 v93, 0xffff0000, v93
	v_pk_mul_f32 v[92:93], v[212:213], v[92:93] op_sel_hi:[0,1]
	v_and_b32_e32 v99, 0xffff0000, v88
	v_lshlrev_b32_e32 v88, 16, v89
	v_and_b32_e32 v89, 0xffff0000, v89
	v_pk_mul_f32 v[100:101], v[212:213], v[100:101] op_sel_hi:[0,1]
	v_pk_mul_f32 v[92:93], v[58:59], v[92:93]
	v_pk_mul_f32 v[100:101], v[56:57], v[100:101]
	v_pk_fma_f32 v[78:79], v[78:79], v[92:93], v[88:89]
	v_lshl_add_u64 v[88:89], s[36:37], 0, v[96:97]
	v_lshlrev_b32_e32 v92, 16, v95
	v_and_b32_e32 v93, 0xffff0000, v95
	v_pk_fma_f32 v[76:77], v[76:77], v[100:101], v[98:99]
	v_lshl_add_u64 v[88:89], v[88:89], 0, v[188:189]
	v_pk_mul_f32 v[92:93], v[212:213], v[92:93] op_sel_hi:[0,1]
	global_store_dwordx4 v[88:89], v[76:79], off nt
	v_pk_mul_f32 v[92:93], v[50:51], v[92:93]
	v_exp_f32_e32 v14, v14
	v_lshlrev_b32_e32 v76, 16, v90
	v_and_b32_e32 v77, 0xffff0000, v90
	v_lshlrev_b32_e32 v78, 16, v94
	v_and_b32_e32 v79, 0xffff0000, v94
	v_lshlrev_b32_e32 v90, 16, v91
	v_and_b32_e32 v91, 0xffff0000, v91
	v_pk_mul_f32 v[78:79], v[212:213], v[78:79] op_sel_hi:[0,1]
	v_pk_fma_f32 v[74:75], v[74:75], v[92:93], v[90:91]
	v_add_co_u32_e32 v90, vcc, s58, v216
	v_pk_mul_f32 v[78:79], v[48:49], v[78:79]
	s_nop 0
	v_addc_co_u32_e32 v91, vcc, 0, v217, vcc
	v_pk_fma_f32 v[72:73], v[72:73], v[78:79], v[76:77]
	v_add_co_u32_e32 v92, vcc, s58, v218
	global_store_dwordx4 v[88:89], v[72:75], off offset:16 nt
	s_nop 0
	v_addc_co_u32_e32 v93, vcc, 0, v219, vcc
	global_load_dwordx4 v[72:75], v[90:91], off
	global_load_dwordx4 v[76:79], v[92:93], off
	s_waitcnt vmcnt(4)
	v_lshlrev_b32_e32 v96, 16, v80
	v_and_b32_e32 v97, 0xffff0000, v80
	v_lshlrev_b32_e32 v80, 16, v81
	v_and_b32_e32 v81, 0xffff0000, v81
	v_pk_mul_f32 v[80:81], v[212:213], v[80:81] op_sel_hi:[0,1]
	v_pk_mul_f32 v[96:97], v[212:213], v[96:97] op_sel_hi:[0,1]
	v_lshlrev_b32_e32 v94, 16, v84
	v_and_b32_e32 v95, 0xffff0000, v84
	v_lshlrev_b32_e32 v84, 16, v85
	v_and_b32_e32 v85, 0xffff0000, v85
	v_pk_mul_f32 v[96:97], v[44:45], v[96:97]
	v_pk_mul_f32 v[80:81], v[46:47], v[80:81]
	v_pk_fma_f32 v[68:69], v[68:69], v[96:97], v[94:95]
	v_pk_fma_f32 v[70:71], v[70:71], v[80:81], v[84:85]
	global_store_dwordx4 v[88:89], v[68:71], off offset:512 nt
	v_lshlrev_b32_e32 v80, 16, v87
	v_and_b32_e32 v81, 0xffff0000, v87
	v_lshlrev_b32_e32 v70, 16, v82
	v_and_b32_e32 v71, 0xffff0000, v82
	v_lshlrev_b32_e32 v82, 16, v83
	v_and_b32_e32 v83, 0xffff0000, v83
	v_pk_mul_f32 v[82:83], v[212:213], v[82:83] op_sel_hi:[0,1]
	v_pk_mul_f32 v[70:71], v[212:213], v[70:71] op_sel_hi:[0,1]
	v_lshlrev_b32_e32 v68, 16, v86
	v_and_b32_e32 v69, 0xffff0000, v86
	v_pk_mul_f32 v[70:71], v[36:37], v[70:71]
	v_pk_mul_f32 v[82:83], v[38:39], v[82:83]
	v_pk_fma_f32 v[64:65], v[64:65], v[70:71], v[68:69]
	v_pk_fma_f32 v[66:67], v[66:67], v[82:83], v[80:81]
	global_store_dwordx4 v[88:89], v[64:67], off offset:528 nt
	global_load_dwordx4 v[64:67], v[90:91], off offset:256
	s_nop 0
	global_load_dwordx4 v[68:71], v[92:93], off offset:256
	v_lshlrev_b64 v[80:81], 12, v[210:211]
	v_exp_f32_e32 v15, v15
	v_exp_f32_e32 v12, v12
	v_exp_f32_e32 v13, v13
	v_pk_fma_f32 v[8:9], v[8:9], v[172:173], v[186:187] op_sel_hi:[1,0,1]
	v_pk_fma_f32 v[10:11], v[10:11], v[172:173], v[184:185] op_sel_hi:[1,0,1]
	v_exp_f32_e32 v8, v8
	v_exp_f32_e32 v9, v9
	v_exp_f32_e32 v10, v10
	v_exp_f32_e32 v11, v11
	v_pk_add_f32 v[14:15], v[14:15], 1.0 op_sel_hi:[1,0]
	v_pk_add_f32 v[12:13], v[12:13], 1.0 op_sel_hi:[1,0]
	v_rcp_f32_e32 v14, v14
	v_rcp_f32_e32 v15, v15
	v_pk_fma_f32 v[4:5], v[4:5], v[172:173], v[182:183] op_sel_hi:[1,0,1]
	v_pk_fma_f32 v[6:7], v[6:7], v[172:173], v[180:181] op_sel_hi:[1,0,1]
	v_rcp_f32_e32 v12, v12
	v_rcp_f32_e32 v13, v13
	v_pk_add_f32 v[8:9], v[8:9], 1.0 op_sel_hi:[1,0]
	v_pk_add_f32 v[10:11], v[10:11], 1.0 op_sel_hi:[1,0]
	v_exp_f32_e32 v4, v4
	v_exp_f32_e32 v5, v5
	v_exp_f32_e32 v6, v6
	v_exp_f32_e32 v7, v7
	v_rcp_f32_e32 v8, v8
	v_rcp_f32_e32 v9, v9
	v_rcp_f32_e32 v10, v10
	v_rcp_f32_e32 v11, v11
	v_pk_fma_f32 v[0:1], v[0:1], v[172:173], v[178:179] op_sel_hi:[1,0,1]
	v_pk_fma_f32 v[2:3], v[2:3], v[172:173], v[176:177] op_sel_hi:[1,0,1]
	v_pk_add_f32 v[4:5], v[4:5], 1.0 op_sel_hi:[1,0]
	v_pk_add_f32 v[6:7], v[6:7], 1.0 op_sel_hi:[1,0]
	v_exp_f32_e32 v0, v0
	v_exp_f32_e32 v1, v1
	v_exp_f32_e32 v2, v2
	v_exp_f32_e32 v3, v3
	v_rcp_f32_e32 v4, v4
	v_rcp_f32_e32 v5, v5
	v_rcp_f32_e32 v6, v6
	v_rcp_f32_e32 v7, v7
	v_pk_add_f32 v[0:1], v[0:1], 1.0 op_sel_hi:[1,0]
	v_pk_add_f32 v[2:3], v[2:3], 1.0 op_sel_hi:[1,0]
	v_rcp_f32_e32 v0, v0
	v_rcp_f32_e32 v1, v1
	v_rcp_f32_e32 v2, v2
	s_waitcnt vmcnt(5)
	v_lshlrev_b32_e32 v82, 16, v72
	s_waitcnt vmcnt(4)
	v_lshlrev_b32_e32 v84, 16, v76
	v_and_b32_e32 v85, 0xffff0000, v76
	v_lshlrev_b32_e32 v76, 16, v77
	v_and_b32_e32 v77, 0xffff0000, v77
	v_pk_mul_f32 v[76:77], v[206:207], v[76:77] op_sel_hi:[0,1]
	v_and_b32_e32 v83, 0xffff0000, v72
	v_lshlrev_b32_e32 v72, 16, v73
	v_and_b32_e32 v73, 0xffff0000, v73
	v_pk_mul_f32 v[84:85], v[206:207], v[84:85] op_sel_hi:[0,1]
	v_pk_mul_f32 v[76:77], v[58:59], v[76:77]
	v_pk_mul_f32 v[84:85], v[56:57], v[84:85]
	v_pk_fma_f32 v[62:63], v[62:63], v[76:77], v[72:73]
	v_lshl_add_u64 v[72:73], s[36:37], 0, v[80:81]
	v_lshlrev_b32_e32 v76, 16, v79
	v_and_b32_e32 v77, 0xffff0000, v79
	v_pk_fma_f32 v[60:61], v[60:61], v[84:85], v[82:83]
	v_lshl_add_u64 v[72:73], v[72:73], 0, v[188:189]
	v_pk_mul_f32 v[76:77], v[206:207], v[76:77] op_sel_hi:[0,1]
	global_store_dwordx4 v[72:73], v[60:63], off nt
	v_pk_mul_f32 v[76:77], v[50:51], v[76:77]
	v_rcp_f32_e32 v3, v3
	v_lshlrev_b32_e32 v60, 16, v74
	v_and_b32_e32 v61, 0xffff0000, v74
	v_lshlrev_b32_e32 v62, 16, v78
	v_and_b32_e32 v63, 0xffff0000, v78
	v_lshlrev_b32_e32 v74, 16, v75
	v_and_b32_e32 v75, 0xffff0000, v75
	v_pk_mul_f32 v[62:63], v[206:207], v[62:63] op_sel_hi:[0,1]
	v_pk_fma_f32 v[54:55], v[54:55], v[76:77], v[74:75]
	v_add_co_u32_e32 v74, vcc, s59, v216
	v_pk_mul_f32 v[62:63], v[48:49], v[62:63]
	s_nop 0
	v_addc_co_u32_e32 v75, vcc, 0, v217, vcc
	v_pk_fma_f32 v[52:53], v[52:53], v[62:63], v[60:61]
	v_add_co_u32_e32 v76, vcc, s59, v218
	global_store_dwordx4 v[72:73], v[52:55], off offset:16 nt
	s_nop 0
	v_addc_co_u32_e32 v77, vcc, 0, v219, vcc
	s_waitcnt vmcnt(2)
	v_lshlrev_b32_e32 v80, 16, v68
	v_and_b32_e32 v81, 0xffff0000, v68
	v_lshlrev_b32_e32 v68, 16, v69
	v_and_b32_e32 v69, 0xffff0000, v69
	global_load_dwordx4 v[52:55], v[74:75], off
	global_load_dwordx4 v[60:63], v[76:77], off
	v_pk_mul_f32 v[68:69], v[206:207], v[68:69] op_sel_hi:[0,1]
	v_pk_mul_f32 v[80:81], v[206:207], v[80:81] op_sel_hi:[0,1]
	v_lshlrev_b32_e32 v78, 16, v64
	v_and_b32_e32 v79, 0xffff0000, v64
	v_lshlrev_b32_e32 v64, 16, v65
	v_and_b32_e32 v65, 0xffff0000, v65
	v_pk_mul_f32 v[80:81], v[44:45], v[80:81]
	v_pk_mul_f32 v[68:69], v[46:47], v[68:69]
	v_pk_fma_f32 v[40:41], v[40:41], v[80:81], v[78:79]
	v_pk_fma_f32 v[42:43], v[42:43], v[68:69], v[64:65]
	global_store_dwordx4 v[72:73], v[40:43], off offset:512 nt
	v_lshlrev_b32_e32 v64, 16, v67
	v_and_b32_e32 v65, 0xffff0000, v67
	v_lshlrev_b32_e32 v40, 16, v66
	v_and_b32_e32 v41, 0xffff0000, v66
	v_lshlrev_b32_e32 v42, 16, v70
	v_and_b32_e32 v43, 0xffff0000, v70
	v_lshlrev_b32_e32 v66, 16, v71
	v_and_b32_e32 v67, 0xffff0000, v71
	v_pk_mul_f32 v[66:67], v[206:207], v[66:67] op_sel_hi:[0,1]
	v_pk_mul_f32 v[42:43], v[206:207], v[42:43] op_sel_hi:[0,1]
	v_pk_mul_f32 v[42:43], v[36:37], v[42:43]
	v_pk_mul_f32 v[66:67], v[38:39], v[66:67]
	v_pk_fma_f32 v[32:33], v[32:33], v[42:43], v[40:41]
	v_pk_fma_f32 v[34:35], v[34:35], v[66:67], v[64:65]
	global_store_dwordx4 v[72:73], v[32:35], off offset:528 nt
	global_load_dwordx4 v[32:35], v[74:75], off offset:256
	s_nop 0
	global_load_dwordx4 v[40:43], v[76:77], off offset:256
	v_lshlrev_b64 v[64:65], 12, v[204:205]
	s_waitcnt vmcnt(5)
	v_lshlrev_b32_e32 v66, 16, v52
	s_waitcnt vmcnt(4)
	v_lshlrev_b32_e32 v68, 16, v60
	v_and_b32_e32 v69, 0xffff0000, v60
	v_lshlrev_b32_e32 v60, 16, v61
	v_and_b32_e32 v61, 0xffff0000, v61
	v_pk_mul_f32 v[60:61], v[200:201], v[60:61] op_sel_hi:[0,1]
	v_and_b32_e32 v67, 0xffff0000, v52
	v_lshlrev_b32_e32 v52, 16, v53
	v_and_b32_e32 v53, 0xffff0000, v53
	v_pk_mul_f32 v[68:69], v[200:201], v[68:69] op_sel_hi:[0,1]
	v_pk_mul_f32 v[60:61], v[58:59], v[60:61]
	v_pk_mul_f32 v[68:69], v[56:57], v[68:69]
	v_pk_fma_f32 v[30:31], v[30:31], v[60:61], v[52:53]
	v_lshl_add_u64 v[52:53], s[36:37], 0, v[64:65]
	v_lshlrev_b32_e32 v60, 16, v63
	v_and_b32_e32 v61, 0xffff0000, v63
	v_pk_fma_f32 v[28:29], v[28:29], v[68:69], v[66:67]
	v_lshl_add_u64 v[52:53], v[52:53], 0, v[188:189]
	v_pk_mul_f32 v[60:61], v[200:201], v[60:61] op_sel_hi:[0,1]
	global_store_dwordx4 v[52:53], v[28:31], off nt
	v_pk_mul_f32 v[60:61], v[50:51], v[60:61]
	s_waitcnt vmcnt(2)
	v_and_b32_e32 v63, 0xffff0000, v32
	v_lshlrev_b32_e32 v28, 16, v54
	v_and_b32_e32 v29, 0xffff0000, v54
	v_lshlrev_b32_e32 v30, 16, v62
	v_and_b32_e32 v31, 0xffff0000, v62
	v_lshlrev_b32_e32 v54, 16, v55
	v_and_b32_e32 v55, 0xffff0000, v55
	v_pk_mul_f32 v[30:31], v[200:201], v[30:31] op_sel_hi:[0,1]
	v_pk_fma_f32 v[26:27], v[26:27], v[60:61], v[54:55]
	v_add_co_u32_e32 v54, vcc, s60, v216
	v_pk_mul_f32 v[30:31], v[48:49], v[30:31]
	s_nop 0
	v_addc_co_u32_e32 v55, vcc, 0, v217, vcc
	v_pk_fma_f32 v[24:25], v[24:25], v[30:31], v[28:29]
	v_add_co_u32_e32 v60, vcc, s60, v218
	s_waitcnt vmcnt(1)
	v_lshlrev_b32_e32 v64, 16, v40
	v_and_b32_e32 v65, 0xffff0000, v40
	v_lshlrev_b32_e32 v40, 16, v41
	v_and_b32_e32 v41, 0xffff0000, v41
	global_store_dwordx4 v[52:53], v[24:27], off offset:16 nt
	v_addc_co_u32_e32 v61, vcc, 0, v219, vcc
	v_pk_mul_f32 v[40:41], v[200:201], v[40:41] op_sel_hi:[0,1]
	v_pk_mul_f32 v[64:65], v[200:201], v[64:65] op_sel_hi:[0,1]
	global_load_dwordx4 v[24:27], v[54:55], off
	global_load_dwordx4 v[28:31], v[60:61], off
	v_lshlrev_b32_e32 v62, 16, v32
	v_lshlrev_b32_e32 v32, 16, v33
	v_and_b32_e32 v33, 0xffff0000, v33
	v_pk_mul_f32 v[64:65], v[44:45], v[64:65]
	v_pk_mul_f32 v[40:41], v[46:47], v[40:41]
	v_pk_fma_f32 v[20:21], v[20:21], v[64:65], v[62:63]
	v_pk_fma_f32 v[22:23], v[22:23], v[40:41], v[32:33]
	global_store_dwordx4 v[52:53], v[20:23], off offset:512 nt
	v_lshlrev_b32_e32 v32, 16, v35
	v_and_b32_e32 v33, 0xffff0000, v35
	v_lshlrev_b32_e32 v20, 16, v34
	v_and_b32_e32 v21, 0xffff0000, v34
	v_lshlrev_b32_e32 v22, 16, v42
	v_and_b32_e32 v23, 0xffff0000, v42
	v_lshlrev_b32_e32 v34, 16, v43
	v_and_b32_e32 v35, 0xffff0000, v43
	v_pk_mul_f32 v[34:35], v[200:201], v[34:35] op_sel_hi:[0,1]
	v_pk_mul_f32 v[22:23], v[200:201], v[22:23] op_sel_hi:[0,1]
	v_pk_mul_f32 v[22:23], v[36:37], v[22:23]
	v_pk_mul_f32 v[34:35], v[38:39], v[34:35]
	v_pk_fma_f32 v[16:17], v[16:17], v[22:23], v[20:21]
	v_pk_fma_f32 v[18:19], v[18:19], v[34:35], v[32:33]
	global_store_dwordx4 v[52:53], v[16:19], off offset:528 nt
	global_load_dwordx4 v[16:19], v[54:55], off offset:256
	s_nop 0
	global_load_dwordx4 v[20:23], v[60:61], off offset:256
	v_lshlrev_b64 v[40:41], 12, v[198:199]
	s_and_b64 vcc, exec, s[0:1]
	s_waitcnt vmcnt(5)
	v_lshlrev_b32_e32 v32, 16, v24
	s_waitcnt vmcnt(4)
	v_lshlrev_b32_e32 v34, 16, v28
	v_and_b32_e32 v35, 0xffff0000, v28
	v_lshlrev_b32_e32 v28, 16, v29
	v_and_b32_e32 v29, 0xffff0000, v29
	v_pk_mul_f32 v[28:29], v[194:195], v[28:29] op_sel_hi:[0,1]
	v_and_b32_e32 v33, 0xffff0000, v24
	v_lshlrev_b32_e32 v24, 16, v25
	v_and_b32_e32 v25, 0xffff0000, v25
	v_pk_mul_f32 v[34:35], v[194:195], v[34:35] op_sel_hi:[0,1]
	v_pk_mul_f32 v[28:29], v[58:59], v[28:29]
	v_pk_mul_f32 v[42:43], v[56:57], v[34:35]
	v_pk_fma_f32 v[34:35], v[14:15], v[28:29], v[24:25]
	v_lshlrev_b32_e32 v24, 16, v30
	v_and_b32_e32 v25, 0xffff0000, v30
	v_lshlrev_b32_e32 v28, 16, v31
	v_and_b32_e32 v29, 0xffff0000, v31
	v_pk_mul_f32 v[28:29], v[194:195], v[28:29] op_sel_hi:[0,1]
	v_pk_mul_f32 v[24:25], v[194:195], v[24:25] op_sel_hi:[0,1]
	v_pk_fma_f32 v[32:33], v[12:13], v[42:43], v[32:33]
	v_lshl_add_u64 v[12:13], s[36:37], 0, v[40:41]
	v_lshlrev_b32_e32 v14, 16, v26
	v_and_b32_e32 v15, 0xffff0000, v26
	v_lshlrev_b32_e32 v26, 16, v27
	v_and_b32_e32 v27, 0xffff0000, v27
	v_pk_mul_f32 v[24:25], v[48:49], v[24:25]
	v_pk_mul_f32 v[28:29], v[50:51], v[28:29]
	v_lshl_add_u64 v[12:13], v[12:13], 0, v[188:189]
	v_pk_fma_f32 v[10:11], v[10:11], v[28:29], v[26:27]
	v_pk_fma_f32 v[8:9], v[8:9], v[24:25], v[14:15]
	global_store_dwordx4 v[12:13], v[8:11], off offset:16 nt
	s_waitcnt vmcnt(2)
	v_lshlrev_b32_e32 v14, 16, v17
	v_and_b32_e32 v15, 0xffff0000, v17
	v_lshlrev_b32_e32 v8, 16, v16
	v_and_b32_e32 v9, 0xffff0000, v16
	s_waitcnt vmcnt(1)
	v_lshlrev_b32_e32 v10, 16, v20
	v_and_b32_e32 v11, 0xffff0000, v20
	v_lshlrev_b32_e32 v16, 16, v21
	v_and_b32_e32 v17, 0xffff0000, v21
	v_pk_mul_f32 v[16:17], v[194:195], v[16:17] op_sel_hi:[0,1]
	v_pk_mul_f32 v[10:11], v[194:195], v[10:11] op_sel_hi:[0,1]
	v_pk_mul_f32 v[10:11], v[44:45], v[10:11]
	v_pk_mul_f32 v[16:17], v[46:47], v[16:17]
	v_pk_fma_f32 v[4:5], v[4:5], v[10:11], v[8:9]
	v_pk_fma_f32 v[6:7], v[6:7], v[16:17], v[14:15]
	global_store_dwordx4 v[12:13], v[4:7], off offset:512 nt
	v_lshlrev_b32_e32 v10, 16, v23
	v_and_b32_e32 v11, 0xffff0000, v23
	v_lshlrev_b32_e32 v6, 16, v22
	v_and_b32_e32 v7, 0xffff0000, v22
	v_pk_mul_f32 v[10:11], v[194:195], v[10:11] op_sel_hi:[0,1]
	v_pk_mul_f32 v[6:7], v[194:195], v[6:7] op_sel_hi:[0,1]
	v_lshlrev_b32_e32 v4, 16, v18
	v_and_b32_e32 v5, 0xffff0000, v18
	v_lshlrev_b32_e32 v8, 16, v19
	v_and_b32_e32 v9, 0xffff0000, v19
	v_pk_mul_f32 v[6:7], v[36:37], v[6:7]
	v_pk_mul_f32 v[10:11], v[38:39], v[10:11]
	v_pk_fma_f32 v[0:1], v[0:1], v[6:7], v[4:5]
	v_pk_fma_f32 v[2:3], v[2:3], v[10:11], v[8:9]
	global_store_dwordx4 v[12:13], v[32:35], off nt
	global_store_dwordx4 v[12:13], v[0:3], off offset:528 nt
	s_cbranch_vccz .LBB0_2024
	s_waitcnt vmcnt(0)
	s_cmpk_gt_u32 s19, 0xff
	s_cbranch_scc1 .LBB0_2035
	s_barrier
